# v33 + K-loops: last 2 of the 6 LDS-DMA issues of each SP2 load segment moved into the following MFMA block (counted wait 8->6)
# speedup vs baseline: 1.0258x; 1.0099x over previous
; #define PG8_STAGE(bufoff, gbase, voff) do { _Pragma("unroll") for (int _i = 0; _i < 2; ++_i) \
;         __builtin_amdgcn_global_load_lds((const unsigned*)((const char*)(gbase) + (voff)[_i]), (PG8_LAS unsigned*)(lds + (bufoff) + ldsw + _i * 8192), 16, 0, 0); } while (0)
; #define PG8_LDA(dst, b, h) do { _Pragma("unroll") for (int m = 0; m < 4; ++m) _Pragma("unroll") for (int k = 0; k < 2; ++k) dst[m][k] = *(const PG8_LAS bf16x8*)(lds + PG8_SA(b, h) + aoff + m * 2048 + k * 1024); } while (0)
; #define PG8_LDB(dst, b, h) do { _Pragma("unroll") for (int n = 0; n < 2; ++n) _Pragma("unroll") for (int k = 0; k < 2; ++k) dst[n][k] = *(const PG8_LAS bf16x8*)(lds + PG8_SB(b, h) + boff + n * 2048 + k * 1024); } while (0)
; #define PG8_MMA(ai, bj, At, Bt) do { __builtin_amdgcn_s_setprio(1); _Pragma("unroll") for (int m = 0; m < 4; ++m) _Pragma("unroll") for (int n = 0; n < 2; ++n) _Pragma("unroll") for (int k = 0; k < 2; ++k) \
;         acc[ai][bj][m][n] = __builtin_amdgcn_mfma_f32_16x16x32_bf16(Bt[n][k], At[m][k], acc[ai][bj][m][n], 0, 0, 0); __builtin_amdgcn_s_setprio(0); } while (0)
; template <class Epi, class Sched, bool ALIGN_EPI = false, bool SP2 = false, bool AGM = false  >
; __device__ __forceinline__ void gemm_phase(PG8_LAS unsigned char* lds, const Gemm g, const Sched& S, const Epi& E) {
;     ...
;         const bool has_next = S.next(ui + 1, nxt);
;         const char* nA = has_next ? (const char*)g.A + (size_t)nxt.pm * tstepA : cA; const char* nB = has_next ? (const char*)g.Bt + (size_t)nxt.pn * tstep : cB;
;         for (int t = 0; t < nt; t += 2) {
;             const bool last = (t == nt - 2);
;             const char* a1 = cA + (size_t)(t + 1) * kstepA;
;             const char* a2 = last ? nA : cA + (size_t)(t + 2) * kstepA; const char* b2 = last ? nB : cB + (size_t)(t + 2) * kstep;
;             const char* a3 = a2 + kstepA; const char* b3 = b2 + kstep;
;             if (last && has_next) S.a_ready(nxt);
;             if constexpr (SP2) {
;             PG8_LDB(B0, 0, 0); PG8_LDB(B1, 0, 1); PG8_SCHED; PG8_LDA(At, 0, 0); PG8_STAGE(PG8_SA(1, 1), a1 + hstepA, voffA);
;             PG8_WAIT_V(8); PG8_WAIT_L(0); PG8_BAR; PG8_MMA(0, 0, At, B0); PG8_MMA(0, 1, At, B1); PG8_BAR; PG8_SCHED;
;             PG8_LDA(At, 0, 1); PG8_STAGE(PG8_SB(0, 0), b2, voffB); PG8_STAGE(PG8_SB(0, 1), b2 + hstep, voffB); PG8_STAGE(PG8_SA(0, 0), a2, voffA);
.LBB0_136:
	s_ashr_i32 s15, s14, 31
	s_lshl_b64 s[16:17], s[14:15], 19
	s_add_u32 s16, s46, s16
	s_addc_u32 s17, s47, s17
	s_and_b64 s[18:19], s[0:1], exec
	s_cselect_b32 s15, s17, s23
	s_cselect_b32 s21, s16, s22
	s_ashr_i32 s13, s12, 31
	s_lshl_b64 s[18:19], s[12:13], 19
	s_add_u32 s18, s3, s18
	s_addc_u32 s19, s28, s19
	s_and_b64 s[26:27], s[0:1], exec
	s_cselect_b32 s13, s19, s25
	s_cselect_b32 s45, s18, s24
	s_add_u32 s22, s22, 0x40080
	s_addc_u32 s23, s23, 0
	s_add_u32 s53, s24, 0x100
	s_addc_u32 s54, s25, 0
	s_mov_b32 s55, -2
	ds_read_b128 v[150:153], v160
	ds_read_b128 v[164:167], v160 offset:1024
	ds_read_b128 v[168:171], v160 offset:2048
	ds_read_b128 v[172:175], v160 offset:3072
	ds_read_b128 v[176:179], v161
	ds_read_b128 v[180:183], v161 offset:1024
	ds_read_b128 v[184:187], v161 offset:2048
	ds_read_b128 v[188:191], v161 offset:3072
	s_add_u32 s24, s22, 0xfffc0080
	s_addc_u32 s25, s23, -1
	s_cmp_eq_u32 s55, 12
	s_cselect_b32 s27, s15, s25
	s_cselect_b32 s26, s21, s24
	s_cselect_b32 s25, s13, s54
	s_cselect_b32 s24, s45, s53
	v_lshl_add_u64 v[224:225], s[22:23], 0, v[142:143]
	s_add_i32 m0, s33, 0xc000
	ds_read_b128 v[192:195], v162
	ds_read_b128 v[196:199], v162 offset:1024
	ds_read_b128 v[200:203], v162 offset:2048
	ds_read_b128 v[204:207], v162 offset:3072
	ds_read_b128 v[208:211], v162 offset:4096
	ds_read_b128 v[212:215], v162 offset:5120
	ds_read_b128 v[216:219], v162 offset:6144
	ds_read_b128 v[220:223], v162 offset:7168
	global_load_lds_dwordx4 v[224:225], off
	v_lshl_add_u64 v[224:225], s[22:23], 0, v[144:145]
	s_add_i32 m0, s33, 0xe000
	s_nop 0
	global_load_lds_dwordx4 v[224:225], off
	s_waitcnt vmcnt(8)
	s_waitcnt lgkmcnt(0)
	s_barrier
	s_setprio 1
	s_waitcnt lgkmcnt(0)
	v_mfma_f32_16x16x32_bf16 v[126:129], v[150:153], v[192:195], 0
	v_mfma_f32_16x16x32_bf16 v[122:125], v[168:171], v[192:195], 0
	v_mfma_f32_16x16x32_bf16 v[114:117], v[150:153], v[200:203], 0
	v_mfma_f32_16x16x32_bf16 v[106:109], v[168:171], v[200:203], 0
	v_mfma_f32_16x16x32_bf16 v[102:105], v[150:153], v[208:211], 0
	v_mfma_f32_16x16x32_bf16 v[94:97], v[168:171], v[208:211], 0
	v_mfma_f32_16x16x32_bf16 v[86:89], v[150:153], v[216:219], 0
	v_mfma_f32_16x16x32_bf16 v[78:81], v[168:171], v[216:219], 0
	v_mfma_f32_16x16x32_bf16 v[126:129], v[164:167], v[196:199], v[126:129]
	v_mfma_f32_16x16x32_bf16 v[122:125], v[172:175], v[196:199], v[122:125]
	v_mfma_f32_16x16x32_bf16 v[114:117], v[164:167], v[204:207], v[114:117]
	v_mfma_f32_16x16x32_bf16 v[106:109], v[172:175], v[204:207], v[106:109]
	v_mfma_f32_16x16x32_bf16 v[102:105], v[164:167], v[212:215], v[102:105]
	v_mfma_f32_16x16x32_bf16 v[94:97], v[172:175], v[212:215], v[94:97]
	v_mfma_f32_16x16x32_bf16 v[86:89], v[164:167], v[220:223], v[86:89]
	v_mfma_f32_16x16x32_bf16 v[78:81], v[172:175], v[220:223], v[78:81]
	s_setprio 0
	s_setprio 1
	v_mfma_f32_16x16x32_bf16 v[118:121], v[176:179], v[192:195], 0
	v_mfma_f32_16x16x32_bf16 v[110:113], v[184:187], v[192:195], 0
	v_mfma_f32_16x16x32_bf16 v[98:101], v[176:179], v[200:203], 0
	v_mfma_f32_16x16x32_bf16 v[90:93], v[184:187], v[200:203], 0
	v_mfma_f32_16x16x32_bf16 v[82:85], v[176:179], v[208:211], 0
	v_mfma_f32_16x16x32_bf16 v[74:77], v[184:187], v[208:211], 0
	v_mfma_f32_16x16x32_bf16 v[70:73], v[176:179], v[216:219], 0
	v_mfma_f32_16x16x32_bf16 v[66:69], v[184:187], v[216:219], 0
	v_mfma_f32_16x16x32_bf16 v[118:121], v[180:183], v[196:199], v[118:121]
	v_mfma_f32_16x16x32_bf16 v[110:113], v[188:191], v[196:199], v[110:113]
	v_mfma_f32_16x16x32_bf16 v[98:101], v[180:183], v[204:207], v[98:101]
	v_mfma_f32_16x16x32_bf16 v[90:93], v[188:191], v[204:207], v[90:93]
	v_mfma_f32_16x16x32_bf16 v[82:85], v[180:183], v[212:215], v[82:85]
	v_mfma_f32_16x16x32_bf16 v[74:77], v[188:191], v[212:215], v[74:77]
	v_mfma_f32_16x16x32_bf16 v[70:73], v[180:183], v[220:223], v[70:73]
	v_mfma_f32_16x16x32_bf16 v[66:69], v[188:191], v[220:223], v[66:69]
	s_setprio 0
	s_barrier
	s_add_i32 s58, s41, s29
	v_lshl_add_u64 v[224:225], s[24:25], 0, v[134:135]
	s_mov_b32 m0, s58
	ds_read_b128 v[192:195], v162 offset:16384
	ds_read_b128 v[196:199], v162 offset:17408
	ds_read_b128 v[200:203], v162 offset:18432
	ds_read_b128 v[204:207], v162 offset:19456
	ds_read_b128 v[208:211], v162 offset:20480
	ds_read_b128 v[212:215], v162 offset:21504
	ds_read_b128 v[216:219], v162 offset:22528
	ds_read_b128 v[220:223], v162 offset:23552
	global_load_lds_dwordx4 v[224:225], off
	s_add_i32 m0, s58, 0x2000
	s_add_u32 s58, s24, 0x40000
	v_lshl_add_u64 v[226:227], s[24:25], 0, v[130:131]
	s_addc_u32 s59, s25, 0
	s_add_i32 s60, s42, s29
	global_load_lds_dwordx4 v[226:227], off
	v_lshl_add_u64 v[228:229], s[58:59], 0, v[134:135]
	s_mov_b32 m0, s60
	v_lshl_add_u64 v[230:231], s[26:27], 0, v[132:133]
	global_load_lds_dwordx4 v[228:229], off
	v_lshl_add_u64 v[228:229], s[58:59], 0, v[130:131]
	s_add_i32 m0, s60, 0x2000
	s_nop 0
	global_load_lds_dwordx4 v[228:229], off
	s_waitcnt vmcnt(6)
	s_waitcnt lgkmcnt(0)
	s_barrier
; #define PG8_STAGE(bufoff, gbase, voff) do { _Pragma("unroll") for (int _i = 0; _i < 2; ++_i) \
;         __builtin_amdgcn_global_load_lds((const unsigned*)((const char*)(gbase) + (voff)[_i]), (PG8_LAS unsigned*)(lds + (bufoff) + ldsw + _i * 8192), 16, 0, 0); } while (0)
; #define PG8_LDA(dst, b, h) do { _Pragma("unroll") for (int m = 0; m < 4; ++m) _Pragma("unroll") for (int k = 0; k < 2; ++k) dst[m][k] = *(const PG8_LAS bf16x8*)(lds + PG8_SA(b, h) + aoff + m * 2048 + k * 1024); } while (0)
; #define PG8_LDB(dst, b, h) do { _Pragma("unroll") for (int n = 0; n < 2; ++n) _Pragma("unroll") for (int k = 0; k < 2; ++k) dst[n][k] = *(const PG8_LAS bf16x8*)(lds + PG8_SB(b, h) + boff + n * 2048 + k * 1024); } while (0)
; #define PG8_MMA(ai, bj, At, Bt) do { __builtin_amdgcn_s_setprio(1); _Pragma("unroll") for (int m = 0; m < 4; ++m) _Pragma("unroll") for (int n = 0; n < 2; ++n) _Pragma("unroll") for (int k = 0; k < 2; ++k) \
;         acc[ai][bj][m][n] = __builtin_amdgcn_mfma_f32_16x16x32_bf16(Bt[n][k], At[m][k], acc[ai][bj][m][n], 0, 0, 0); __builtin_amdgcn_s_setprio(0); } while (0)
; #define PG8_WAIT_V(n) asm volatile("s_waitcnt vmcnt(" #n ")" ::: "memory")
; #define PG8_WAIT_L(n) asm volatile("s_waitcnt lgkmcnt(" #n ")" ::: "memory")
; #define PG8_BAR __builtin_amdgcn_s_barrier()
; #define PG8_SCHED __builtin_amdgcn_sched_barrier(0)
; template <class Epi, class Sched, bool ALIGN_EPI = false, bool SP2 = false, bool AGM = false  >
; __device__ __forceinline__ void gemm_phase(PG8_LAS unsigned char* lds, const Gemm g, const Sched& S, const Epi& E) {
;     ...
;             PG8_LDA(At, 0, 1); PG8_STAGE(PG8_SB(0, 0), b2, voffB); PG8_STAGE(PG8_SB(0, 1), b2 + hstep, voffB); PG8_STAGE(PG8_SA(0, 0), a2, voffA);
;             PG8_WAIT_V(8); PG8_WAIT_L(0); PG8_BAR; PG8_MMA(1, 0, At, B0); PG8_MMA(1, 1, At, B1); PG8_BAR; PG8_SCHED;
;             PG8_LDB(B0, 1, 0); PG8_LDB(B1, 1, 1); PG8_SCHED; PG8_LDA(At, 1, 0); PG8_STAGE(PG8_SA(0, 1), a2 + hstepA, voffA);
;             PG8_WAIT_V(8); PG8_WAIT_L(0); PG8_BAR; PG8_MMA(0, 0, At, B0); PG8_MMA(0, 1, At, B1); PG8_BAR; PG8_SCHED;
	s_setprio 1
	s_waitcnt lgkmcnt(0)
	v_mfma_f32_16x16x32_bf16 v[62:65], v[150:153], v[192:195], 0
	v_mfma_f32_16x16x32_bf16 v[58:61], v[168:171], v[192:195], 0
	v_mfma_f32_16x16x32_bf16 v[54:57], v[150:153], v[200:203], 0
	v_mfma_f32_16x16x32_bf16 v[46:49], v[168:171], v[200:203], 0
	v_mfma_f32_16x16x32_bf16 v[38:41], v[150:153], v[208:211], 0
	v_mfma_f32_16x16x32_bf16 v[30:33], v[168:171], v[208:211], 0
	v_mfma_f32_16x16x32_bf16 v[22:25], v[150:153], v[216:219], 0
	v_mfma_f32_16x16x32_bf16 v[14:17], v[168:171], v[216:219], 0
	v_mfma_f32_16x16x32_bf16 v[62:65], v[164:167], v[196:199], v[62:65]
	v_mfma_f32_16x16x32_bf16 v[58:61], v[172:175], v[196:199], v[58:61]
	v_lshl_add_u64 v[228:229], s[26:27], 0, v[136:137]
	s_mov_b32 m0, s33
	s_nop 0
	global_load_lds_dwordx4 v[228:229], off
	v_mfma_f32_16x16x32_bf16 v[54:57], v[164:167], v[204:207], v[54:57]
	v_mfma_f32_16x16x32_bf16 v[46:49], v[172:175], v[204:207], v[46:49]
	v_mfma_f32_16x16x32_bf16 v[38:41], v[164:167], v[212:215], v[38:41]
	v_mfma_f32_16x16x32_bf16 v[30:33], v[172:175], v[212:215], v[30:33]
	v_mfma_f32_16x16x32_bf16 v[22:25], v[164:167], v[220:223], v[22:25]
	v_mfma_f32_16x16x32_bf16 v[14:17], v[172:175], v[220:223], v[14:17]
	s_setprio 0
	s_setprio 1
	v_mfma_f32_16x16x32_bf16 v[50:53], v[176:179], v[192:195], 0
	v_mfma_f32_16x16x32_bf16 v[42:45], v[184:187], v[192:195], 0
	v_mfma_f32_16x16x32_bf16 v[34:37], v[176:179], v[200:203], 0
	v_mfma_f32_16x16x32_bf16 v[26:29], v[184:187], v[200:203], 0
	v_mfma_f32_16x16x32_bf16 v[18:21], v[176:179], v[208:211], 0
	v_mfma_f32_16x16x32_bf16 v[10:13], v[184:187], v[208:211], 0
	v_mfma_f32_16x16x32_bf16 v[6:9], v[176:179], v[216:219], 0
	v_mfma_f32_16x16x32_bf16 v[2:5], v[184:187], v[216:219], 0
	v_mfma_f32_16x16x32_bf16 v[50:53], v[180:183], v[196:199], v[50:53]
	v_mfma_f32_16x16x32_bf16 v[42:45], v[188:191], v[196:199], v[42:45]
	s_mov_b32 m0, s34
	s_nop 0
	global_load_lds_dwordx4 v[230:231], off
	v_mfma_f32_16x16x32_bf16 v[34:37], v[180:183], v[204:207], v[34:37]
	v_mfma_f32_16x16x32_bf16 v[26:29], v[188:191], v[204:207], v[26:29]
	v_mfma_f32_16x16x32_bf16 v[18:21], v[180:183], v[212:215], v[18:21]
	v_mfma_f32_16x16x32_bf16 v[10:13], v[188:191], v[212:215], v[10:13]
	v_mfma_f32_16x16x32_bf16 v[6:9], v[180:183], v[220:223], v[6:9]
	v_mfma_f32_16x16x32_bf16 v[2:5], v[188:191], v[220:223], v[2:5]
	s_setprio 0
	s_barrier
	s_add_i32 s58, 0, 0x18000
	v_add_u32_e32 v138, s58, v157
	s_add_i32 s59, 0, 0x1c000
	ds_read_b128 v[150:153], v138
	ds_read_b128 v[164:167], v138 offset:1024
	ds_read_b128 v[168:171], v138 offset:2048
	ds_read_b128 v[172:175], v138 offset:3072
	v_add_u32_e32 v138, s59, v157
	ds_read_b128 v[176:179], v138
	ds_read_b128 v[180:183], v138 offset:1024
	ds_read_b128 v[184:187], v138 offset:2048
	ds_read_b128 v[188:191], v138 offset:3072
	s_add_u32 s26, s26, 0x40000
	s_addc_u32 s27, s27, 0
	s_mov_b32 m0, s35
	v_lshl_add_u64 v[232:233], s[26:27], 0, v[136:137]
	ds_read_b128 v[192:195], v162 offset:32768
	ds_read_b128 v[196:199], v162 offset:33792
	ds_read_b128 v[200:203], v162 offset:34816
	ds_read_b128 v[204:207], v162 offset:35840
	ds_read_b128 v[208:211], v162 offset:36864
	ds_read_b128 v[212:215], v162 offset:37888
	ds_read_b128 v[216:219], v162 offset:38912
	ds_read_b128 v[220:223], v162 offset:39936
	global_load_lds_dwordx4 v[232:233], off
	v_lshl_add_u64 v[232:233], s[26:27], 0, v[132:133]
	s_mov_b32 m0, s36
	s_nop 0
	global_load_lds_dwordx4 v[232:233], off
	s_waitcnt vmcnt(8)
	s_waitcnt lgkmcnt(0)
	s_barrier
	s_setprio 1
	s_waitcnt lgkmcnt(0)
	v_mfma_f32_16x16x32_bf16 v[126:129], v[150:153], v[192:195], v[126:129]
	v_mfma_f32_16x16x32_bf16 v[122:125], v[168:171], v[192:195], v[122:125]
	v_mfma_f32_16x16x32_bf16 v[114:117], v[150:153], v[200:203], v[114:117]
	v_mfma_f32_16x16x32_bf16 v[106:109], v[168:171], v[200:203], v[106:109]
	v_mfma_f32_16x16x32_bf16 v[102:105], v[150:153], v[208:211], v[102:105]
	v_mfma_f32_16x16x32_bf16 v[94:97], v[168:171], v[208:211], v[94:97]
	v_mfma_f32_16x16x32_bf16 v[86:89], v[150:153], v[216:219], v[86:89]
	v_mfma_f32_16x16x32_bf16 v[78:81], v[168:171], v[216:219], v[78:81]
	v_mfma_f32_16x16x32_bf16 v[126:129], v[164:167], v[196:199], v[126:129]
	v_mfma_f32_16x16x32_bf16 v[122:125], v[172:175], v[196:199], v[122:125]
	v_mfma_f32_16x16x32_bf16 v[114:117], v[164:167], v[204:207], v[114:117]
	v_mfma_f32_16x16x32_bf16 v[106:109], v[172:175], v[204:207], v[106:109]
	v_mfma_f32_16x16x32_bf16 v[102:105], v[164:167], v[212:215], v[102:105]
	v_mfma_f32_16x16x32_bf16 v[94:97], v[172:175], v[212:215], v[94:97]
	v_mfma_f32_16x16x32_bf16 v[86:89], v[164:167], v[220:223], v[86:89]
	v_mfma_f32_16x16x32_bf16 v[78:81], v[172:175], v[220:223], v[78:81]
	s_setprio 0
	s_setprio 1
	v_mfma_f32_16x16x32_bf16 v[118:121], v[176:179], v[192:195], v[118:121]
	v_mfma_f32_16x16x32_bf16 v[110:113], v[184:187], v[192:195], v[110:113]
	v_mfma_f32_16x16x32_bf16 v[98:101], v[176:179], v[200:203], v[98:101]
	v_mfma_f32_16x16x32_bf16 v[90:93], v[184:187], v[200:203], v[90:93]
	v_mfma_f32_16x16x32_bf16 v[82:85], v[176:179], v[208:211], v[82:85]
	v_mfma_f32_16x16x32_bf16 v[74:77], v[184:187], v[208:211], v[74:77]
	v_mfma_f32_16x16x32_bf16 v[70:73], v[176:179], v[216:219], v[70:73]
	v_mfma_f32_16x16x32_bf16 v[66:69], v[184:187], v[216:219], v[66:69]
	v_mfma_f32_16x16x32_bf16 v[118:121], v[180:183], v[196:199], v[118:121]
	v_mfma_f32_16x16x32_bf16 v[110:113], v[188:191], v[196:199], v[110:113]
	v_mfma_f32_16x16x32_bf16 v[98:101], v[180:183], v[204:207], v[98:101]
	v_mfma_f32_16x16x32_bf16 v[90:93], v[188:191], v[204:207], v[90:93]
	v_mfma_f32_16x16x32_bf16 v[82:85], v[180:183], v[212:215], v[82:85]
	v_mfma_f32_16x16x32_bf16 v[74:77], v[188:191], v[212:215], v[74:77]
	v_mfma_f32_16x16x32_bf16 v[70:73], v[180:183], v[220:223], v[70:73]
	v_mfma_f32_16x16x32_bf16 v[66:69], v[188:191], v[220:223], v[66:69]
	s_setprio 0
	s_barrier
; #define PG8_STAGE(bufoff, gbase, voff) do { _Pragma("unroll") for (int _i = 0; _i < 2; ++_i) \
;         __builtin_amdgcn_global_load_lds((const unsigned*)((const char*)(gbase) + (voff)[_i]), (PG8_LAS unsigned*)(lds + (bufoff) + ldsw + _i * 8192), 16, 0, 0); } while (0)
; #define PG8_LDA(dst, b, h) do { _Pragma("unroll") for (int m = 0; m < 4; ++m) _Pragma("unroll") for (int k = 0; k < 2; ++k) dst[m][k] = *(const PG8_LAS bf16x8*)(lds + PG8_SA(b, h) + aoff + m * 2048 + k * 1024); } while (0)
; #define PG8_LDB(dst, b, h) do { _Pragma("unroll") for (int n = 0; n < 2; ++n) _Pragma("unroll") for (int k = 0; k < 2; ++k) dst[n][k] = *(const PG8_LAS bf16x8*)(lds + PG8_SB(b, h) + boff + n * 2048 + k * 1024); } while (0)
; #define PG8_MMA(ai, bj, At, Bt) do { __builtin_amdgcn_s_setprio(1); _Pragma("unroll") for (int m = 0; m < 4; ++m) _Pragma("unroll") for (int n = 0; n < 2; ++n) _Pragma("unroll") for (int k = 0; k < 2; ++k) \
;         acc[ai][bj][m][n] = __builtin_amdgcn_mfma_f32_16x16x32_bf16(Bt[n][k], At[m][k], acc[ai][bj][m][n], 0, 0, 0); __builtin_amdgcn_s_setprio(0); } while (0)
; #define PG8_WAIT_V(n) asm volatile("s_waitcnt vmcnt(" #n ")" ::: "memory")
; #define PG8_WAIT_L(n) asm volatile("s_waitcnt lgkmcnt(" #n ")" ::: "memory")
; #define PG8_BAR __builtin_amdgcn_s_barrier()
; #define PG8_SCHED __builtin_amdgcn_sched_barrier(0)
; template <class Epi, class Sched, bool ALIGN_EPI = false, bool SP2 = false, bool AGM = false  >
; __device__ __forceinline__ void gemm_phase(PG8_LAS unsigned char* lds, const Gemm g, const Sched& S, const Epi& E) {
;     ...
;             PG8_LDB(B0, 0, 0); PG8_LDB(B1, 0, 1); PG8_SCHED; PG8_LDA(At, 0, 0); PG8_STAGE(PG8_SA(1, 1), a1 + hstepA, voffA);
;             PG8_WAIT_V(8); PG8_WAIT_L(0); PG8_BAR; PG8_MMA(0, 0, At, B0); PG8_MMA(0, 1, At, B1); PG8_BAR; PG8_SCHED;
;     ...
;             PG8_LDA(At, 1, 1); PG8_STAGE(PG8_SB(1, 0), b3, voffB); PG8_STAGE(PG8_SB(1, 1), b3 + hstep, voffB); PG8_STAGE(PG8_SA(1, 0), a3, voffA);
;             PG8_WAIT_V(8); PG8_WAIT_L(0); PG8_BAR; PG8_MMA(1, 0, At, B0); PG8_MMA(1, 1, At, B1); PG8_BAR; PG8_SCHED;
	s_add_i32 s26, s58, s29
	v_lshl_add_u64 v[224:225], v[224:225], 0, s[10:11]
	s_mov_b32 m0, s26
	ds_read_b128 v[192:195], v162 offset:49152
	ds_read_b128 v[196:199], v162 offset:50176
	ds_read_b128 v[200:203], v162 offset:51200
	ds_read_b128 v[204:207], v162 offset:52224
	ds_read_b128 v[208:211], v162 offset:53248
	ds_read_b128 v[212:215], v162 offset:54272
	ds_read_b128 v[216:219], v162 offset:55296
	ds_read_b128 v[220:223], v162 offset:56320
	global_load_lds_dwordx4 v[224:225], off
	s_add_i32 m0, s26, 0x2000
	s_add_u32 s24, s24, 0x40080
	v_lshl_add_u64 v[224:225], v[226:227], 0, s[10:11]
	s_addc_u32 s25, s25, 0
	s_add_i32 s26, s59, s29
	global_load_lds_dwordx4 v[224:225], off
	v_lshl_add_u64 v[224:225], s[24:25], 0, v[134:135]
	s_mov_b32 m0, s26
	s_nop 0
	global_load_lds_dwordx4 v[224:225], off
	v_lshl_add_u64 v[224:225], s[24:25], 0, v[130:131]
	s_add_i32 m0, s26, 0x2000
	s_nop 0
	global_load_lds_dwordx4 v[224:225], off
	s_waitcnt vmcnt(6)
	s_waitcnt lgkmcnt(0)
	s_barrier
	s_setprio 1
	s_waitcnt lgkmcnt(0)
	v_mfma_f32_16x16x32_bf16 v[62:65], v[150:153], v[192:195], v[62:65]
	v_mfma_f32_16x16x32_bf16 v[58:61], v[168:171], v[192:195], v[58:61]
	v_mfma_f32_16x16x32_bf16 v[54:57], v[150:153], v[200:203], v[54:57]
	v_mfma_f32_16x16x32_bf16 v[46:49], v[168:171], v[200:203], v[46:49]
	v_mfma_f32_16x16x32_bf16 v[38:41], v[150:153], v[208:211], v[38:41]
	v_mfma_f32_16x16x32_bf16 v[30:33], v[168:171], v[208:211], v[30:33]
	v_mfma_f32_16x16x32_bf16 v[22:25], v[150:153], v[216:219], v[22:25]
	v_mfma_f32_16x16x32_bf16 v[14:17], v[168:171], v[216:219], v[14:17]
	v_mfma_f32_16x16x32_bf16 v[62:65], v[164:167], v[196:199], v[62:65]
	v_mfma_f32_16x16x32_bf16 v[58:61], v[172:175], v[196:199], v[58:61]
	v_lshl_add_u64 v[224:225], v[228:229], 0, s[10:11]
	s_mov_b32 m0, s38
	s_nop 0
	global_load_lds_dwordx4 v[224:225], off
	v_mfma_f32_16x16x32_bf16 v[54:57], v[164:167], v[204:207], v[54:57]
	v_mfma_f32_16x16x32_bf16 v[46:49], v[172:175], v[204:207], v[46:49]
	v_mfma_f32_16x16x32_bf16 v[38:41], v[164:167], v[212:215], v[38:41]
	v_mfma_f32_16x16x32_bf16 v[30:33], v[172:175], v[212:215], v[30:33]
	v_mfma_f32_16x16x32_bf16 v[22:25], v[164:167], v[220:223], v[22:25]
	v_mfma_f32_16x16x32_bf16 v[14:17], v[172:175], v[220:223], v[14:17]
	s_setprio 0
	s_setprio 1
	v_mfma_f32_16x16x32_bf16 v[50:53], v[176:179], v[192:195], v[50:53]
	v_mfma_f32_16x16x32_bf16 v[42:45], v[184:187], v[192:195], v[42:45]
	v_mfma_f32_16x16x32_bf16 v[34:37], v[176:179], v[200:203], v[34:37]
	v_mfma_f32_16x16x32_bf16 v[26:29], v[184:187], v[200:203], v[26:29]
	v_mfma_f32_16x16x32_bf16 v[18:21], v[176:179], v[208:211], v[18:21]
	v_mfma_f32_16x16x32_bf16 v[10:13], v[184:187], v[208:211], v[10:13]
	v_mfma_f32_16x16x32_bf16 v[6:9], v[176:179], v[216:219], v[6:9]
	v_mfma_f32_16x16x32_bf16 v[2:5], v[184:187], v[216:219], v[2:5]
	v_mfma_f32_16x16x32_bf16 v[50:53], v[180:183], v[196:199], v[50:53]
	v_mfma_f32_16x16x32_bf16 v[42:45], v[188:191], v[196:199], v[42:45]
	v_lshl_add_u64 v[224:225], v[230:231], 0, s[10:11]
	s_mov_b32 m0, s39
	s_nop 0
	global_load_lds_dwordx4 v[224:225], off
	v_mfma_f32_16x16x32_bf16 v[34:37], v[180:183], v[204:207], v[34:37]
	v_mfma_f32_16x16x32_bf16 v[26:29], v[188:191], v[204:207], v[26:29]
	v_mfma_f32_16x16x32_bf16 v[18:21], v[180:183], v[212:215], v[18:21]
	v_mfma_f32_16x16x32_bf16 v[10:13], v[188:191], v[212:215], v[10:13]
	v_mfma_f32_16x16x32_bf16 v[6:9], v[180:183], v[220:223], v[6:9]
	v_mfma_f32_16x16x32_bf16 v[2:5], v[188:191], v[220:223], v[2:5]
	s_setprio 0
	s_barrier
	s_add_i32 s55, s55, 2
	s_add_u32 s22, s22, 0x100
	s_addc_u32 s23, s23, 0
	s_add_u32 s53, s53, 0x100
	s_addc_u32 s54, s54, 0
	s_cmp_gt_u32 s55, 13
	s_cbranch_scc1 .Lpeel_done_p1
	.p2align	6
.LBB0_137:
	ds_read_b128 v[150:153], v160
	ds_read_b128 v[164:167], v160 offset:1024
	ds_read_b128 v[168:171], v160 offset:2048
	ds_read_b128 v[172:175], v160 offset:3072
	ds_read_b128 v[176:179], v161
	ds_read_b128 v[180:183], v161 offset:1024
	ds_read_b128 v[184:187], v161 offset:2048
	ds_read_b128 v[188:191], v161 offset:3072
	s_add_u32 s24, s22, 0xfffc0080
	s_addc_u32 s25, s23, -1
	s_cmp_eq_u32 s55, 12
	s_cselect_b32 s27, s15, s25
	s_cselect_b32 s26, s21, s24
	s_cselect_b32 s25, s13, s54
	s_cselect_b32 s24, s45, s53
	v_lshl_add_u64 v[224:225], s[22:23], 0, v[142:143]
	s_add_i32 m0, s33, 0xc000
	ds_read_b128 v[192:195], v162
	ds_read_b128 v[196:199], v162 offset:1024
	ds_read_b128 v[200:203], v162 offset:2048
	ds_read_b128 v[204:207], v162 offset:3072
	ds_read_b128 v[208:211], v162 offset:4096
	ds_read_b128 v[212:215], v162 offset:5120
	ds_read_b128 v[216:219], v162 offset:6144
	ds_read_b128 v[220:223], v162 offset:7168
	global_load_lds_dwordx4 v[224:225], off
	v_lshl_add_u64 v[224:225], s[22:23], 0, v[144:145]
	s_add_i32 m0, s33, 0xe000
	s_nop 0
	global_load_lds_dwordx4 v[224:225], off
	s_waitcnt vmcnt(8)
	s_waitcnt lgkmcnt(0)
	s_barrier
; #define PG8_STAGE(bufoff, gbase, voff) do { _Pragma("unroll") for (int _i = 0; _i < 2; ++_i) \
;         __builtin_amdgcn_global_load_lds((const unsigned*)((const char*)(gbase) + (voff)[_i]), (PG8_LAS unsigned*)(lds + (bufoff) + ldsw + _i * 8192), 16, 0, 0); } while (0)
; #define PG8_LDA(dst, b, h) do { _Pragma("unroll") for (int m = 0; m < 4; ++m) _Pragma("unroll") for (int k = 0; k < 2; ++k) dst[m][k] = *(const PG8_LAS bf16x8*)(lds + PG8_SA(b, h) + aoff + m * 2048 + k * 1024); } while (0)
; #define PG8_MMA(ai, bj, At, Bt) do { __builtin_amdgcn_s_setprio(1); _Pragma("unroll") for (int m = 0; m < 4; ++m) _Pragma("unroll") for (int n = 0; n < 2; ++n) _Pragma("unroll") for (int k = 0; k < 2; ++k) \
;         acc[ai][bj][m][n] = __builtin_amdgcn_mfma_f32_16x16x32_bf16(Bt[n][k], At[m][k], acc[ai][bj][m][n], 0, 0, 0); __builtin_amdgcn_s_setprio(0); } while (0)
; #define PG8_WAIT_V(n) asm volatile("s_waitcnt vmcnt(" #n ")" ::: "memory")
; #define PG8_WAIT_L(n) asm volatile("s_waitcnt lgkmcnt(" #n ")" ::: "memory")
; #define PG8_BAR __builtin_amdgcn_s_barrier()
; #define PG8_SCHED __builtin_amdgcn_sched_barrier(0)
; template <class Epi, class Sched, bool ALIGN_EPI = false, bool SP2 = false, bool AGM = false  >
; __device__ __forceinline__ void gemm_phase(PG8_LAS unsigned char* lds, const Gemm g, const Sched& S, const Epi& E) {
;     ...
;             PG8_WAIT_V(8); PG8_WAIT_L(0); PG8_BAR; PG8_MMA(0, 0, At, B0); PG8_MMA(0, 1, At, B1); PG8_BAR; PG8_SCHED;
;             PG8_LDA(At, 0, 1); PG8_STAGE(PG8_SB(0, 0), b2, voffB); PG8_STAGE(PG8_SB(0, 1), b2 + hstep, voffB); PG8_STAGE(PG8_SA(0, 0), a2, voffA);
;             PG8_WAIT_V(8); PG8_WAIT_L(0); PG8_BAR; PG8_MMA(1, 0, At, B0); PG8_MMA(1, 1, At, B1); PG8_BAR; PG8_SCHED;
	s_setprio 1
	s_waitcnt lgkmcnt(0)
	v_mfma_f32_16x16x32_bf16 v[126:129], v[150:153], v[192:195], v[126:129]
	v_mfma_f32_16x16x32_bf16 v[122:125], v[168:171], v[192:195], v[122:125]
	v_mfma_f32_16x16x32_bf16 v[114:117], v[150:153], v[200:203], v[114:117]
	v_mfma_f32_16x16x32_bf16 v[106:109], v[168:171], v[200:203], v[106:109]
	v_mfma_f32_16x16x32_bf16 v[102:105], v[150:153], v[208:211], v[102:105]
	v_mfma_f32_16x16x32_bf16 v[94:97], v[168:171], v[208:211], v[94:97]
	v_mfma_f32_16x16x32_bf16 v[86:89], v[150:153], v[216:219], v[86:89]
	v_mfma_f32_16x16x32_bf16 v[78:81], v[168:171], v[216:219], v[78:81]
	v_mfma_f32_16x16x32_bf16 v[126:129], v[164:167], v[196:199], v[126:129]
	v_mfma_f32_16x16x32_bf16 v[122:125], v[172:175], v[196:199], v[122:125]
	v_mfma_f32_16x16x32_bf16 v[114:117], v[164:167], v[204:207], v[114:117]
	v_mfma_f32_16x16x32_bf16 v[106:109], v[172:175], v[204:207], v[106:109]
	v_mfma_f32_16x16x32_bf16 v[102:105], v[164:167], v[212:215], v[102:105]
	v_mfma_f32_16x16x32_bf16 v[94:97], v[172:175], v[212:215], v[94:97]
	v_mfma_f32_16x16x32_bf16 v[86:89], v[164:167], v[220:223], v[86:89]
	v_mfma_f32_16x16x32_bf16 v[78:81], v[172:175], v[220:223], v[78:81]
	s_setprio 0
	s_setprio 1
	v_mfma_f32_16x16x32_bf16 v[118:121], v[176:179], v[192:195], v[118:121]
	v_mfma_f32_16x16x32_bf16 v[110:113], v[184:187], v[192:195], v[110:113]
	v_mfma_f32_16x16x32_bf16 v[98:101], v[176:179], v[200:203], v[98:101]
	v_mfma_f32_16x16x32_bf16 v[90:93], v[184:187], v[200:203], v[90:93]
	v_mfma_f32_16x16x32_bf16 v[82:85], v[176:179], v[208:211], v[82:85]
	v_mfma_f32_16x16x32_bf16 v[74:77], v[184:187], v[208:211], v[74:77]
	v_mfma_f32_16x16x32_bf16 v[70:73], v[176:179], v[216:219], v[70:73]
	v_mfma_f32_16x16x32_bf16 v[66:69], v[184:187], v[216:219], v[66:69]
	v_mfma_f32_16x16x32_bf16 v[118:121], v[180:183], v[196:199], v[118:121]
	v_mfma_f32_16x16x32_bf16 v[110:113], v[188:191], v[196:199], v[110:113]
	v_mfma_f32_16x16x32_bf16 v[98:101], v[180:183], v[204:207], v[98:101]
	v_mfma_f32_16x16x32_bf16 v[90:93], v[188:191], v[204:207], v[90:93]
	v_mfma_f32_16x16x32_bf16 v[82:85], v[180:183], v[212:215], v[82:85]
	v_mfma_f32_16x16x32_bf16 v[74:77], v[188:191], v[212:215], v[74:77]
	v_mfma_f32_16x16x32_bf16 v[70:73], v[180:183], v[220:223], v[70:73]
	v_mfma_f32_16x16x32_bf16 v[66:69], v[188:191], v[220:223], v[66:69]
	s_setprio 0
	s_barrier
	s_add_i32 s58, s41, s29
	v_lshl_add_u64 v[224:225], s[24:25], 0, v[134:135]
	s_mov_b32 m0, s58
	ds_read_b128 v[192:195], v162 offset:16384
	ds_read_b128 v[196:199], v162 offset:17408
	ds_read_b128 v[200:203], v162 offset:18432
	ds_read_b128 v[204:207], v162 offset:19456
	ds_read_b128 v[208:211], v162 offset:20480
	ds_read_b128 v[212:215], v162 offset:21504
	ds_read_b128 v[216:219], v162 offset:22528
	ds_read_b128 v[220:223], v162 offset:23552
	global_load_lds_dwordx4 v[224:225], off
	s_add_i32 m0, s58, 0x2000
	s_add_u32 s58, s24, 0x40000
	v_lshl_add_u64 v[226:227], s[24:25], 0, v[130:131]
	s_addc_u32 s59, s25, 0
	s_add_i32 s60, s42, s29
	global_load_lds_dwordx4 v[226:227], off
	v_lshl_add_u64 v[228:229], s[58:59], 0, v[134:135]
	s_mov_b32 m0, s60
	v_lshl_add_u64 v[230:231], s[26:27], 0, v[132:133]
	global_load_lds_dwordx4 v[228:229], off
	v_lshl_add_u64 v[228:229], s[58:59], 0, v[130:131]
	s_add_i32 m0, s60, 0x2000
	s_nop 0
	global_load_lds_dwordx4 v[228:229], off
	s_waitcnt vmcnt(6)
	s_waitcnt lgkmcnt(0)
	s_barrier
	s_setprio 1
	s_waitcnt lgkmcnt(0)
	v_mfma_f32_16x16x32_bf16 v[62:65], v[150:153], v[192:195], v[62:65]
	v_mfma_f32_16x16x32_bf16 v[58:61], v[168:171], v[192:195], v[58:61]
	v_mfma_f32_16x16x32_bf16 v[54:57], v[150:153], v[200:203], v[54:57]
	v_mfma_f32_16x16x32_bf16 v[46:49], v[168:171], v[200:203], v[46:49]
	v_mfma_f32_16x16x32_bf16 v[38:41], v[150:153], v[208:211], v[38:41]
	v_mfma_f32_16x16x32_bf16 v[30:33], v[168:171], v[208:211], v[30:33]
	v_mfma_f32_16x16x32_bf16 v[22:25], v[150:153], v[216:219], v[22:25]
	v_mfma_f32_16x16x32_bf16 v[14:17], v[168:171], v[216:219], v[14:17]
	v_mfma_f32_16x16x32_bf16 v[62:65], v[164:167], v[196:199], v[62:65]
	v_mfma_f32_16x16x32_bf16 v[58:61], v[172:175], v[196:199], v[58:61]
	v_lshl_add_u64 v[228:229], s[26:27], 0, v[136:137]
	s_mov_b32 m0, s33
	s_nop 0
	global_load_lds_dwordx4 v[228:229], off
	v_mfma_f32_16x16x32_bf16 v[54:57], v[164:167], v[204:207], v[54:57]
	v_mfma_f32_16x16x32_bf16 v[46:49], v[172:175], v[204:207], v[46:49]
	v_mfma_f32_16x16x32_bf16 v[38:41], v[164:167], v[212:215], v[38:41]
	v_mfma_f32_16x16x32_bf16 v[30:33], v[172:175], v[212:215], v[30:33]
	v_mfma_f32_16x16x32_bf16 v[22:25], v[164:167], v[220:223], v[22:25]
	v_mfma_f32_16x16x32_bf16 v[14:17], v[172:175], v[220:223], v[14:17]
	s_setprio 0
	s_setprio 1
	v_mfma_f32_16x16x32_bf16 v[50:53], v[176:179], v[192:195], v[50:53]
	v_mfma_f32_16x16x32_bf16 v[42:45], v[184:187], v[192:195], v[42:45]
	v_mfma_f32_16x16x32_bf16 v[34:37], v[176:179], v[200:203], v[34:37]
	v_mfma_f32_16x16x32_bf16 v[26:29], v[184:187], v[200:203], v[26:29]
	v_mfma_f32_16x16x32_bf16 v[18:21], v[176:179], v[208:211], v[18:21]
	v_mfma_f32_16x16x32_bf16 v[10:13], v[184:187], v[208:211], v[10:13]
	v_mfma_f32_16x16x32_bf16 v[6:9], v[176:179], v[216:219], v[6:9]
	v_mfma_f32_16x16x32_bf16 v[2:5], v[184:187], v[216:219], v[2:5]
	v_mfma_f32_16x16x32_bf16 v[50:53], v[180:183], v[196:199], v[50:53]
	v_mfma_f32_16x16x32_bf16 v[42:45], v[188:191], v[196:199], v[42:45]
	s_mov_b32 m0, s34
	s_nop 0
	global_load_lds_dwordx4 v[230:231], off
	v_mfma_f32_16x16x32_bf16 v[34:37], v[180:183], v[204:207], v[34:37]
	v_mfma_f32_16x16x32_bf16 v[26:29], v[188:191], v[204:207], v[26:29]
	v_mfma_f32_16x16x32_bf16 v[18:21], v[180:183], v[212:215], v[18:21]
	v_mfma_f32_16x16x32_bf16 v[10:13], v[188:191], v[212:215], v[10:13]
	v_mfma_f32_16x16x32_bf16 v[6:9], v[180:183], v[220:223], v[6:9]
	v_mfma_f32_16x16x32_bf16 v[2:5], v[188:191], v[220:223], v[2:5]
	s_setprio 0
	s_barrier
; #define PG8_STAGE(bufoff, gbase, voff) do { _Pragma("unroll") for (int _i = 0; _i < 2; ++_i) \
;         __builtin_amdgcn_global_load_lds((const unsigned*)((const char*)(gbase) + (voff)[_i]), (PG8_LAS unsigned*)(lds + (bufoff) + ldsw + _i * 8192), 16, 0, 0); } while (0)
; #define PG8_LDA(dst, b, h) do { _Pragma("unroll") for (int m = 0; m < 4; ++m) _Pragma("unroll") for (int k = 0; k < 2; ++k) dst[m][k] = *(const PG8_LAS bf16x8*)(lds + PG8_SA(b, h) + aoff + m * 2048 + k * 1024); } while (0)
; #define PG8_LDB(dst, b, h) do { _Pragma("unroll") for (int n = 0; n < 2; ++n) _Pragma("unroll") for (int k = 0; k < 2; ++k) dst[n][k] = *(const PG8_LAS bf16x8*)(lds + PG8_SB(b, h) + boff + n * 2048 + k * 1024); } while (0)
; #define PG8_MMA(ai, bj, At, Bt) do { __builtin_amdgcn_s_setprio(1); _Pragma("unroll") for (int m = 0; m < 4; ++m) _Pragma("unroll") for (int n = 0; n < 2; ++n) _Pragma("unroll") for (int k = 0; k < 2; ++k) \
;         acc[ai][bj][m][n] = __builtin_amdgcn_mfma_f32_16x16x32_bf16(Bt[n][k], At[m][k], acc[ai][bj][m][n], 0, 0, 0); __builtin_amdgcn_s_setprio(0); } while (0)
; #define PG8_WAIT_V(n) asm volatile("s_waitcnt vmcnt(" #n ")" ::: "memory")
; #define PG8_WAIT_L(n) asm volatile("s_waitcnt lgkmcnt(" #n ")" ::: "memory")
; #define PG8_BAR __builtin_amdgcn_s_barrier()
; #define PG8_SCHED __builtin_amdgcn_sched_barrier(0)
; template <class Epi, class Sched, bool ALIGN_EPI = false, bool SP2 = false, bool AGM = false  >
; __device__ __forceinline__ void gemm_phase(PG8_LAS unsigned char* lds, const Gemm g, const Sched& S, const Epi& E) {
;     ...
;             PG8_LDB(B0, 1, 0); PG8_LDB(B1, 1, 1); PG8_SCHED; PG8_LDA(At, 1, 0); PG8_STAGE(PG8_SA(0, 1), a2 + hstepA, voffA);
;             PG8_WAIT_V(8); PG8_WAIT_L(0); PG8_BAR; PG8_MMA(0, 0, At, B0); PG8_MMA(0, 1, At, B1); PG8_BAR; PG8_SCHED;
	s_add_i32 s58, 0, 0x18000
	v_add_u32_e32 v138, s58, v157
	s_add_i32 s59, 0, 0x1c000
	ds_read_b128 v[150:153], v138
	ds_read_b128 v[164:167], v138 offset:1024
	ds_read_b128 v[168:171], v138 offset:2048
	ds_read_b128 v[172:175], v138 offset:3072
	v_add_u32_e32 v138, s59, v157
	ds_read_b128 v[176:179], v138
	ds_read_b128 v[180:183], v138 offset:1024
	ds_read_b128 v[184:187], v138 offset:2048
	ds_read_b128 v[188:191], v138 offset:3072
	s_add_u32 s26, s26, 0x40000
	s_addc_u32 s27, s27, 0
	s_mov_b32 m0, s35
	v_lshl_add_u64 v[232:233], s[26:27], 0, v[136:137]
	ds_read_b128 v[192:195], v162 offset:32768
	ds_read_b128 v[196:199], v162 offset:33792
	ds_read_b128 v[200:203], v162 offset:34816
	ds_read_b128 v[204:207], v162 offset:35840
	ds_read_b128 v[208:211], v162 offset:36864
	ds_read_b128 v[212:215], v162 offset:37888
	ds_read_b128 v[216:219], v162 offset:38912
	ds_read_b128 v[220:223], v162 offset:39936
	global_load_lds_dwordx4 v[232:233], off
	v_lshl_add_u64 v[232:233], s[26:27], 0, v[132:133]
	s_mov_b32 m0, s36
	s_nop 0
	global_load_lds_dwordx4 v[232:233], off
	s_waitcnt vmcnt(8)
	s_waitcnt lgkmcnt(0)
	s_barrier
	s_setprio 1
	s_waitcnt lgkmcnt(0)
	v_mfma_f32_16x16x32_bf16 v[126:129], v[150:153], v[192:195], v[126:129]
	v_mfma_f32_16x16x32_bf16 v[122:125], v[168:171], v[192:195], v[122:125]
	v_mfma_f32_16x16x32_bf16 v[114:117], v[150:153], v[200:203], v[114:117]
	v_mfma_f32_16x16x32_bf16 v[106:109], v[168:171], v[200:203], v[106:109]
	v_mfma_f32_16x16x32_bf16 v[102:105], v[150:153], v[208:211], v[102:105]
	v_mfma_f32_16x16x32_bf16 v[94:97], v[168:171], v[208:211], v[94:97]
	v_mfma_f32_16x16x32_bf16 v[86:89], v[150:153], v[216:219], v[86:89]
	v_mfma_f32_16x16x32_bf16 v[78:81], v[168:171], v[216:219], v[78:81]
	v_mfma_f32_16x16x32_bf16 v[126:129], v[164:167], v[196:199], v[126:129]
	v_mfma_f32_16x16x32_bf16 v[122:125], v[172:175], v[196:199], v[122:125]
	v_mfma_f32_16x16x32_bf16 v[114:117], v[164:167], v[204:207], v[114:117]
	v_mfma_f32_16x16x32_bf16 v[106:109], v[172:175], v[204:207], v[106:109]
	v_mfma_f32_16x16x32_bf16 v[102:105], v[164:167], v[212:215], v[102:105]
	v_mfma_f32_16x16x32_bf16 v[94:97], v[172:175], v[212:215], v[94:97]
	v_mfma_f32_16x16x32_bf16 v[86:89], v[164:167], v[220:223], v[86:89]
	v_mfma_f32_16x16x32_bf16 v[78:81], v[172:175], v[220:223], v[78:81]
	s_setprio 0
	s_setprio 1
	v_mfma_f32_16x16x32_bf16 v[118:121], v[176:179], v[192:195], v[118:121]
	v_mfma_f32_16x16x32_bf16 v[110:113], v[184:187], v[192:195], v[110:113]
	v_mfma_f32_16x16x32_bf16 v[98:101], v[176:179], v[200:203], v[98:101]
	v_mfma_f32_16x16x32_bf16 v[90:93], v[184:187], v[200:203], v[90:93]
	v_mfma_f32_16x16x32_bf16 v[82:85], v[176:179], v[208:211], v[82:85]
	v_mfma_f32_16x16x32_bf16 v[74:77], v[184:187], v[208:211], v[74:77]
	v_mfma_f32_16x16x32_bf16 v[70:73], v[176:179], v[216:219], v[70:73]
	v_mfma_f32_16x16x32_bf16 v[66:69], v[184:187], v[216:219], v[66:69]
	v_mfma_f32_16x16x32_bf16 v[118:121], v[180:183], v[196:199], v[118:121]
	v_mfma_f32_16x16x32_bf16 v[110:113], v[188:191], v[196:199], v[110:113]
	v_mfma_f32_16x16x32_bf16 v[98:101], v[180:183], v[204:207], v[98:101]
	v_mfma_f32_16x16x32_bf16 v[90:93], v[188:191], v[204:207], v[90:93]
	v_mfma_f32_16x16x32_bf16 v[82:85], v[180:183], v[212:215], v[82:85]
	v_mfma_f32_16x16x32_bf16 v[74:77], v[188:191], v[212:215], v[74:77]
	v_mfma_f32_16x16x32_bf16 v[70:73], v[180:183], v[220:223], v[70:73]
	v_mfma_f32_16x16x32_bf16 v[66:69], v[188:191], v[220:223], v[66:69]
	s_setprio 0
	s_barrier
; #define PG8_STAGE(bufoff, gbase, voff) do { _Pragma("unroll") for (int _i = 0; _i < 2; ++_i) \
;         __builtin_amdgcn_global_load_lds((const unsigned*)((const char*)(gbase) + (voff)[_i]), (PG8_LAS unsigned*)(lds + (bufoff) + ldsw + _i * 8192), 16, 0, 0); } while (0)
; #define PG8_LDA(dst, b, h) do { _Pragma("unroll") for (int m = 0; m < 4; ++m) _Pragma("unroll") for (int k = 0; k < 2; ++k) dst[m][k] = *(const PG8_LAS bf16x8*)(lds + PG8_SA(b, h) + aoff + m * 2048 + k * 1024); } while (0)
; #define PG8_MMA(ai, bj, At, Bt) do { __builtin_amdgcn_s_setprio(1); _Pragma("unroll") for (int m = 0; m < 4; ++m) _Pragma("unroll") for (int n = 0; n < 2; ++n) _Pragma("unroll") for (int k = 0; k < 2; ++k) \
;         acc[ai][bj][m][n] = __builtin_amdgcn_mfma_f32_16x16x32_bf16(Bt[n][k], At[m][k], acc[ai][bj][m][n], 0, 0, 0); __builtin_amdgcn_s_setprio(0); } while (0)
; #define PG8_WAIT_V(n) asm volatile("s_waitcnt vmcnt(" #n ")" ::: "memory")
; #define PG8_WAIT_L(n) asm volatile("s_waitcnt lgkmcnt(" #n ")" ::: "memory")
; #define PG8_BAR __builtin_amdgcn_s_barrier()
; #define PG8_SCHED __builtin_amdgcn_sched_barrier(0)
; template <class Epi, class Sched, bool ALIGN_EPI = false, bool SP2 = false, bool AGM = false  >
; __device__ __forceinline__ void gemm_phase(PG8_LAS unsigned char* lds, const Gemm g, const Sched& S, const Epi& E) {
;     ...
;             PG8_LDA(At, 1, 1); PG8_STAGE(PG8_SB(1, 0), b3, voffB); PG8_STAGE(PG8_SB(1, 1), b3 + hstep, voffB); PG8_STAGE(PG8_SA(1, 0), a3, voffA);
;             PG8_WAIT_V(8); PG8_WAIT_L(0); PG8_BAR; PG8_MMA(1, 0, At, B0); PG8_MMA(1, 1, At, B1); PG8_BAR; PG8_SCHED;
	s_add_i32 s26, s58, s29
	v_lshl_add_u64 v[224:225], v[224:225], 0, s[10:11]
	s_mov_b32 m0, s26
	ds_read_b128 v[192:195], v162 offset:49152
	ds_read_b128 v[196:199], v162 offset:50176
	ds_read_b128 v[200:203], v162 offset:51200
	ds_read_b128 v[204:207], v162 offset:52224
	ds_read_b128 v[208:211], v162 offset:53248
	ds_read_b128 v[212:215], v162 offset:54272
	ds_read_b128 v[216:219], v162 offset:55296
	ds_read_b128 v[220:223], v162 offset:56320
	global_load_lds_dwordx4 v[224:225], off
	s_add_i32 m0, s26, 0x2000
	s_add_u32 s24, s24, 0x40080
	v_lshl_add_u64 v[224:225], v[226:227], 0, s[10:11]
	s_addc_u32 s25, s25, 0
	s_add_i32 s26, s59, s29
	global_load_lds_dwordx4 v[224:225], off
	v_lshl_add_u64 v[224:225], s[24:25], 0, v[134:135]
	s_mov_b32 m0, s26
	s_nop 0
	global_load_lds_dwordx4 v[224:225], off
	v_lshl_add_u64 v[224:225], s[24:25], 0, v[130:131]
	s_add_i32 m0, s26, 0x2000
	s_nop 0
	global_load_lds_dwordx4 v[224:225], off
	s_waitcnt vmcnt(6)
	s_waitcnt lgkmcnt(0)
	s_barrier
	s_setprio 1
	s_waitcnt lgkmcnt(0)
	v_mfma_f32_16x16x32_bf16 v[62:65], v[150:153], v[192:195], v[62:65]
	v_mfma_f32_16x16x32_bf16 v[58:61], v[168:171], v[192:195], v[58:61]
	v_mfma_f32_16x16x32_bf16 v[54:57], v[150:153], v[200:203], v[54:57]
	v_mfma_f32_16x16x32_bf16 v[46:49], v[168:171], v[200:203], v[46:49]
	v_mfma_f32_16x16x32_bf16 v[38:41], v[150:153], v[208:211], v[38:41]
	v_mfma_f32_16x16x32_bf16 v[30:33], v[168:171], v[208:211], v[30:33]
	v_mfma_f32_16x16x32_bf16 v[22:25], v[150:153], v[216:219], v[22:25]
	v_mfma_f32_16x16x32_bf16 v[14:17], v[168:171], v[216:219], v[14:17]
	v_mfma_f32_16x16x32_bf16 v[62:65], v[164:167], v[196:199], v[62:65]
	v_mfma_f32_16x16x32_bf16 v[58:61], v[172:175], v[196:199], v[58:61]
	v_lshl_add_u64 v[224:225], v[228:229], 0, s[10:11]
	s_mov_b32 m0, s38
	s_nop 0
	global_load_lds_dwordx4 v[224:225], off
	v_mfma_f32_16x16x32_bf16 v[54:57], v[164:167], v[204:207], v[54:57]
	v_mfma_f32_16x16x32_bf16 v[46:49], v[172:175], v[204:207], v[46:49]
	v_mfma_f32_16x16x32_bf16 v[38:41], v[164:167], v[212:215], v[38:41]
	v_mfma_f32_16x16x32_bf16 v[30:33], v[172:175], v[212:215], v[30:33]
	v_mfma_f32_16x16x32_bf16 v[22:25], v[164:167], v[220:223], v[22:25]
	v_mfma_f32_16x16x32_bf16 v[14:17], v[172:175], v[220:223], v[14:17]
	s_setprio 0
	s_setprio 1
	v_mfma_f32_16x16x32_bf16 v[50:53], v[176:179], v[192:195], v[50:53]
	v_mfma_f32_16x16x32_bf16 v[42:45], v[184:187], v[192:195], v[42:45]
	v_mfma_f32_16x16x32_bf16 v[34:37], v[176:179], v[200:203], v[34:37]
	v_mfma_f32_16x16x32_bf16 v[26:29], v[184:187], v[200:203], v[26:29]
	v_mfma_f32_16x16x32_bf16 v[18:21], v[176:179], v[208:211], v[18:21]
	v_mfma_f32_16x16x32_bf16 v[10:13], v[184:187], v[208:211], v[10:13]
	v_mfma_f32_16x16x32_bf16 v[6:9], v[176:179], v[216:219], v[6:9]
	v_mfma_f32_16x16x32_bf16 v[2:5], v[184:187], v[216:219], v[2:5]
	v_mfma_f32_16x16x32_bf16 v[50:53], v[180:183], v[196:199], v[50:53]
	v_mfma_f32_16x16x32_bf16 v[42:45], v[188:191], v[196:199], v[42:45]
	v_lshl_add_u64 v[224:225], v[230:231], 0, s[10:11]
	s_mov_b32 m0, s39
	s_nop 0
	global_load_lds_dwordx4 v[224:225], off
	v_mfma_f32_16x16x32_bf16 v[34:37], v[180:183], v[204:207], v[34:37]
	v_mfma_f32_16x16x32_bf16 v[26:29], v[188:191], v[204:207], v[26:29]
	v_mfma_f32_16x16x32_bf16 v[18:21], v[180:183], v[212:215], v[18:21]
	v_mfma_f32_16x16x32_bf16 v[10:13], v[188:191], v[212:215], v[10:13]
	v_mfma_f32_16x16x32_bf16 v[6:9], v[180:183], v[220:223], v[6:9]
	v_mfma_f32_16x16x32_bf16 v[2:5], v[188:191], v[220:223], v[2:5]
	s_setprio 0
	s_barrier
	s_add_i32 s55, s55, 2
	s_add_u32 s22, s22, 0x100
	s_addc_u32 s23, s23, 0
	s_add_u32 s53, s53, 0x100
	s_addc_u32 s54, s54, 0
	s_cmp_gt_u32 s55, 13
	s_cbranch_scc0 .LBB0_137

; #define PG8_STAGE(bufoff, gbase, voff) do { _Pragma("unroll") for (int _i = 0; _i < 2; ++_i) \
;         __builtin_amdgcn_global_load_lds((const unsigned*)((const char*)(gbase) + (voff)[_i]), (PG8_LAS unsigned*)(lds + (bufoff) + ldsw + _i * 8192), 16, 0, 0); } while (0)
; #define PG8_LDA(dst, b, h) do { _Pragma("unroll") for (int m = 0; m < 4; ++m) _Pragma("unroll") for (int k = 0; k < 2; ++k) dst[m][k] = *(const PG8_LAS bf16x8*)(lds + PG8_SA(b, h) + aoff + m * 2048 + k * 1024); } while (0)
; #define PG8_LDB(dst, b, h) do { _Pragma("unroll") for (int n = 0; n < 2; ++n) _Pragma("unroll") for (int k = 0; k < 2; ++k) dst[n][k] = *(const PG8_LAS bf16x8*)(lds + PG8_SB(b, h) + boff + n * 2048 + k * 1024); } while (0)
; #define PG8_MMA(ai, bj, At, Bt) do { __builtin_amdgcn_s_setprio(1); _Pragma("unroll") for (int m = 0; m < 4; ++m) _Pragma("unroll") for (int n = 0; n < 2; ++n) _Pragma("unroll") for (int k = 0; k < 2; ++k) \
;         acc[ai][bj][m][n] = __builtin_amdgcn_mfma_f32_16x16x32_bf16(Bt[n][k], At[m][k], acc[ai][bj][m][n], 0, 0, 0); __builtin_amdgcn_s_setprio(0); } while (0)
; #define PG8_WAIT_V(n) asm volatile("s_waitcnt vmcnt(" #n ")" ::: "memory")
; #define PG8_WAIT_L(n) asm volatile("s_waitcnt lgkmcnt(" #n ")" ::: "memory")
; template <class Epi, class Sched, bool ALIGN_EPI = false, bool SP2 = false, bool AGM = false  >
; __device__ __forceinline__ void gemm_phase(PG8_LAS unsigned char* lds, const Gemm g, const Sched& S, const Epi& E) {
;     ...
;             const bool last = (t == nt - 2);
;             const char* a1 = cA + (size_t)(t + 1) * kstepA;
;             const char* a2 = last ? nA : cA + (size_t)(t + 2) * kstepA; const char* b2 = last ? nB : cB + (size_t)(t + 2) * kstep;
;             const char* a3 = a2 + kstepA; const char* b3 = b2 + kstep;
;             if (last && has_next) S.a_ready(nxt);
;             if constexpr (SP2) {
;             PG8_LDB(B0, 0, 0); PG8_LDB(B1, 0, 1); PG8_SCHED; PG8_LDA(At, 0, 0); PG8_STAGE(PG8_SA(1, 1), a1 + hstepA, voffA);
;             PG8_WAIT_V(8); PG8_WAIT_L(0); PG8_BAR; PG8_MMA(0, 0, At, B0); PG8_MMA(0, 1, At, B1); PG8_BAR; PG8_SCHED;
;             PG8_LDA(At, 0, 1); PG8_STAGE(PG8_SB(0, 0), b2, voffB); PG8_STAGE(PG8_SB(0, 1), b2 + hstep, voffB); PG8_STAGE(PG8_SA(0, 0), a2, voffA);
;             PG8_WAIT_V(8); PG8_WAIT_L(0); PG8_BAR; PG8_MMA(1, 0, At, B0); PG8_MMA(1, 1, At, B1); PG8_BAR; PG8_SCHED;
.LBB0_677:
	ds_read_b128 v[150:153], v157
	ds_read_b128 v[164:167], v157 offset:1024
	ds_read_b128 v[168:171], v157 offset:2048
	ds_read_b128 v[172:175], v157 offset:3072
	ds_read_b128 v[176:179], v158
	ds_read_b128 v[180:183], v158 offset:1024
	ds_read_b128 v[184:187], v158 offset:2048
	ds_read_b128 v[188:191], v158 offset:3072
	s_add_u32 s26, s24, 0x440000
	s_addc_u32 s27, s25, 0
	s_cmp_eq_u32 s70, 4
	s_cselect_b32 s34, s62, s26
	s_cselect_b32 s35, s19, s27
	s_cselect_b32 s30, s63, s68
	s_cselect_b32 s31, s17, s69
	s_add_u32 s28, s34, 0x220000
	s_addc_u32 s29, s35, 0
	v_lshl_add_u64 v[224:225], s[24:25], 0, v[142:143]
	s_add_i32 m0, s5, 0xc000
	ds_read_b128 v[192:195], v159
	ds_read_b128 v[196:199], v159 offset:1024
	ds_read_b128 v[200:203], v159 offset:2048
	ds_read_b128 v[204:207], v159 offset:3072
	ds_read_b128 v[208:211], v159 offset:4096
	ds_read_b128 v[212:215], v159 offset:5120
	ds_read_b128 v[216:219], v159 offset:6144
	ds_read_b128 v[220:223], v159 offset:7168
	global_load_lds_dwordx4 v[224:225], off
	v_lshl_add_u64 v[224:225], s[24:25], 0, v[144:145]
	s_add_i32 m0, s5, 0xe000
	s_nop 0
	global_load_lds_dwordx4 v[224:225], off
	s_waitcnt vmcnt(8)
	s_waitcnt lgkmcnt(0)
	s_barrier
	s_setprio 1
	s_waitcnt lgkmcnt(0)
	v_mfma_f32_16x16x32_bf16 v[126:129], v[150:153], v[192:195], v[126:129]
	v_mfma_f32_16x16x32_bf16 v[122:125], v[168:171], v[192:195], v[122:125]
	v_mfma_f32_16x16x32_bf16 v[110:113], v[150:153], v[200:203], v[110:113]
	v_mfma_f32_16x16x32_bf16 v[106:109], v[168:171], v[200:203], v[106:109]
	v_mfma_f32_16x16x32_bf16 v[94:97], v[150:153], v[208:211], v[94:97]
	v_mfma_f32_16x16x32_bf16 v[90:93], v[168:171], v[208:211], v[90:93]
	v_mfma_f32_16x16x32_bf16 v[78:81], v[150:153], v[216:219], v[78:81]
	v_mfma_f32_16x16x32_bf16 v[74:77], v[168:171], v[216:219], v[74:77]
	v_mfma_f32_16x16x32_bf16 v[126:129], v[164:167], v[196:199], v[126:129]
	v_mfma_f32_16x16x32_bf16 v[122:125], v[172:175], v[196:199], v[122:125]
	v_mfma_f32_16x16x32_bf16 v[110:113], v[164:167], v[204:207], v[110:113]
	v_mfma_f32_16x16x32_bf16 v[106:109], v[172:175], v[204:207], v[106:109]
	v_mfma_f32_16x16x32_bf16 v[94:97], v[164:167], v[212:215], v[94:97]
	v_mfma_f32_16x16x32_bf16 v[90:93], v[172:175], v[212:215], v[90:93]
	v_mfma_f32_16x16x32_bf16 v[78:81], v[164:167], v[220:223], v[78:81]
	v_mfma_f32_16x16x32_bf16 v[74:77], v[172:175], v[220:223], v[74:77]
	s_setprio 0
	s_setprio 1
	v_mfma_f32_16x16x32_bf16 v[118:121], v[176:179], v[192:195], v[118:121]
	v_mfma_f32_16x16x32_bf16 v[114:117], v[184:187], v[192:195], v[114:117]
	v_mfma_f32_16x16x32_bf16 v[102:105], v[176:179], v[200:203], v[102:105]
	v_mfma_f32_16x16x32_bf16 v[98:101], v[184:187], v[200:203], v[98:101]
	v_mfma_f32_16x16x32_bf16 v[86:89], v[176:179], v[208:211], v[86:89]
	v_mfma_f32_16x16x32_bf16 v[82:85], v[184:187], v[208:211], v[82:85]
	v_mfma_f32_16x16x32_bf16 v[70:73], v[176:179], v[216:219], v[70:73]
	v_mfma_f32_16x16x32_bf16 v[66:69], v[184:187], v[216:219], v[66:69]
	v_mfma_f32_16x16x32_bf16 v[118:121], v[180:183], v[196:199], v[118:121]
	v_mfma_f32_16x16x32_bf16 v[114:117], v[188:191], v[196:199], v[114:117]
	v_mfma_f32_16x16x32_bf16 v[102:105], v[180:183], v[204:207], v[102:105]
	v_mfma_f32_16x16x32_bf16 v[98:101], v[188:191], v[204:207], v[98:101]
	v_mfma_f32_16x16x32_bf16 v[86:89], v[180:183], v[212:215], v[86:89]
	v_mfma_f32_16x16x32_bf16 v[82:85], v[188:191], v[212:215], v[82:85]
	v_mfma_f32_16x16x32_bf16 v[70:73], v[180:183], v[220:223], v[70:73]
	v_mfma_f32_16x16x32_bf16 v[66:69], v[188:191], v[220:223], v[66:69]
	s_setprio 0
	s_barrier
	s_add_i32 s24, s54, s37
	v_lshl_add_u64 v[224:225], s[30:31], 0, v[134:135]
	s_mov_b32 m0, s24
	ds_read_b128 v[192:195], v159 offset:16384
	ds_read_b128 v[196:199], v159 offset:17408
	ds_read_b128 v[200:203], v159 offset:18432
	ds_read_b128 v[204:207], v159 offset:19456
	ds_read_b128 v[208:211], v159 offset:20480
	ds_read_b128 v[212:215], v159 offset:21504
	ds_read_b128 v[216:219], v159 offset:22528
	ds_read_b128 v[220:223], v159 offset:23552
	global_load_lds_dwordx4 v[224:225], off
	s_add_i32 m0, s24, 0x2000
	s_add_u32 s24, s30, 0x20000
	v_lshl_add_u64 v[226:227], s[30:31], 0, v[130:131]
	s_addc_u32 s25, s31, 0
	s_add_i32 s71, s55, s37
	global_load_lds_dwordx4 v[226:227], off
	v_lshl_add_u64 v[228:229], s[24:25], 0, v[134:135]
	s_mov_b32 m0, s71
	s_nop 0
	global_load_lds_dwordx4 v[228:229], off
	v_lshl_add_u64 v[228:229], s[24:25], 0, v[130:131]
	s_add_i32 m0, s71, 0x2000
	s_nop 0
	global_load_lds_dwordx4 v[228:229], off
	s_waitcnt vmcnt(6)
	s_waitcnt lgkmcnt(0)
	s_barrier
; #define PG8_STAGE(bufoff, gbase, voff) do { _Pragma("unroll") for (int _i = 0; _i < 2; ++_i) \
;         __builtin_amdgcn_global_load_lds((const unsigned*)((const char*)(gbase) + (voff)[_i]), (PG8_LAS unsigned*)(lds + (bufoff) + ldsw + _i * 8192), 16, 0, 0); } while (0)
; #define PG8_LDA(dst, b, h) do { _Pragma("unroll") for (int m = 0; m < 4; ++m) _Pragma("unroll") for (int k = 0; k < 2; ++k) dst[m][k] = *(const PG8_LAS bf16x8*)(lds + PG8_SA(b, h) + aoff + m * 2048 + k * 1024); } while (0)
; #define PG8_LDB(dst, b, h) do { _Pragma("unroll") for (int n = 0; n < 2; ++n) _Pragma("unroll") for (int k = 0; k < 2; ++k) dst[n][k] = *(const PG8_LAS bf16x8*)(lds + PG8_SB(b, h) + boff + n * 2048 + k * 1024); } while (0)
; #define PG8_MMA(ai, bj, At, Bt) do { __builtin_amdgcn_s_setprio(1); _Pragma("unroll") for (int m = 0; m < 4; ++m) _Pragma("unroll") for (int n = 0; n < 2; ++n) _Pragma("unroll") for (int k = 0; k < 2; ++k) \
;         acc[ai][bj][m][n] = __builtin_amdgcn_mfma_f32_16x16x32_bf16(Bt[n][k], At[m][k], acc[ai][bj][m][n], 0, 0, 0); __builtin_amdgcn_s_setprio(0); } while (0)
; #define PG8_WAIT_V(n) asm volatile("s_waitcnt vmcnt(" #n ")" ::: "memory")
; #define PG8_WAIT_L(n) asm volatile("s_waitcnt lgkmcnt(" #n ")" ::: "memory")
; #define PG8_BAR __builtin_amdgcn_s_barrier()
; #define PG8_SCHED __builtin_amdgcn_sched_barrier(0)
; template <class Epi, class Sched, bool ALIGN_EPI = false, bool SP2 = false, bool AGM = false  >
; __device__ __forceinline__ void gemm_phase(PG8_LAS unsigned char* lds, const Gemm g, const Sched& S, const Epi& E) {
;     ...
;             PG8_LDA(At, 0, 1); PG8_STAGE(PG8_SB(0, 0), b2, voffB); PG8_STAGE(PG8_SB(0, 1), b2 + hstep, voffB); PG8_STAGE(PG8_SA(0, 0), a2, voffA);
;             PG8_WAIT_V(8); PG8_WAIT_L(0); PG8_BAR; PG8_MMA(1, 0, At, B0); PG8_MMA(1, 1, At, B1); PG8_BAR; PG8_SCHED;
;             PG8_LDB(B0, 1, 0); PG8_LDB(B1, 1, 1); PG8_SCHED; PG8_LDA(At, 1, 0); PG8_STAGE(PG8_SA(0, 1), a2 + hstepA, voffA);
;             PG8_WAIT_V(8); PG8_WAIT_L(0); PG8_BAR; PG8_MMA(0, 0, At, B0); PG8_MMA(0, 1, At, B1); PG8_BAR; PG8_SCHED;
	s_setprio 1
	s_waitcnt lgkmcnt(0)
	v_mfma_f32_16x16x32_bf16 v[62:65], v[150:153], v[192:195], v[62:65]
	v_mfma_f32_16x16x32_bf16 v[58:61], v[168:171], v[192:195], v[58:61]
	v_mfma_f32_16x16x32_bf16 v[46:49], v[150:153], v[200:203], v[46:49]
	v_mfma_f32_16x16x32_bf16 v[42:45], v[168:171], v[200:203], v[42:45]
	v_mfma_f32_16x16x32_bf16 v[30:33], v[150:153], v[208:211], v[30:33]
	v_mfma_f32_16x16x32_bf16 v[26:29], v[168:171], v[208:211], v[26:29]
	v_mfma_f32_16x16x32_bf16 v[14:17], v[150:153], v[216:219], v[14:17]
	v_mfma_f32_16x16x32_bf16 v[10:13], v[168:171], v[216:219], v[10:13]
	v_mfma_f32_16x16x32_bf16 v[62:65], v[164:167], v[196:199], v[62:65]
	v_mfma_f32_16x16x32_bf16 v[58:61], v[172:175], v[196:199], v[58:61]
	v_lshl_add_u64 v[228:229], s[34:35], 0, v[136:137]
	s_mov_b32 m0, s5
	s_nop 0
	global_load_lds_dwordx4 v[228:229], off
	v_mfma_f32_16x16x32_bf16 v[46:49], v[164:167], v[204:207], v[46:49]
	v_mfma_f32_16x16x32_bf16 v[42:45], v[172:175], v[204:207], v[42:45]
	v_mfma_f32_16x16x32_bf16 v[30:33], v[164:167], v[212:215], v[30:33]
	v_mfma_f32_16x16x32_bf16 v[26:29], v[172:175], v[212:215], v[26:29]
	v_mfma_f32_16x16x32_bf16 v[14:17], v[164:167], v[220:223], v[14:17]
	v_mfma_f32_16x16x32_bf16 v[10:13], v[172:175], v[220:223], v[10:13]
	s_setprio 0
	s_setprio 1
	v_mfma_f32_16x16x32_bf16 v[54:57], v[176:179], v[192:195], v[54:57]
	v_mfma_f32_16x16x32_bf16 v[50:53], v[184:187], v[192:195], v[50:53]
	v_mfma_f32_16x16x32_bf16 v[38:41], v[176:179], v[200:203], v[38:41]
	v_mfma_f32_16x16x32_bf16 v[34:37], v[184:187], v[200:203], v[34:37]
	v_mfma_f32_16x16x32_bf16 v[22:25], v[176:179], v[208:211], v[22:25]
	v_mfma_f32_16x16x32_bf16 v[18:21], v[184:187], v[208:211], v[18:21]
	v_mfma_f32_16x16x32_bf16 v[6:9], v[176:179], v[216:219], v[6:9]
	v_mfma_f32_16x16x32_bf16 v[2:5], v[184:187], v[216:219], v[2:5]
	v_mfma_f32_16x16x32_bf16 v[54:57], v[180:183], v[196:199], v[54:57]
	v_mfma_f32_16x16x32_bf16 v[50:53], v[188:191], v[196:199], v[50:53]
	v_lshl_add_u64 v[228:229], s[34:35], 0, v[132:133]
	s_mov_b32 m0, s39
	s_nop 0
	global_load_lds_dwordx4 v[228:229], off
	v_mfma_f32_16x16x32_bf16 v[38:41], v[180:183], v[204:207], v[38:41]
	v_mfma_f32_16x16x32_bf16 v[34:37], v[188:191], v[204:207], v[34:37]
	v_mfma_f32_16x16x32_bf16 v[22:25], v[180:183], v[212:215], v[22:25]
	v_mfma_f32_16x16x32_bf16 v[18:21], v[188:191], v[212:215], v[18:21]
	v_mfma_f32_16x16x32_bf16 v[6:9], v[180:183], v[220:223], v[6:9]
	v_mfma_f32_16x16x32_bf16 v[2:5], v[188:191], v[220:223], v[2:5]
	s_setprio 0
	s_barrier
	s_add_i32 s71, 0, 0x18000
	v_add_u32_e32 v163, s71, v155
	s_add_i32 s72, 0, 0x1c000
	ds_read_b128 v[150:153], v163
	ds_read_b128 v[164:167], v163 offset:1024
	ds_read_b128 v[168:171], v163 offset:2048
	ds_read_b128 v[172:175], v163 offset:3072
	v_add_u32_e32 v163, s72, v155
	ds_read_b128 v[176:179], v163
	ds_read_b128 v[180:183], v163 offset:1024
	ds_read_b128 v[184:187], v163 offset:2048
	ds_read_b128 v[188:191], v163 offset:3072
	s_add_u32 s24, s34, 0x1000
	s_addc_u32 s25, s35, 0
	s_mov_b32 m0, s40
	v_lshl_add_u64 v[228:229], s[24:25], 0, v[136:137]
	ds_read_b128 v[192:195], v159 offset:32768
	ds_read_b128 v[196:199], v159 offset:33792
	ds_read_b128 v[200:203], v159 offset:34816
	ds_read_b128 v[204:207], v159 offset:35840
	ds_read_b128 v[208:211], v159 offset:36864
	ds_read_b128 v[212:215], v159 offset:37888
	ds_read_b128 v[216:219], v159 offset:38912
	ds_read_b128 v[220:223], v159 offset:39936
	global_load_lds_dwordx4 v[228:229], off
	v_lshl_add_u64 v[228:229], s[24:25], 0, v[132:133]
	s_mov_b32 m0, s41
	s_nop 0
	global_load_lds_dwordx4 v[228:229], off
	s_waitcnt vmcnt(8)
	s_waitcnt lgkmcnt(0)
	s_barrier
	s_setprio 1
	s_waitcnt lgkmcnt(0)
	v_mfma_f32_16x16x32_bf16 v[126:129], v[150:153], v[192:195], v[126:129]
	v_mfma_f32_16x16x32_bf16 v[122:125], v[168:171], v[192:195], v[122:125]
	v_mfma_f32_16x16x32_bf16 v[110:113], v[150:153], v[200:203], v[110:113]
	v_mfma_f32_16x16x32_bf16 v[106:109], v[168:171], v[200:203], v[106:109]
	v_mfma_f32_16x16x32_bf16 v[94:97], v[150:153], v[208:211], v[94:97]
	v_mfma_f32_16x16x32_bf16 v[90:93], v[168:171], v[208:211], v[90:93]
	v_mfma_f32_16x16x32_bf16 v[78:81], v[150:153], v[216:219], v[78:81]
	v_mfma_f32_16x16x32_bf16 v[74:77], v[168:171], v[216:219], v[74:77]
	v_mfma_f32_16x16x32_bf16 v[126:129], v[164:167], v[196:199], v[126:129]
	v_mfma_f32_16x16x32_bf16 v[122:125], v[172:175], v[196:199], v[122:125]
	v_mfma_f32_16x16x32_bf16 v[110:113], v[164:167], v[204:207], v[110:113]
	v_mfma_f32_16x16x32_bf16 v[106:109], v[172:175], v[204:207], v[106:109]
	v_mfma_f32_16x16x32_bf16 v[94:97], v[164:167], v[212:215], v[94:97]
	v_mfma_f32_16x16x32_bf16 v[90:93], v[172:175], v[212:215], v[90:93]
	v_mfma_f32_16x16x32_bf16 v[78:81], v[164:167], v[220:223], v[78:81]
	v_mfma_f32_16x16x32_bf16 v[74:77], v[172:175], v[220:223], v[74:77]
	s_setprio 0
	s_setprio 1
	v_mfma_f32_16x16x32_bf16 v[118:121], v[176:179], v[192:195], v[118:121]
	v_mfma_f32_16x16x32_bf16 v[114:117], v[184:187], v[192:195], v[114:117]
	v_mfma_f32_16x16x32_bf16 v[102:105], v[176:179], v[200:203], v[102:105]
	v_mfma_f32_16x16x32_bf16 v[98:101], v[184:187], v[200:203], v[98:101]
	v_mfma_f32_16x16x32_bf16 v[86:89], v[176:179], v[208:211], v[86:89]
	v_mfma_f32_16x16x32_bf16 v[82:85], v[184:187], v[208:211], v[82:85]
	v_mfma_f32_16x16x32_bf16 v[70:73], v[176:179], v[216:219], v[70:73]
	v_mfma_f32_16x16x32_bf16 v[66:69], v[184:187], v[216:219], v[66:69]
	v_mfma_f32_16x16x32_bf16 v[118:121], v[180:183], v[196:199], v[118:121]
	v_mfma_f32_16x16x32_bf16 v[114:117], v[188:191], v[196:199], v[114:117]
	v_mfma_f32_16x16x32_bf16 v[102:105], v[180:183], v[204:207], v[102:105]
	v_mfma_f32_16x16x32_bf16 v[98:101], v[188:191], v[204:207], v[98:101]
	v_mfma_f32_16x16x32_bf16 v[86:89], v[180:183], v[212:215], v[86:89]
	v_mfma_f32_16x16x32_bf16 v[82:85], v[188:191], v[212:215], v[82:85]
	v_mfma_f32_16x16x32_bf16 v[70:73], v[180:183], v[220:223], v[70:73]
	v_mfma_f32_16x16x32_bf16 v[66:69], v[188:191], v[220:223], v[66:69]
	s_setprio 0
	s_barrier
; #define PG8_STAGE(bufoff, gbase, voff) do { _Pragma("unroll") for (int _i = 0; _i < 2; ++_i) \
;         __builtin_amdgcn_global_load_lds((const unsigned*)((const char*)(gbase) + (voff)[_i]), (PG8_LAS unsigned*)(lds + (bufoff) + ldsw + _i * 8192), 16, 0, 0); } while (0)
; #define PG8_LDA(dst, b, h) do { _Pragma("unroll") for (int m = 0; m < 4; ++m) _Pragma("unroll") for (int k = 0; k < 2; ++k) dst[m][k] = *(const PG8_LAS bf16x8*)(lds + PG8_SA(b, h) + aoff + m * 2048 + k * 1024); } while (0)
; #define PG8_MMA(ai, bj, At, Bt) do { __builtin_amdgcn_s_setprio(1); _Pragma("unroll") for (int m = 0; m < 4; ++m) _Pragma("unroll") for (int n = 0; n < 2; ++n) _Pragma("unroll") for (int k = 0; k < 2; ++k) \
;         acc[ai][bj][m][n] = __builtin_amdgcn_mfma_f32_16x16x32_bf16(Bt[n][k], At[m][k], acc[ai][bj][m][n], 0, 0, 0); __builtin_amdgcn_s_setprio(0); } while (0)
; #define PG8_WAIT_V(n) asm volatile("s_waitcnt vmcnt(" #n ")" ::: "memory")
; #define PG8_WAIT_L(n) asm volatile("s_waitcnt lgkmcnt(" #n ")" ::: "memory")
; #define PG8_BAR __builtin_amdgcn_s_barrier()
; #define PG8_SCHED __builtin_amdgcn_sched_barrier(0)
; template <class Epi, class Sched, bool ALIGN_EPI = false, bool SP2 = false, bool AGM = false  >
; __device__ __forceinline__ void gemm_phase(PG8_LAS unsigned char* lds, const Gemm g, const Sched& S, const Epi& E) {
;     ...
;             PG8_LDA(At, 1, 1); PG8_STAGE(PG8_SB(1, 0), b3, voffB); PG8_STAGE(PG8_SB(1, 1), b3 + hstep, voffB); PG8_STAGE(PG8_SA(1, 0), a3, voffA);
;             PG8_WAIT_V(8); PG8_WAIT_L(0); PG8_BAR; PG8_MMA(1, 0, At, B0); PG8_MMA(1, 1, At, B1); PG8_BAR; PG8_SCHED;
	s_add_i32 s24, s71, s37
	v_lshl_add_u64 v[224:225], v[224:225], 0, s[12:13]
	s_mov_b32 m0, s24
	ds_read_b128 v[192:195], v159 offset:49152
	ds_read_b128 v[196:199], v159 offset:50176
	ds_read_b128 v[200:203], v159 offset:51200
	ds_read_b128 v[204:207], v159 offset:52224
	ds_read_b128 v[208:211], v159 offset:53248
	ds_read_b128 v[212:215], v159 offset:54272
	ds_read_b128 v[216:219], v159 offset:55296
	ds_read_b128 v[220:223], v159 offset:56320
	global_load_lds_dwordx4 v[224:225], off
	s_add_i32 m0, s24, 0x2000
	s_add_u32 s24, s30, 0x20080
	v_lshl_add_u64 v[224:225], v[226:227], 0, s[12:13]
	s_addc_u32 s25, s31, 0
	s_add_i32 s30, s72, s37
	global_load_lds_dwordx4 v[224:225], off
	v_lshl_add_u64 v[224:225], s[24:25], 0, v[134:135]
	s_mov_b32 m0, s30
	s_nop 0
	global_load_lds_dwordx4 v[224:225], off
	v_lshl_add_u64 v[224:225], s[24:25], 0, v[130:131]
	s_add_i32 m0, s30, 0x2000
	s_nop 0
	global_load_lds_dwordx4 v[224:225], off
	s_waitcnt vmcnt(6)
	s_waitcnt lgkmcnt(0)
	s_barrier
	s_setprio 1
	s_waitcnt lgkmcnt(0)
	v_mfma_f32_16x16x32_bf16 v[62:65], v[150:153], v[192:195], v[62:65]
	v_mfma_f32_16x16x32_bf16 v[58:61], v[168:171], v[192:195], v[58:61]
	v_mfma_f32_16x16x32_bf16 v[46:49], v[150:153], v[200:203], v[46:49]
	v_mfma_f32_16x16x32_bf16 v[42:45], v[168:171], v[200:203], v[42:45]
	v_mfma_f32_16x16x32_bf16 v[30:33], v[150:153], v[208:211], v[30:33]
	v_mfma_f32_16x16x32_bf16 v[26:29], v[168:171], v[208:211], v[26:29]
	v_mfma_f32_16x16x32_bf16 v[14:17], v[150:153], v[216:219], v[14:17]
	v_mfma_f32_16x16x32_bf16 v[10:13], v[168:171], v[216:219], v[10:13]
	v_mfma_f32_16x16x32_bf16 v[62:65], v[164:167], v[196:199], v[62:65]
	v_mfma_f32_16x16x32_bf16 v[58:61], v[172:175], v[196:199], v[58:61]
	v_lshl_add_u64 v[224:225], s[28:29], 0, v[136:137]
	s_mov_b32 m0, s44
	s_nop 0
	global_load_lds_dwordx4 v[224:225], off
	v_mfma_f32_16x16x32_bf16 v[46:49], v[164:167], v[204:207], v[46:49]
	v_mfma_f32_16x16x32_bf16 v[42:45], v[172:175], v[204:207], v[42:45]
	v_mfma_f32_16x16x32_bf16 v[30:33], v[164:167], v[212:215], v[30:33]
	v_mfma_f32_16x16x32_bf16 v[26:29], v[172:175], v[212:215], v[26:29]
	v_mfma_f32_16x16x32_bf16 v[14:17], v[164:167], v[220:223], v[14:17]
	v_mfma_f32_16x16x32_bf16 v[10:13], v[172:175], v[220:223], v[10:13]
	s_setprio 0
	s_setprio 1
	v_mfma_f32_16x16x32_bf16 v[54:57], v[176:179], v[192:195], v[54:57]
	v_mfma_f32_16x16x32_bf16 v[50:53], v[184:187], v[192:195], v[50:53]
	v_mfma_f32_16x16x32_bf16 v[38:41], v[176:179], v[200:203], v[38:41]
	v_mfma_f32_16x16x32_bf16 v[34:37], v[184:187], v[200:203], v[34:37]
	v_mfma_f32_16x16x32_bf16 v[22:25], v[176:179], v[208:211], v[22:25]
	v_mfma_f32_16x16x32_bf16 v[18:21], v[184:187], v[208:211], v[18:21]
	v_mfma_f32_16x16x32_bf16 v[6:9], v[176:179], v[216:219], v[6:9]
	v_mfma_f32_16x16x32_bf16 v[2:5], v[184:187], v[216:219], v[2:5]
	v_mfma_f32_16x16x32_bf16 v[54:57], v[180:183], v[196:199], v[54:57]
	v_mfma_f32_16x16x32_bf16 v[50:53], v[188:191], v[196:199], v[50:53]
	v_lshl_add_u64 v[224:225], s[28:29], 0, v[132:133]
	s_mov_b32 m0, s45
	s_nop 0
	global_load_lds_dwordx4 v[224:225], off
	v_mfma_f32_16x16x32_bf16 v[38:41], v[180:183], v[204:207], v[38:41]
	v_mfma_f32_16x16x32_bf16 v[34:37], v[188:191], v[204:207], v[34:37]
	v_mfma_f32_16x16x32_bf16 v[22:25], v[180:183], v[212:215], v[22:25]
	v_mfma_f32_16x16x32_bf16 v[18:21], v[188:191], v[212:215], v[18:21]
	v_mfma_f32_16x16x32_bf16 v[6:9], v[180:183], v[220:223], v[6:9]
	v_mfma_f32_16x16x32_bf16 v[2:5], v[188:191], v[220:223], v[2:5]
	s_setprio 0
	s_barrier
	s_add_i32 s70, s70, 2
	s_add_u32 s68, s68, 0x100
	s_addc_u32 s69, s69, 0
	s_cmp_gt_u32 s70, 5
	s_mov_b64 s[24:25], s[26:27]
	s_cbranch_scc0 .LBB0_677
	s_and_b64 vcc, exec, s[14:15]
	s_cbranch_vccz .LBB0_680
	s_barrier

; #define PG8_STAGE(bufoff, gbase, voff) do { _Pragma("unroll") for (int _i = 0; _i < 2; ++_i) \
;         __builtin_amdgcn_global_load_lds((const unsigned*)((const char*)(gbase) + (voff)[_i]), (PG8_LAS unsigned*)(lds + (bufoff) + ldsw + _i * 8192), 16, 0, 0); } while (0)
; #define PG8_LDA(dst, b, h) do { _Pragma("unroll") for (int m = 0; m < 4; ++m) _Pragma("unroll") for (int k = 0; k < 2; ++k) dst[m][k] = *(const PG8_LAS bf16x8*)(lds + PG8_SA(b, h) + aoff + m * 2048 + k * 1024); } while (0)
; #define PG8_LDB(dst, b, h) do { _Pragma("unroll") for (int n = 0; n < 2; ++n) _Pragma("unroll") for (int k = 0; k < 2; ++k) dst[n][k] = *(const PG8_LAS bf16x8*)(lds + PG8_SB(b, h) + boff + n * 2048 + k * 1024); } while (0)
; #define PG8_MMA(ai, bj, At, Bt) do { __builtin_amdgcn_s_setprio(1); _Pragma("unroll") for (int m = 0; m < 4; ++m) _Pragma("unroll") for (int n = 0; n < 2; ++n) _Pragma("unroll") for (int k = 0; k < 2; ++k) \
;         acc[ai][bj][m][n] = __builtin_amdgcn_mfma_f32_16x16x32_bf16(Bt[n][k], At[m][k], acc[ai][bj][m][n], 0, 0, 0); __builtin_amdgcn_s_setprio(0); } while (0)
; #define PG8_WAIT_V(n) asm volatile("s_waitcnt vmcnt(" #n ")" ::: "memory")
; #define PG8_WAIT_L(n) asm volatile("s_waitcnt lgkmcnt(" #n ")" ::: "memory")
; template <class Epi, class Sched, bool ALIGN_EPI = false, bool SP2 = false, bool AGM = false  >
; __device__ __forceinline__ void gemm_phase(PG8_LAS unsigned char* lds, const Gemm g, const Sched& S, const Epi& E) {
;     ...
;             const bool last = (t == nt - 2);
;             const char* a1 = cA + (size_t)(t + 1) * kstepA;
;             const char* a2 = last ? nA : cA + (size_t)(t + 2) * kstepA; const char* b2 = last ? nB : cB + (size_t)(t + 2) * kstep;
;             const char* a3 = a2 + kstepA; const char* b3 = b2 + kstep;
;             if (last && has_next) S.a_ready(nxt);
;             if constexpr (SP2) {
;             PG8_LDB(B0, 0, 0); PG8_LDB(B1, 0, 1); PG8_SCHED; PG8_LDA(At, 0, 0); PG8_STAGE(PG8_SA(1, 1), a1 + hstepA, voffA);
;             PG8_WAIT_V(8); PG8_WAIT_L(0); PG8_BAR; PG8_MMA(0, 0, At, B0); PG8_MMA(0, 1, At, B1); PG8_BAR; PG8_SCHED;
;             PG8_LDA(At, 0, 1); PG8_STAGE(PG8_SB(0, 0), b2, voffB); PG8_STAGE(PG8_SB(0, 1), b2 + hstep, voffB); PG8_STAGE(PG8_SA(0, 0), a2, voffA);
;             PG8_WAIT_V(8); PG8_WAIT_L(0); PG8_BAR; PG8_MMA(1, 0, At, B0); PG8_MMA(1, 1, At, B1); PG8_BAR; PG8_SCHED;
.LBB0_783:
	ds_read_b128 v[130:133], v186
	ds_read_b128 v[134:137], v186 offset:1024
	ds_read_b128 v[138:141], v186 offset:2048
	ds_read_b128 v[142:145], v186 offset:3072
	ds_read_b128 v[146:149], v187
	ds_read_b128 v[150:153], v187 offset:1024
	ds_read_b128 v[178:181], v187 offset:2048
	ds_read_b128 v[194:197], v187 offset:3072
	s_add_u32 s40, s38, 0xfffc0080
	s_addc_u32 s41, s39, -1
	s_cmp_eq_u32 s75, 12
	s_cselect_b32 s43, s5, s41
	s_cselect_b32 s42, s31, s40
	s_cselect_b32 s41, s29, s74
	s_cselect_b32 s40, s33, s62
	v_lshl_add_u64 v[182:183], s[38:39], 0, v[170:171]
	s_add_i32 m0, s44, 0xc000
	ds_read_b128 v[198:201], v188
	ds_read_b128 v[202:205], v188 offset:1024
	ds_read_b128 v[206:209], v188 offset:2048
	ds_read_b128 v[210:213], v188 offset:3072
	ds_read_b128 v[214:217], v188 offset:4096
	ds_read_b128 v[218:221], v188 offset:5120
	ds_read_b128 v[222:225], v188 offset:6144
	ds_read_b128 v[226:229], v188 offset:7168
	global_load_lds_dwordx4 v[182:183], off
	v_lshl_add_u64 v[182:183], s[38:39], 0, v[172:173]
	s_add_i32 m0, s44, 0xe000
	s_nop 0
	global_load_lds_dwordx4 v[182:183], off
	s_waitcnt vmcnt(8)
	s_waitcnt lgkmcnt(0)
	s_barrier
	s_setprio 1
	s_waitcnt lgkmcnt(0)
	v_mfma_f32_16x16x32_bf16 v[126:129], v[130:133], v[198:201], v[126:129]
	v_mfma_f32_16x16x32_bf16 v[122:125], v[138:141], v[198:201], v[122:125]
	v_mfma_f32_16x16x32_bf16 v[110:113], v[130:133], v[206:209], v[110:113]
	v_mfma_f32_16x16x32_bf16 v[106:109], v[138:141], v[206:209], v[106:109]
	v_mfma_f32_16x16x32_bf16 v[94:97], v[130:133], v[214:217], v[94:97]
	v_mfma_f32_16x16x32_bf16 v[90:93], v[138:141], v[214:217], v[90:93]
	v_mfma_f32_16x16x32_bf16 v[78:81], v[130:133], v[222:225], v[78:81]
	v_mfma_f32_16x16x32_bf16 v[74:77], v[138:141], v[222:225], v[74:77]
	v_mfma_f32_16x16x32_bf16 v[126:129], v[134:137], v[202:205], v[126:129]
	v_mfma_f32_16x16x32_bf16 v[122:125], v[142:145], v[202:205], v[122:125]
	v_mfma_f32_16x16x32_bf16 v[110:113], v[134:137], v[210:213], v[110:113]
	v_mfma_f32_16x16x32_bf16 v[106:109], v[142:145], v[210:213], v[106:109]
	v_mfma_f32_16x16x32_bf16 v[94:97], v[134:137], v[218:221], v[94:97]
	v_mfma_f32_16x16x32_bf16 v[90:93], v[142:145], v[218:221], v[90:93]
	v_mfma_f32_16x16x32_bf16 v[78:81], v[134:137], v[226:229], v[78:81]
	v_mfma_f32_16x16x32_bf16 v[74:77], v[142:145], v[226:229], v[74:77]
	s_setprio 0
	s_setprio 1
	v_mfma_f32_16x16x32_bf16 v[118:121], v[146:149], v[198:201], v[118:121]
	v_mfma_f32_16x16x32_bf16 v[114:117], v[178:181], v[198:201], v[114:117]
	v_mfma_f32_16x16x32_bf16 v[102:105], v[146:149], v[206:209], v[102:105]
	v_mfma_f32_16x16x32_bf16 v[98:101], v[178:181], v[206:209], v[98:101]
	v_mfma_f32_16x16x32_bf16 v[86:89], v[146:149], v[214:217], v[86:89]
	v_mfma_f32_16x16x32_bf16 v[82:85], v[178:181], v[214:217], v[82:85]
	v_mfma_f32_16x16x32_bf16 v[70:73], v[146:149], v[222:225], v[70:73]
	v_mfma_f32_16x16x32_bf16 v[66:69], v[178:181], v[222:225], v[66:69]
	v_mfma_f32_16x16x32_bf16 v[118:121], v[150:153], v[202:205], v[118:121]
	v_mfma_f32_16x16x32_bf16 v[114:117], v[194:197], v[202:205], v[114:117]
	v_mfma_f32_16x16x32_bf16 v[102:105], v[150:153], v[210:213], v[102:105]
	v_mfma_f32_16x16x32_bf16 v[98:101], v[194:197], v[210:213], v[98:101]
	v_mfma_f32_16x16x32_bf16 v[86:89], v[150:153], v[218:221], v[86:89]
	v_mfma_f32_16x16x32_bf16 v[82:85], v[194:197], v[218:221], v[82:85]
	v_mfma_f32_16x16x32_bf16 v[70:73], v[150:153], v[226:229], v[70:73]
	v_mfma_f32_16x16x32_bf16 v[66:69], v[194:197], v[226:229], v[66:69]
	s_setprio 0
	s_barrier
	s_add_i32 s76, s71, s3
	v_lshl_add_u64 v[182:183], s[40:41], 0, v[158:159]
	s_mov_b32 m0, s76
	ds_read_b128 v[198:201], v188 offset:16384
	ds_read_b128 v[202:205], v188 offset:17408
	ds_read_b128 v[206:209], v188 offset:18432
	ds_read_b128 v[210:213], v188 offset:19456
	ds_read_b128 v[214:217], v188 offset:20480
	ds_read_b128 v[218:221], v188 offset:21504
	ds_read_b128 v[222:225], v188 offset:22528
	ds_read_b128 v[226:229], v188 offset:23552
	global_load_lds_dwordx4 v[182:183], off
	s_add_i32 m0, s76, 0x2000
	s_add_u32 s76, s40, 0x40000
	v_lshl_add_u64 v[230:231], s[40:41], 0, v[162:163]
	s_addc_u32 s77, s41, 0
	s_add_i32 s78, s72, s3
	global_load_lds_dwordx4 v[230:231], off
	v_lshl_add_u64 v[232:233], s[76:77], 0, v[158:159]
	s_mov_b32 m0, s78
	v_lshl_add_u64 v[234:235], s[42:43], 0, v[160:161]
	global_load_lds_dwordx4 v[232:233], off
	v_lshl_add_u64 v[232:233], s[76:77], 0, v[162:163]
	s_add_i32 m0, s78, 0x2000
	s_nop 0
	global_load_lds_dwordx4 v[232:233], off
	s_waitcnt vmcnt(6)
	s_waitcnt lgkmcnt(0)
	s_barrier
; #define PG8_STAGE(bufoff, gbase, voff) do { _Pragma("unroll") for (int _i = 0; _i < 2; ++_i) \
;         __builtin_amdgcn_global_load_lds((const unsigned*)((const char*)(gbase) + (voff)[_i]), (PG8_LAS unsigned*)(lds + (bufoff) + ldsw + _i * 8192), 16, 0, 0); } while (0)
; #define PG8_LDA(dst, b, h) do { _Pragma("unroll") for (int m = 0; m < 4; ++m) _Pragma("unroll") for (int k = 0; k < 2; ++k) dst[m][k] = *(const PG8_LAS bf16x8*)(lds + PG8_SA(b, h) + aoff + m * 2048 + k * 1024); } while (0)
; #define PG8_LDB(dst, b, h) do { _Pragma("unroll") for (int n = 0; n < 2; ++n) _Pragma("unroll") for (int k = 0; k < 2; ++k) dst[n][k] = *(const PG8_LAS bf16x8*)(lds + PG8_SB(b, h) + boff + n * 2048 + k * 1024); } while (0)
; #define PG8_MMA(ai, bj, At, Bt) do { __builtin_amdgcn_s_setprio(1); _Pragma("unroll") for (int m = 0; m < 4; ++m) _Pragma("unroll") for (int n = 0; n < 2; ++n) _Pragma("unroll") for (int k = 0; k < 2; ++k) \
;         acc[ai][bj][m][n] = __builtin_amdgcn_mfma_f32_16x16x32_bf16(Bt[n][k], At[m][k], acc[ai][bj][m][n], 0, 0, 0); __builtin_amdgcn_s_setprio(0); } while (0)
; #define PG8_WAIT_V(n) asm volatile("s_waitcnt vmcnt(" #n ")" ::: "memory")
; #define PG8_WAIT_L(n) asm volatile("s_waitcnt lgkmcnt(" #n ")" ::: "memory")
; #define PG8_BAR __builtin_amdgcn_s_barrier()
; #define PG8_SCHED __builtin_amdgcn_sched_barrier(0)
; template <class Epi, class Sched, bool ALIGN_EPI = false, bool SP2 = false, bool AGM = false  >
; __device__ __forceinline__ void gemm_phase(PG8_LAS unsigned char* lds, const Gemm g, const Sched& S, const Epi& E) {
;     ...
;             PG8_LDA(At, 0, 1); PG8_STAGE(PG8_SB(0, 0), b2, voffB); PG8_STAGE(PG8_SB(0, 1), b2 + hstep, voffB); PG8_STAGE(PG8_SA(0, 0), a2, voffA);
;             PG8_WAIT_V(8); PG8_WAIT_L(0); PG8_BAR; PG8_MMA(1, 0, At, B0); PG8_MMA(1, 1, At, B1); PG8_BAR; PG8_SCHED;
;             PG8_LDB(B0, 1, 0); PG8_LDB(B1, 1, 1); PG8_SCHED; PG8_LDA(At, 1, 0); PG8_STAGE(PG8_SA(0, 1), a2 + hstepA, voffA);
;             PG8_WAIT_V(8); PG8_WAIT_L(0); PG8_BAR; PG8_MMA(0, 0, At, B0); PG8_MMA(0, 1, At, B1); PG8_BAR; PG8_SCHED;
	s_setprio 1
	s_waitcnt lgkmcnt(0)
	v_mfma_f32_16x16x32_bf16 v[62:65], v[130:133], v[198:201], v[62:65]
	v_mfma_f32_16x16x32_bf16 v[58:61], v[138:141], v[198:201], v[58:61]
	v_mfma_f32_16x16x32_bf16 v[46:49], v[130:133], v[206:209], v[46:49]
	v_mfma_f32_16x16x32_bf16 v[42:45], v[138:141], v[206:209], v[42:45]
	v_mfma_f32_16x16x32_bf16 v[30:33], v[130:133], v[214:217], v[30:33]
	v_mfma_f32_16x16x32_bf16 v[26:29], v[138:141], v[214:217], v[26:29]
	v_mfma_f32_16x16x32_bf16 v[14:17], v[130:133], v[222:225], v[14:17]
	v_mfma_f32_16x16x32_bf16 v[10:13], v[138:141], v[222:225], v[10:13]
	v_mfma_f32_16x16x32_bf16 v[62:65], v[134:137], v[202:205], v[62:65]
	v_mfma_f32_16x16x32_bf16 v[58:61], v[142:145], v[202:205], v[58:61]
	v_lshl_add_u64 v[232:233], s[42:43], 0, v[156:157]
	s_mov_b32 m0, s44
	s_nop 0
	global_load_lds_dwordx4 v[232:233], off
	v_mfma_f32_16x16x32_bf16 v[46:49], v[134:137], v[210:213], v[46:49]
	v_mfma_f32_16x16x32_bf16 v[42:45], v[142:145], v[210:213], v[42:45]
	v_mfma_f32_16x16x32_bf16 v[30:33], v[134:137], v[218:221], v[30:33]
	v_mfma_f32_16x16x32_bf16 v[26:29], v[142:145], v[218:221], v[26:29]
	v_mfma_f32_16x16x32_bf16 v[14:17], v[134:137], v[226:229], v[14:17]
	v_mfma_f32_16x16x32_bf16 v[10:13], v[142:145], v[226:229], v[10:13]
	s_setprio 0
	s_setprio 1
	v_mfma_f32_16x16x32_bf16 v[54:57], v[146:149], v[198:201], v[54:57]
	v_mfma_f32_16x16x32_bf16 v[50:53], v[178:181], v[198:201], v[50:53]
	v_mfma_f32_16x16x32_bf16 v[38:41], v[146:149], v[206:209], v[38:41]
	v_mfma_f32_16x16x32_bf16 v[34:37], v[178:181], v[206:209], v[34:37]
	v_mfma_f32_16x16x32_bf16 v[22:25], v[146:149], v[214:217], v[22:25]
	v_mfma_f32_16x16x32_bf16 v[18:21], v[178:181], v[214:217], v[18:21]
	v_mfma_f32_16x16x32_bf16 v[6:9], v[146:149], v[222:225], v[6:9]
	v_mfma_f32_16x16x32_bf16 v[2:5], v[178:181], v[222:225], v[2:5]
	v_mfma_f32_16x16x32_bf16 v[54:57], v[150:153], v[202:205], v[54:57]
	v_mfma_f32_16x16x32_bf16 v[50:53], v[194:197], v[202:205], v[50:53]
	s_mov_b32 m0, s45
	s_nop 0
	global_load_lds_dwordx4 v[234:235], off
	v_mfma_f32_16x16x32_bf16 v[38:41], v[150:153], v[210:213], v[38:41]
	v_mfma_f32_16x16x32_bf16 v[34:37], v[194:197], v[210:213], v[34:37]
	v_mfma_f32_16x16x32_bf16 v[22:25], v[150:153], v[218:221], v[22:25]
	v_mfma_f32_16x16x32_bf16 v[18:21], v[194:197], v[218:221], v[18:21]
	v_mfma_f32_16x16x32_bf16 v[6:9], v[150:153], v[226:229], v[6:9]
	v_mfma_f32_16x16x32_bf16 v[2:5], v[194:197], v[226:229], v[2:5]
	s_setprio 0
	s_barrier
	s_add_i32 s76, 0, 0x18000
	s_add_i32 s77, 0, 0x1c000
	v_add_u32_e32 v142, s76, v184
	v_add_u32_e32 v164, s77, v184
	ds_read_b128 v[130:133], v142
	ds_read_b128 v[134:137], v142 offset:1024
	ds_read_b128 v[138:141], v142 offset:2048
	ds_read_b128 v[142:145], v142 offset:3072
	ds_read_b128 v[146:149], v164
	ds_read_b128 v[150:153], v164 offset:1024
	ds_read_b128 v[178:181], v164 offset:2048
	ds_read_b128 v[194:197], v164 offset:3072
	s_add_u32 s42, s42, 0x40000
	s_addc_u32 s43, s43, 0
	s_mov_b32 m0, s53
	v_lshl_add_u64 v[236:237], s[42:43], 0, v[156:157]
	ds_read_b128 v[198:201], v188 offset:32768
	ds_read_b128 v[202:205], v188 offset:33792
	ds_read_b128 v[206:209], v188 offset:34816
	ds_read_b128 v[210:213], v188 offset:35840
	ds_read_b128 v[214:217], v188 offset:36864
	ds_read_b128 v[218:221], v188 offset:37888
	ds_read_b128 v[222:225], v188 offset:38912
	ds_read_b128 v[226:229], v188 offset:39936
	global_load_lds_dwordx4 v[236:237], off
	v_lshl_add_u64 v[236:237], s[42:43], 0, v[160:161]
	s_mov_b32 m0, s54
	s_nop 0
	global_load_lds_dwordx4 v[236:237], off
	s_waitcnt vmcnt(8)
	s_waitcnt lgkmcnt(0)
	s_barrier
	s_setprio 1
	s_waitcnt lgkmcnt(0)
	v_mfma_f32_16x16x32_bf16 v[126:129], v[130:133], v[198:201], v[126:129]
	v_mfma_f32_16x16x32_bf16 v[122:125], v[138:141], v[198:201], v[122:125]
	v_mfma_f32_16x16x32_bf16 v[110:113], v[130:133], v[206:209], v[110:113]
	v_mfma_f32_16x16x32_bf16 v[106:109], v[138:141], v[206:209], v[106:109]
	v_mfma_f32_16x16x32_bf16 v[94:97], v[130:133], v[214:217], v[94:97]
	v_mfma_f32_16x16x32_bf16 v[90:93], v[138:141], v[214:217], v[90:93]
	v_mfma_f32_16x16x32_bf16 v[78:81], v[130:133], v[222:225], v[78:81]
	v_mfma_f32_16x16x32_bf16 v[74:77], v[138:141], v[222:225], v[74:77]
	v_mfma_f32_16x16x32_bf16 v[126:129], v[134:137], v[202:205], v[126:129]
	v_mfma_f32_16x16x32_bf16 v[122:125], v[142:145], v[202:205], v[122:125]
	v_mfma_f32_16x16x32_bf16 v[110:113], v[134:137], v[210:213], v[110:113]
	v_mfma_f32_16x16x32_bf16 v[106:109], v[142:145], v[210:213], v[106:109]
	v_mfma_f32_16x16x32_bf16 v[94:97], v[134:137], v[218:221], v[94:97]
	v_mfma_f32_16x16x32_bf16 v[90:93], v[142:145], v[218:221], v[90:93]
	v_mfma_f32_16x16x32_bf16 v[78:81], v[134:137], v[226:229], v[78:81]
	v_mfma_f32_16x16x32_bf16 v[74:77], v[142:145], v[226:229], v[74:77]
	s_setprio 0
	s_setprio 1
	v_mfma_f32_16x16x32_bf16 v[118:121], v[146:149], v[198:201], v[118:121]
	v_mfma_f32_16x16x32_bf16 v[114:117], v[178:181], v[198:201], v[114:117]
	v_mfma_f32_16x16x32_bf16 v[102:105], v[146:149], v[206:209], v[102:105]
	v_mfma_f32_16x16x32_bf16 v[98:101], v[178:181], v[206:209], v[98:101]
	v_mfma_f32_16x16x32_bf16 v[86:89], v[146:149], v[214:217], v[86:89]
	v_mfma_f32_16x16x32_bf16 v[82:85], v[178:181], v[214:217], v[82:85]
	v_mfma_f32_16x16x32_bf16 v[70:73], v[146:149], v[222:225], v[70:73]
	v_mfma_f32_16x16x32_bf16 v[66:69], v[178:181], v[222:225], v[66:69]
	v_mfma_f32_16x16x32_bf16 v[118:121], v[150:153], v[202:205], v[118:121]
	v_mfma_f32_16x16x32_bf16 v[114:117], v[194:197], v[202:205], v[114:117]
	v_mfma_f32_16x16x32_bf16 v[102:105], v[150:153], v[210:213], v[102:105]
	v_mfma_f32_16x16x32_bf16 v[98:101], v[194:197], v[210:213], v[98:101]
	v_mfma_f32_16x16x32_bf16 v[86:89], v[150:153], v[218:221], v[86:89]
	v_mfma_f32_16x16x32_bf16 v[82:85], v[194:197], v[218:221], v[82:85]
	v_mfma_f32_16x16x32_bf16 v[70:73], v[150:153], v[226:229], v[70:73]
	v_mfma_f32_16x16x32_bf16 v[66:69], v[194:197], v[226:229], v[66:69]
	s_setprio 0
	s_barrier
; #define PG8_STAGE(bufoff, gbase, voff) do { _Pragma("unroll") for (int _i = 0; _i < 2; ++_i) \
;         __builtin_amdgcn_global_load_lds((const unsigned*)((const char*)(gbase) + (voff)[_i]), (PG8_LAS unsigned*)(lds + (bufoff) + ldsw + _i * 8192), 16, 0, 0); } while (0)
; #define PG8_LDA(dst, b, h) do { _Pragma("unroll") for (int m = 0; m < 4; ++m) _Pragma("unroll") for (int k = 0; k < 2; ++k) dst[m][k] = *(const PG8_LAS bf16x8*)(lds + PG8_SA(b, h) + aoff + m * 2048 + k * 1024); } while (0)
; #define PG8_MMA(ai, bj, At, Bt) do { __builtin_amdgcn_s_setprio(1); _Pragma("unroll") for (int m = 0; m < 4; ++m) _Pragma("unroll") for (int n = 0; n < 2; ++n) _Pragma("unroll") for (int k = 0; k < 2; ++k) \
;         acc[ai][bj][m][n] = __builtin_amdgcn_mfma_f32_16x16x32_bf16(Bt[n][k], At[m][k], acc[ai][bj][m][n], 0, 0, 0); __builtin_amdgcn_s_setprio(0); } while (0)
; #define PG8_WAIT_V(n) asm volatile("s_waitcnt vmcnt(" #n ")" ::: "memory")
; #define PG8_WAIT_L(n) asm volatile("s_waitcnt lgkmcnt(" #n ")" ::: "memory")
; #define PG8_BAR __builtin_amdgcn_s_barrier()
; #define PG8_SCHED __builtin_amdgcn_sched_barrier(0)
; template <class Epi, class Sched, bool ALIGN_EPI = false, bool SP2 = false, bool AGM = false  >
; __device__ __forceinline__ void gemm_phase(PG8_LAS unsigned char* lds, const Gemm g, const Sched& S, const Epi& E) {
;     ...
;             PG8_LDA(At, 1, 1); PG8_STAGE(PG8_SB(1, 0), b3, voffB); PG8_STAGE(PG8_SB(1, 1), b3 + hstep, voffB); PG8_STAGE(PG8_SA(1, 0), a3, voffA);
;             PG8_WAIT_V(8); PG8_WAIT_L(0); PG8_BAR; PG8_MMA(1, 0, At, B0); PG8_MMA(1, 1, At, B1); PG8_BAR; PG8_SCHED;
	s_add_i32 s42, s76, s3
	v_lshl_add_u64 v[182:183], v[182:183], 0, s[24:25]
	s_mov_b32 m0, s42
	ds_read_b128 v[198:201], v188 offset:49152
	ds_read_b128 v[202:205], v188 offset:50176
	ds_read_b128 v[206:209], v188 offset:51200
	ds_read_b128 v[210:213], v188 offset:52224
	ds_read_b128 v[214:217], v188 offset:53248
	ds_read_b128 v[218:221], v188 offset:54272
	ds_read_b128 v[222:225], v188 offset:55296
	ds_read_b128 v[226:229], v188 offset:56320
	global_load_lds_dwordx4 v[182:183], off
	s_add_i32 m0, s42, 0x2000
	s_add_u32 s40, s40, 0x40080
	v_lshl_add_u64 v[182:183], v[230:231], 0, s[24:25]
	s_addc_u32 s41, s41, 0
	s_add_i32 s42, s77, s3
	global_load_lds_dwordx4 v[182:183], off
	v_lshl_add_u64 v[182:183], s[40:41], 0, v[158:159]
	s_mov_b32 m0, s42
	s_nop 0
	global_load_lds_dwordx4 v[182:183], off
	v_lshl_add_u64 v[182:183], s[40:41], 0, v[162:163]
	s_add_i32 m0, s42, 0x2000
	s_nop 0
	global_load_lds_dwordx4 v[182:183], off
	s_waitcnt vmcnt(6)
	s_waitcnt lgkmcnt(0)
	s_barrier
	s_setprio 1
	s_waitcnt lgkmcnt(0)
	v_mfma_f32_16x16x32_bf16 v[62:65], v[130:133], v[198:201], v[62:65]
	v_mfma_f32_16x16x32_bf16 v[58:61], v[138:141], v[198:201], v[58:61]
	v_mfma_f32_16x16x32_bf16 v[46:49], v[130:133], v[206:209], v[46:49]
	v_mfma_f32_16x16x32_bf16 v[42:45], v[138:141], v[206:209], v[42:45]
	v_mfma_f32_16x16x32_bf16 v[30:33], v[130:133], v[214:217], v[30:33]
	v_mfma_f32_16x16x32_bf16 v[26:29], v[138:141], v[214:217], v[26:29]
	v_mfma_f32_16x16x32_bf16 v[14:17], v[130:133], v[222:225], v[14:17]
	v_mfma_f32_16x16x32_bf16 v[10:13], v[138:141], v[222:225], v[10:13]
	v_mfma_f32_16x16x32_bf16 v[62:65], v[134:137], v[202:205], v[62:65]
	v_mfma_f32_16x16x32_bf16 v[58:61], v[142:145], v[202:205], v[58:61]
	v_lshl_add_u64 v[182:183], v[232:233], 0, s[24:25]
	s_mov_b32 m0, s60
	s_nop 0
	global_load_lds_dwordx4 v[182:183], off
	v_mfma_f32_16x16x32_bf16 v[46:49], v[134:137], v[210:213], v[46:49]
	v_mfma_f32_16x16x32_bf16 v[42:45], v[142:145], v[210:213], v[42:45]
	v_mfma_f32_16x16x32_bf16 v[30:33], v[134:137], v[218:221], v[30:33]
	v_mfma_f32_16x16x32_bf16 v[26:29], v[142:145], v[218:221], v[26:29]
	v_mfma_f32_16x16x32_bf16 v[14:17], v[134:137], v[226:229], v[14:17]
	v_mfma_f32_16x16x32_bf16 v[10:13], v[142:145], v[226:229], v[10:13]
	s_setprio 0
	s_setprio 1
	v_mfma_f32_16x16x32_bf16 v[54:57], v[146:149], v[198:201], v[54:57]
	v_mfma_f32_16x16x32_bf16 v[50:53], v[178:181], v[198:201], v[50:53]
	v_mfma_f32_16x16x32_bf16 v[38:41], v[146:149], v[206:209], v[38:41]
	v_mfma_f32_16x16x32_bf16 v[34:37], v[178:181], v[206:209], v[34:37]
	v_mfma_f32_16x16x32_bf16 v[22:25], v[146:149], v[214:217], v[22:25]
	v_mfma_f32_16x16x32_bf16 v[18:21], v[178:181], v[214:217], v[18:21]
	v_mfma_f32_16x16x32_bf16 v[6:9], v[146:149], v[222:225], v[6:9]
	v_mfma_f32_16x16x32_bf16 v[2:5], v[178:181], v[222:225], v[2:5]
	v_mfma_f32_16x16x32_bf16 v[54:57], v[150:153], v[202:205], v[54:57]
	v_mfma_f32_16x16x32_bf16 v[50:53], v[194:197], v[202:205], v[50:53]
	v_lshl_add_u64 v[182:183], v[234:235], 0, s[24:25]
	s_mov_b32 m0, s61
	s_nop 0
	global_load_lds_dwordx4 v[182:183], off
	v_mfma_f32_16x16x32_bf16 v[38:41], v[150:153], v[210:213], v[38:41]
	v_mfma_f32_16x16x32_bf16 v[34:37], v[194:197], v[210:213], v[34:37]
	v_mfma_f32_16x16x32_bf16 v[22:25], v[150:153], v[218:221], v[22:25]
	v_mfma_f32_16x16x32_bf16 v[18:21], v[194:197], v[218:221], v[18:21]
	v_mfma_f32_16x16x32_bf16 v[6:9], v[150:153], v[226:229], v[6:9]
	v_mfma_f32_16x16x32_bf16 v[2:5], v[194:197], v[226:229], v[2:5]
	s_setprio 0
	s_barrier
	s_add_i32 s75, s75, 2
	s_add_u32 s38, s38, 0x100
	s_addc_u32 s39, s39, 0
	s_add_u32 s62, s62, 0x100
	s_addc_u32 s74, s74, 0
	s_cmp_gt_u32 s75, 13
	s_cbranch_scc0 .LBB0_783
	s_and_b64 vcc, exec, s[26:27]
	s_cbranch_vccz .LBB0_786
	s_barrier

; #define PG8_STAGE(bufoff, gbase, voff) do { _Pragma("unroll") for (int _i = 0; _i < 2; ++_i) \
;         __builtin_amdgcn_global_load_lds((const unsigned*)((const char*)(gbase) + (voff)[_i]), (PG8_LAS unsigned*)(lds + (bufoff) + ldsw + _i * 8192), 16, 0, 0); } while (0)
; #define PG8_LDA(dst, b, h) do { _Pragma("unroll") for (int m = 0; m < 4; ++m) _Pragma("unroll") for (int k = 0; k < 2; ++k) dst[m][k] = *(const PG8_LAS bf16x8*)(lds + PG8_SA(b, h) + aoff + m * 2048 + k * 1024); } while (0)
; #define PG8_LDB(dst, b, h) do { _Pragma("unroll") for (int n = 0; n < 2; ++n) _Pragma("unroll") for (int k = 0; k < 2; ++k) dst[n][k] = *(const PG8_LAS bf16x8*)(lds + PG8_SB(b, h) + boff + n * 2048 + k * 1024); } while (0)
; #define PG8_MMA(ai, bj, At, Bt) do { __builtin_amdgcn_s_setprio(1); _Pragma("unroll") for (int m = 0; m < 4; ++m) _Pragma("unroll") for (int n = 0; n < 2; ++n) _Pragma("unroll") for (int k = 0; k < 2; ++k) \
;         acc[ai][bj][m][n] = __builtin_amdgcn_mfma_f32_16x16x32_bf16(Bt[n][k], At[m][k], acc[ai][bj][m][n], 0, 0, 0); __builtin_amdgcn_s_setprio(0); } while (0)
; template <class Epi, class Sched, bool ALIGN_EPI = false, bool SP2 = false, bool AGM = false  >
; __device__ __forceinline__ void gemm_phase(PG8_LAS unsigned char* lds, const Gemm g, const Sched& S, const Epi& E) {
;     ...
;         const bool has_next = S.next(ui + 1, nxt);
;         const char* nA = has_next ? (const char*)g.A + (size_t)nxt.pm * tstepA : cA; const char* nB = has_next ? (const char*)g.Bt + (size_t)nxt.pn * tstep : cB;
;         for (int t = 0; t < nt; t += 2) {
;             const bool last = (t == nt - 2);
;             const char* a1 = cA + (size_t)(t + 1) * kstepA;
;             const char* a2 = last ? nA : cA + (size_t)(t + 2) * kstepA; const char* b2 = last ? nB : cB + (size_t)(t + 2) * kstep;
;             const char* a3 = a2 + kstepA; const char* b3 = b2 + kstep;
;             if (last && has_next) S.a_ready(nxt);
;             if constexpr (SP2) {
;             PG8_LDB(B0, 0, 0); PG8_LDB(B1, 0, 1); PG8_SCHED; PG8_LDA(At, 0, 0); PG8_STAGE(PG8_SA(1, 1), a1 + hstepA, voffA);
;             PG8_WAIT_V(8); PG8_WAIT_L(0); PG8_BAR; PG8_MMA(0, 0, At, B0); PG8_MMA(0, 1, At, B1); PG8_BAR; PG8_SCHED;
;             PG8_LDA(At, 0, 1); PG8_STAGE(PG8_SB(0, 0), b2, voffB); PG8_STAGE(PG8_SB(0, 1), b2 + hstep, voffB); PG8_STAGE(PG8_SA(0, 0), a2, voffA);
.LBB0_876:
	s_ashr_i32 s23, s22, 31
	s_lshl_b64 s[24:25], s[22:23], 19
	s_add_u32 s24, s46, s24
	s_addc_u32 s25, s47, s25
	s_and_b64 s[26:27], s[0:1], exec
	s_cselect_b32 s23, s25, s29
	s_cselect_b32 s64, s24, s28
	s_ashr_i32 s21, s20, 31
	s_lshl_b64 s[26:27], s[20:21], 19
	s_add_u32 s26, s10, s26
	s_addc_u32 s27, s11, s27
	s_and_b64 s[34:35], s[0:1], exec
	s_cselect_b32 s21, s27, s31
	s_cselect_b32 s65, s26, s30
	s_add_u32 s28, s28, 0x40080
	s_addc_u32 s29, s29, 0
	s_add_u32 s66, s30, 0x100
	s_addc_u32 s67, s31, 0
	s_mov_b32 s68, -2
	s_waitcnt vmcnt(0)
	s_waitcnt lgkmcnt(0)
	ds_read_b128 v[148:151], v156
	ds_read_b128 v[164:167], v156 offset:1024
	ds_read_b128 v[168:171], v156 offset:2048
	ds_read_b128 v[172:175], v156 offset:3072
	ds_read_b128 v[176:179], v157
	ds_read_b128 v[180:183], v157 offset:1024
	ds_read_b128 v[184:187], v157 offset:2048
	ds_read_b128 v[188:191], v157 offset:3072
	s_add_u32 s30, s28, 0xfffc0080
	s_addc_u32 s31, s29, -1
	s_cmp_eq_u32 s68, 12
	s_cselect_b32 s35, s23, s31
	s_cselect_b32 s34, s64, s30
	s_cselect_b32 s31, s21, s67
	s_cselect_b32 s30, s65, s66
	v_lshl_add_u64 v[224:225], s[28:29], 0, v[140:141]
	s_add_i32 m0, s37, 0xc000
	ds_read_b128 v[192:195], v158
	ds_read_b128 v[196:199], v158 offset:1024
	ds_read_b128 v[200:203], v158 offset:2048
	ds_read_b128 v[204:207], v158 offset:3072
	ds_read_b128 v[208:211], v158 offset:4096
	ds_read_b128 v[212:215], v158 offset:5120
	ds_read_b128 v[216:219], v158 offset:6144
	ds_read_b128 v[220:223], v158 offset:7168
	global_load_lds_dwordx4 v[224:225], off
	v_lshl_add_u64 v[224:225], s[28:29], 0, v[142:143]
	s_add_i32 m0, s37, 0xe000
	s_nop 0
	global_load_lds_dwordx4 v[224:225], off
	s_waitcnt vmcnt(8)
	s_waitcnt lgkmcnt(0)
	s_barrier
	s_setprio 1
	s_waitcnt lgkmcnt(0)
	v_mfma_f32_16x16x32_bf16 v[126:129], v[148:151], v[192:195], 0
	v_mfma_f32_16x16x32_bf16 v[122:125], v[168:171], v[192:195], 0
	v_mfma_f32_16x16x32_bf16 v[110:113], v[148:151], v[200:203], 0
	v_mfma_f32_16x16x32_bf16 v[106:109], v[168:171], v[200:203], 0
	v_mfma_f32_16x16x32_bf16 v[94:97], v[148:151], v[208:211], 0
	v_mfma_f32_16x16x32_bf16 v[90:93], v[168:171], v[208:211], 0
	v_mfma_f32_16x16x32_bf16 v[78:81], v[148:151], v[216:219], 0
	v_mfma_f32_16x16x32_bf16 v[74:77], v[168:171], v[216:219], 0
	v_mfma_f32_16x16x32_bf16 v[126:129], v[164:167], v[196:199], v[126:129]
	v_mfma_f32_16x16x32_bf16 v[122:125], v[172:175], v[196:199], v[122:125]
	v_mfma_f32_16x16x32_bf16 v[110:113], v[164:167], v[204:207], v[110:113]
	v_mfma_f32_16x16x32_bf16 v[106:109], v[172:175], v[204:207], v[106:109]
	v_mfma_f32_16x16x32_bf16 v[94:97], v[164:167], v[212:215], v[94:97]
	v_mfma_f32_16x16x32_bf16 v[90:93], v[172:175], v[212:215], v[90:93]
	v_mfma_f32_16x16x32_bf16 v[78:81], v[164:167], v[220:223], v[78:81]
	v_mfma_f32_16x16x32_bf16 v[74:77], v[172:175], v[220:223], v[74:77]
	s_setprio 0
	s_setprio 1
	v_mfma_f32_16x16x32_bf16 v[118:121], v[176:179], v[192:195], 0
	v_mfma_f32_16x16x32_bf16 v[114:117], v[184:187], v[192:195], 0
	v_mfma_f32_16x16x32_bf16 v[102:105], v[176:179], v[200:203], 0
	v_mfma_f32_16x16x32_bf16 v[98:101], v[184:187], v[200:203], 0
	v_mfma_f32_16x16x32_bf16 v[86:89], v[176:179], v[208:211], 0
	v_mfma_f32_16x16x32_bf16 v[82:85], v[184:187], v[208:211], 0
	v_mfma_f32_16x16x32_bf16 v[70:73], v[176:179], v[216:219], 0
	v_mfma_f32_16x16x32_bf16 v[66:69], v[184:187], v[216:219], 0
	v_mfma_f32_16x16x32_bf16 v[118:121], v[180:183], v[196:199], v[118:121]
	v_mfma_f32_16x16x32_bf16 v[114:117], v[188:191], v[196:199], v[114:117]
	v_mfma_f32_16x16x32_bf16 v[102:105], v[180:183], v[204:207], v[102:105]
	v_mfma_f32_16x16x32_bf16 v[98:101], v[188:191], v[204:207], v[98:101]
	v_mfma_f32_16x16x32_bf16 v[86:89], v[180:183], v[212:215], v[86:89]
	v_mfma_f32_16x16x32_bf16 v[82:85], v[188:191], v[212:215], v[82:85]
	v_mfma_f32_16x16x32_bf16 v[70:73], v[180:183], v[220:223], v[70:73]
	v_mfma_f32_16x16x32_bf16 v[66:69], v[188:191], v[220:223], v[66:69]
	s_setprio 0
	s_barrier
	s_add_i32 s69, s53, s3
	v_lshl_add_u64 v[224:225], s[30:31], 0, v[134:135]
	s_mov_b32 m0, s69
	ds_read_b128 v[192:195], v158 offset:16384
	ds_read_b128 v[196:199], v158 offset:17408
	ds_read_b128 v[200:203], v158 offset:18432
	ds_read_b128 v[204:207], v158 offset:19456
	ds_read_b128 v[208:211], v158 offset:20480
	ds_read_b128 v[212:215], v158 offset:21504
	ds_read_b128 v[216:219], v158 offset:22528
	ds_read_b128 v[220:223], v158 offset:23552
	global_load_lds_dwordx4 v[224:225], off
	s_add_i32 m0, s69, 0x2000
	s_add_u32 s70, s30, 0x40000
	v_lshl_add_u64 v[226:227], s[30:31], 0, v[130:131]
	s_addc_u32 s71, s31, 0
	s_add_i32 s69, s54, s3
	global_load_lds_dwordx4 v[226:227], off
	v_lshl_add_u64 v[228:229], s[70:71], 0, v[134:135]
	s_mov_b32 m0, s69
	v_lshl_add_u64 v[230:231], s[34:35], 0, v[132:133]
	global_load_lds_dwordx4 v[228:229], off
	v_lshl_add_u64 v[228:229], s[70:71], 0, v[130:131]
	s_add_i32 m0, s69, 0x2000
	s_nop 0
	global_load_lds_dwordx4 v[228:229], off
	s_waitcnt vmcnt(6)
	s_waitcnt lgkmcnt(0)
	s_barrier
; #define PG8_STAGE(bufoff, gbase, voff) do { _Pragma("unroll") for (int _i = 0; _i < 2; ++_i) \
;         __builtin_amdgcn_global_load_lds((const unsigned*)((const char*)(gbase) + (voff)[_i]), (PG8_LAS unsigned*)(lds + (bufoff) + ldsw + _i * 8192), 16, 0, 0); } while (0)
; #define PG8_LDA(dst, b, h) do { _Pragma("unroll") for (int m = 0; m < 4; ++m) _Pragma("unroll") for (int k = 0; k < 2; ++k) dst[m][k] = *(const PG8_LAS bf16x8*)(lds + PG8_SA(b, h) + aoff + m * 2048 + k * 1024); } while (0)
; #define PG8_LDB(dst, b, h) do { _Pragma("unroll") for (int n = 0; n < 2; ++n) _Pragma("unroll") for (int k = 0; k < 2; ++k) dst[n][k] = *(const PG8_LAS bf16x8*)(lds + PG8_SB(b, h) + boff + n * 2048 + k * 1024); } while (0)
; #define PG8_MMA(ai, bj, At, Bt) do { __builtin_amdgcn_s_setprio(1); _Pragma("unroll") for (int m = 0; m < 4; ++m) _Pragma("unroll") for (int n = 0; n < 2; ++n) _Pragma("unroll") for (int k = 0; k < 2; ++k) \
;         acc[ai][bj][m][n] = __builtin_amdgcn_mfma_f32_16x16x32_bf16(Bt[n][k], At[m][k], acc[ai][bj][m][n], 0, 0, 0); __builtin_amdgcn_s_setprio(0); } while (0)
; #define PG8_WAIT_V(n) asm volatile("s_waitcnt vmcnt(" #n ")" ::: "memory")
; #define PG8_WAIT_L(n) asm volatile("s_waitcnt lgkmcnt(" #n ")" ::: "memory")
; #define PG8_BAR __builtin_amdgcn_s_barrier()
; #define PG8_SCHED __builtin_amdgcn_sched_barrier(0)
; template <class Epi, class Sched, bool ALIGN_EPI = false, bool SP2 = false, bool AGM = false  >
; __device__ __forceinline__ void gemm_phase(PG8_LAS unsigned char* lds, const Gemm g, const Sched& S, const Epi& E) {
;     ...
;             PG8_LDA(At, 0, 1); PG8_STAGE(PG8_SB(0, 0), b2, voffB); PG8_STAGE(PG8_SB(0, 1), b2 + hstep, voffB); PG8_STAGE(PG8_SA(0, 0), a2, voffA);
;             PG8_WAIT_V(8); PG8_WAIT_L(0); PG8_BAR; PG8_MMA(1, 0, At, B0); PG8_MMA(1, 1, At, B1); PG8_BAR; PG8_SCHED;
;             PG8_LDB(B0, 1, 0); PG8_LDB(B1, 1, 1); PG8_SCHED; PG8_LDA(At, 1, 0); PG8_STAGE(PG8_SA(0, 1), a2 + hstepA, voffA);
;             PG8_WAIT_V(8); PG8_WAIT_L(0); PG8_BAR; PG8_MMA(0, 0, At, B0); PG8_MMA(0, 1, At, B1); PG8_BAR; PG8_SCHED;
	s_setprio 1
	s_waitcnt lgkmcnt(0)
	v_mfma_f32_16x16x32_bf16 v[62:65], v[148:151], v[192:195], 0
	v_mfma_f32_16x16x32_bf16 v[58:61], v[168:171], v[192:195], 0
	v_mfma_f32_16x16x32_bf16 v[46:49], v[148:151], v[200:203], 0
	v_mfma_f32_16x16x32_bf16 v[42:45], v[168:171], v[200:203], 0
	v_mfma_f32_16x16x32_bf16 v[30:33], v[148:151], v[208:211], 0
	v_mfma_f32_16x16x32_bf16 v[26:29], v[168:171], v[208:211], 0
	v_mfma_f32_16x16x32_bf16 v[14:17], v[148:151], v[216:219], 0
	v_mfma_f32_16x16x32_bf16 v[10:13], v[168:171], v[216:219], 0
	v_mfma_f32_16x16x32_bf16 v[62:65], v[164:167], v[196:199], v[62:65]
	v_mfma_f32_16x16x32_bf16 v[58:61], v[172:175], v[196:199], v[58:61]
	v_lshl_add_u64 v[228:229], s[34:35], 0, v[136:137]
	s_mov_b32 m0, s37
	s_nop 0
	global_load_lds_dwordx4 v[228:229], off
	v_mfma_f32_16x16x32_bf16 v[46:49], v[164:167], v[204:207], v[46:49]
	v_mfma_f32_16x16x32_bf16 v[42:45], v[172:175], v[204:207], v[42:45]
	v_mfma_f32_16x16x32_bf16 v[30:33], v[164:167], v[212:215], v[30:33]
	v_mfma_f32_16x16x32_bf16 v[26:29], v[172:175], v[212:215], v[26:29]
	v_mfma_f32_16x16x32_bf16 v[14:17], v[164:167], v[220:223], v[14:17]
	v_mfma_f32_16x16x32_bf16 v[10:13], v[172:175], v[220:223], v[10:13]
	s_setprio 0
	s_setprio 1
	v_mfma_f32_16x16x32_bf16 v[54:57], v[176:179], v[192:195], 0
	v_mfma_f32_16x16x32_bf16 v[50:53], v[184:187], v[192:195], 0
	v_mfma_f32_16x16x32_bf16 v[38:41], v[176:179], v[200:203], 0
	v_mfma_f32_16x16x32_bf16 v[34:37], v[184:187], v[200:203], 0
	v_mfma_f32_16x16x32_bf16 v[22:25], v[176:179], v[208:211], 0
	v_mfma_f32_16x16x32_bf16 v[18:21], v[184:187], v[208:211], 0
	v_mfma_f32_16x16x32_bf16 v[6:9], v[176:179], v[216:219], 0
	v_mfma_f32_16x16x32_bf16 v[2:5], v[184:187], v[216:219], 0
	v_mfma_f32_16x16x32_bf16 v[54:57], v[180:183], v[196:199], v[54:57]
	v_mfma_f32_16x16x32_bf16 v[50:53], v[188:191], v[196:199], v[50:53]
	s_mov_b32 m0, s38
	s_nop 0
	global_load_lds_dwordx4 v[230:231], off
	v_mfma_f32_16x16x32_bf16 v[38:41], v[180:183], v[204:207], v[38:41]
	v_mfma_f32_16x16x32_bf16 v[34:37], v[188:191], v[204:207], v[34:37]
	v_mfma_f32_16x16x32_bf16 v[22:25], v[180:183], v[212:215], v[22:25]
	v_mfma_f32_16x16x32_bf16 v[18:21], v[188:191], v[212:215], v[18:21]
	v_mfma_f32_16x16x32_bf16 v[6:9], v[180:183], v[220:223], v[6:9]
	v_mfma_f32_16x16x32_bf16 v[2:5], v[188:191], v[220:223], v[2:5]
	s_setprio 0
	s_barrier
	s_add_i32 s69, 0, 0x18000
	s_add_i32 s70, 0, 0x1c000
	v_add_u32_e32 v172, s69, v155
	v_add_u32_e32 v188, s70, v155
	ds_read_b128 v[148:151], v172
	ds_read_b128 v[164:167], v172 offset:1024
	ds_read_b128 v[168:171], v172 offset:2048
	ds_read_b128 v[172:175], v172 offset:3072
	ds_read_b128 v[176:179], v188
	ds_read_b128 v[180:183], v188 offset:1024
	ds_read_b128 v[184:187], v188 offset:2048
	ds_read_b128 v[188:191], v188 offset:3072
	s_add_u32 s34, s34, 0x40000
	s_addc_u32 s35, s35, 0
	s_mov_b32 m0, s39
	v_lshl_add_u64 v[232:233], s[34:35], 0, v[136:137]
	ds_read_b128 v[192:195], v158 offset:32768
	ds_read_b128 v[196:199], v158 offset:33792
	ds_read_b128 v[200:203], v158 offset:34816
	ds_read_b128 v[204:207], v158 offset:35840
	ds_read_b128 v[208:211], v158 offset:36864
	ds_read_b128 v[212:215], v158 offset:37888
	ds_read_b128 v[216:219], v158 offset:38912
	ds_read_b128 v[220:223], v158 offset:39936
	global_load_lds_dwordx4 v[232:233], off
	v_lshl_add_u64 v[232:233], s[34:35], 0, v[132:133]
	s_mov_b32 m0, s40
	s_nop 0
	global_load_lds_dwordx4 v[232:233], off
	s_waitcnt vmcnt(8)
	s_waitcnt lgkmcnt(0)
	s_barrier
	s_setprio 1
	s_waitcnt lgkmcnt(0)
	v_mfma_f32_16x16x32_bf16 v[126:129], v[148:151], v[192:195], v[126:129]
	v_mfma_f32_16x16x32_bf16 v[122:125], v[168:171], v[192:195], v[122:125]
	v_mfma_f32_16x16x32_bf16 v[110:113], v[148:151], v[200:203], v[110:113]
	v_mfma_f32_16x16x32_bf16 v[106:109], v[168:171], v[200:203], v[106:109]
	v_mfma_f32_16x16x32_bf16 v[94:97], v[148:151], v[208:211], v[94:97]
	v_mfma_f32_16x16x32_bf16 v[90:93], v[168:171], v[208:211], v[90:93]
	v_mfma_f32_16x16x32_bf16 v[78:81], v[148:151], v[216:219], v[78:81]
	v_mfma_f32_16x16x32_bf16 v[74:77], v[168:171], v[216:219], v[74:77]
	v_mfma_f32_16x16x32_bf16 v[126:129], v[164:167], v[196:199], v[126:129]
	v_mfma_f32_16x16x32_bf16 v[122:125], v[172:175], v[196:199], v[122:125]
	v_mfma_f32_16x16x32_bf16 v[110:113], v[164:167], v[204:207], v[110:113]
	v_mfma_f32_16x16x32_bf16 v[106:109], v[172:175], v[204:207], v[106:109]
	v_mfma_f32_16x16x32_bf16 v[94:97], v[164:167], v[212:215], v[94:97]
	v_mfma_f32_16x16x32_bf16 v[90:93], v[172:175], v[212:215], v[90:93]
	v_mfma_f32_16x16x32_bf16 v[78:81], v[164:167], v[220:223], v[78:81]
	v_mfma_f32_16x16x32_bf16 v[74:77], v[172:175], v[220:223], v[74:77]
	s_setprio 0
	s_setprio 1
	v_mfma_f32_16x16x32_bf16 v[118:121], v[176:179], v[192:195], v[118:121]
	v_mfma_f32_16x16x32_bf16 v[114:117], v[184:187], v[192:195], v[114:117]
	v_mfma_f32_16x16x32_bf16 v[102:105], v[176:179], v[200:203], v[102:105]
	v_mfma_f32_16x16x32_bf16 v[98:101], v[184:187], v[200:203], v[98:101]
	v_mfma_f32_16x16x32_bf16 v[86:89], v[176:179], v[208:211], v[86:89]
	v_mfma_f32_16x16x32_bf16 v[82:85], v[184:187], v[208:211], v[82:85]
	v_mfma_f32_16x16x32_bf16 v[70:73], v[176:179], v[216:219], v[70:73]
	v_mfma_f32_16x16x32_bf16 v[66:69], v[184:187], v[216:219], v[66:69]
	v_mfma_f32_16x16x32_bf16 v[118:121], v[180:183], v[196:199], v[118:121]
	v_mfma_f32_16x16x32_bf16 v[114:117], v[188:191], v[196:199], v[114:117]
	v_mfma_f32_16x16x32_bf16 v[102:105], v[180:183], v[204:207], v[102:105]
	v_mfma_f32_16x16x32_bf16 v[98:101], v[188:191], v[204:207], v[98:101]
	v_mfma_f32_16x16x32_bf16 v[86:89], v[180:183], v[212:215], v[86:89]
	v_mfma_f32_16x16x32_bf16 v[82:85], v[188:191], v[212:215], v[82:85]
	v_mfma_f32_16x16x32_bf16 v[70:73], v[180:183], v[220:223], v[70:73]
	v_mfma_f32_16x16x32_bf16 v[66:69], v[188:191], v[220:223], v[66:69]
	s_setprio 0
	s_barrier
; #define PG8_STAGE(bufoff, gbase, voff) do { _Pragma("unroll") for (int _i = 0; _i < 2; ++_i) \
;         __builtin_amdgcn_global_load_lds((const unsigned*)((const char*)(gbase) + (voff)[_i]), (PG8_LAS unsigned*)(lds + (bufoff) + ldsw + _i * 8192), 16, 0, 0); } while (0)
; #define PG8_LDA(dst, b, h) do { _Pragma("unroll") for (int m = 0; m < 4; ++m) _Pragma("unroll") for (int k = 0; k < 2; ++k) dst[m][k] = *(const PG8_LAS bf16x8*)(lds + PG8_SA(b, h) + aoff + m * 2048 + k * 1024); } while (0)
; #define PG8_LDB(dst, b, h) do { _Pragma("unroll") for (int n = 0; n < 2; ++n) _Pragma("unroll") for (int k = 0; k < 2; ++k) dst[n][k] = *(const PG8_LAS bf16x8*)(lds + PG8_SB(b, h) + boff + n * 2048 + k * 1024); } while (0)
; #define PG8_MMA(ai, bj, At, Bt) do { __builtin_amdgcn_s_setprio(1); _Pragma("unroll") for (int m = 0; m < 4; ++m) _Pragma("unroll") for (int n = 0; n < 2; ++n) _Pragma("unroll") for (int k = 0; k < 2; ++k) \
;         acc[ai][bj][m][n] = __builtin_amdgcn_mfma_f32_16x16x32_bf16(Bt[n][k], At[m][k], acc[ai][bj][m][n], 0, 0, 0); __builtin_amdgcn_s_setprio(0); } while (0)
; #define PG8_WAIT_V(n) asm volatile("s_waitcnt vmcnt(" #n ")" ::: "memory")
; #define PG8_WAIT_L(n) asm volatile("s_waitcnt lgkmcnt(" #n ")" ::: "memory")
; #define PG8_BAR __builtin_amdgcn_s_barrier()
; #define PG8_SCHED __builtin_amdgcn_sched_barrier(0)
; template <class Epi, class Sched, bool ALIGN_EPI = false, bool SP2 = false, bool AGM = false  >
; __device__ __forceinline__ void gemm_phase(PG8_LAS unsigned char* lds, const Gemm g, const Sched& S, const Epi& E) {
;     ...
;             PG8_LDB(B0, 0, 0); PG8_LDB(B1, 0, 1); PG8_SCHED; PG8_LDA(At, 0, 0); PG8_STAGE(PG8_SA(1, 1), a1 + hstepA, voffA);
;             PG8_WAIT_V(8); PG8_WAIT_L(0); PG8_BAR; PG8_MMA(0, 0, At, B0); PG8_MMA(0, 1, At, B1); PG8_BAR; PG8_SCHED;
;     ...
;             PG8_LDA(At, 1, 1); PG8_STAGE(PG8_SB(1, 0), b3, voffB); PG8_STAGE(PG8_SB(1, 1), b3 + hstep, voffB); PG8_STAGE(PG8_SA(1, 0), a3, voffA);
;             PG8_WAIT_V(8); PG8_WAIT_L(0); PG8_BAR; PG8_MMA(1, 0, At, B0); PG8_MMA(1, 1, At, B1); PG8_BAR; PG8_SCHED;
	s_add_i32 s34, s69, s3
	v_lshl_add_u64 v[224:225], v[224:225], 0, s[16:17]
	s_mov_b32 m0, s34
	ds_read_b128 v[192:195], v158 offset:49152
	ds_read_b128 v[196:199], v158 offset:50176
	ds_read_b128 v[200:203], v158 offset:51200
	ds_read_b128 v[204:207], v158 offset:52224
	ds_read_b128 v[208:211], v158 offset:53248
	ds_read_b128 v[212:215], v158 offset:54272
	ds_read_b128 v[216:219], v158 offset:55296
	ds_read_b128 v[220:223], v158 offset:56320
	global_load_lds_dwordx4 v[224:225], off
	s_add_i32 m0, s34, 0x2000
	s_add_u32 s30, s30, 0x40080
	v_lshl_add_u64 v[224:225], v[226:227], 0, s[16:17]
	s_addc_u32 s31, s31, 0
	s_add_i32 s34, s70, s3
	global_load_lds_dwordx4 v[224:225], off
	v_lshl_add_u64 v[224:225], s[30:31], 0, v[134:135]
	s_mov_b32 m0, s34
	s_nop 0
	global_load_lds_dwordx4 v[224:225], off
	v_lshl_add_u64 v[224:225], s[30:31], 0, v[130:131]
	s_add_i32 m0, s34, 0x2000
	s_nop 0
	global_load_lds_dwordx4 v[224:225], off
	s_waitcnt vmcnt(6)
	s_waitcnt lgkmcnt(0)
	s_barrier
	s_setprio 1
	s_waitcnt lgkmcnt(0)
	v_mfma_f32_16x16x32_bf16 v[62:65], v[148:151], v[192:195], v[62:65]
	v_mfma_f32_16x16x32_bf16 v[58:61], v[168:171], v[192:195], v[58:61]
	v_mfma_f32_16x16x32_bf16 v[46:49], v[148:151], v[200:203], v[46:49]
	v_mfma_f32_16x16x32_bf16 v[42:45], v[168:171], v[200:203], v[42:45]
	v_mfma_f32_16x16x32_bf16 v[30:33], v[148:151], v[208:211], v[30:33]
	v_mfma_f32_16x16x32_bf16 v[26:29], v[168:171], v[208:211], v[26:29]
	v_mfma_f32_16x16x32_bf16 v[14:17], v[148:151], v[216:219], v[14:17]
	v_mfma_f32_16x16x32_bf16 v[10:13], v[168:171], v[216:219], v[10:13]
	v_mfma_f32_16x16x32_bf16 v[62:65], v[164:167], v[196:199], v[62:65]
	v_mfma_f32_16x16x32_bf16 v[58:61], v[172:175], v[196:199], v[58:61]
	v_lshl_add_u64 v[224:225], v[228:229], 0, s[16:17]
	s_mov_b32 m0, s43
	s_nop 0
	global_load_lds_dwordx4 v[224:225], off
	v_mfma_f32_16x16x32_bf16 v[46:49], v[164:167], v[204:207], v[46:49]
	v_mfma_f32_16x16x32_bf16 v[42:45], v[172:175], v[204:207], v[42:45]
	v_mfma_f32_16x16x32_bf16 v[30:33], v[164:167], v[212:215], v[30:33]
	v_mfma_f32_16x16x32_bf16 v[26:29], v[172:175], v[212:215], v[26:29]
	v_mfma_f32_16x16x32_bf16 v[14:17], v[164:167], v[220:223], v[14:17]
	v_mfma_f32_16x16x32_bf16 v[10:13], v[172:175], v[220:223], v[10:13]
	s_setprio 0
	s_setprio 1
	v_mfma_f32_16x16x32_bf16 v[54:57], v[176:179], v[192:195], v[54:57]
	v_mfma_f32_16x16x32_bf16 v[50:53], v[184:187], v[192:195], v[50:53]
	v_mfma_f32_16x16x32_bf16 v[38:41], v[176:179], v[200:203], v[38:41]
	v_mfma_f32_16x16x32_bf16 v[34:37], v[184:187], v[200:203], v[34:37]
	v_mfma_f32_16x16x32_bf16 v[22:25], v[176:179], v[208:211], v[22:25]
	v_mfma_f32_16x16x32_bf16 v[18:21], v[184:187], v[208:211], v[18:21]
	v_mfma_f32_16x16x32_bf16 v[6:9], v[176:179], v[216:219], v[6:9]
	v_mfma_f32_16x16x32_bf16 v[2:5], v[184:187], v[216:219], v[2:5]
	v_mfma_f32_16x16x32_bf16 v[54:57], v[180:183], v[196:199], v[54:57]
	v_mfma_f32_16x16x32_bf16 v[50:53], v[188:191], v[196:199], v[50:53]
	v_lshl_add_u64 v[224:225], v[230:231], 0, s[16:17]
	s_mov_b32 m0, s44
	s_nop 0
	global_load_lds_dwordx4 v[224:225], off
	v_mfma_f32_16x16x32_bf16 v[38:41], v[180:183], v[204:207], v[38:41]
	v_mfma_f32_16x16x32_bf16 v[34:37], v[188:191], v[204:207], v[34:37]
	v_mfma_f32_16x16x32_bf16 v[22:25], v[180:183], v[212:215], v[22:25]
	v_mfma_f32_16x16x32_bf16 v[18:21], v[188:191], v[212:215], v[18:21]
	v_mfma_f32_16x16x32_bf16 v[6:9], v[180:183], v[220:223], v[6:9]
	v_mfma_f32_16x16x32_bf16 v[2:5], v[188:191], v[220:223], v[2:5]
	s_setprio 0
	s_barrier
	s_add_i32 s68, s68, 2
	s_add_u32 s28, s28, 0x100
	s_addc_u32 s29, s29, 0
	s_add_u32 s66, s66, 0x100
	s_addc_u32 s67, s67, 0
	s_cmp_gt_u32 s68, 13
	s_cbranch_scc1 .Lpeel_done_p6
	.p2align	6
.LBB0_877:
	ds_read_b128 v[148:151], v156
	ds_read_b128 v[164:167], v156 offset:1024
	ds_read_b128 v[168:171], v156 offset:2048
	ds_read_b128 v[172:175], v156 offset:3072
	ds_read_b128 v[176:179], v157
	ds_read_b128 v[180:183], v157 offset:1024
	ds_read_b128 v[184:187], v157 offset:2048
	ds_read_b128 v[188:191], v157 offset:3072
	s_add_u32 s30, s28, 0xfffc0080
	s_addc_u32 s31, s29, -1
	s_cmp_eq_u32 s68, 12
	s_cselect_b32 s35, s23, s31
	s_cselect_b32 s34, s64, s30
	s_cselect_b32 s31, s21, s67
	s_cselect_b32 s30, s65, s66
	v_lshl_add_u64 v[224:225], s[28:29], 0, v[140:141]
	s_add_i32 m0, s37, 0xc000
	ds_read_b128 v[192:195], v158
	ds_read_b128 v[196:199], v158 offset:1024
	ds_read_b128 v[200:203], v158 offset:2048
	ds_read_b128 v[204:207], v158 offset:3072
	ds_read_b128 v[208:211], v158 offset:4096
	ds_read_b128 v[212:215], v158 offset:5120
	ds_read_b128 v[216:219], v158 offset:6144
	ds_read_b128 v[220:223], v158 offset:7168
	global_load_lds_dwordx4 v[224:225], off
	v_lshl_add_u64 v[224:225], s[28:29], 0, v[142:143]
	s_add_i32 m0, s37, 0xe000
	s_nop 0
	global_load_lds_dwordx4 v[224:225], off
	s_waitcnt vmcnt(8)
	s_waitcnt lgkmcnt(0)
	s_barrier
; #define PG8_STAGE(bufoff, gbase, voff) do { _Pragma("unroll") for (int _i = 0; _i < 2; ++_i) \
;         __builtin_amdgcn_global_load_lds((const unsigned*)((const char*)(gbase) + (voff)[_i]), (PG8_LAS unsigned*)(lds + (bufoff) + ldsw + _i * 8192), 16, 0, 0); } while (0)
; #define PG8_LDA(dst, b, h) do { _Pragma("unroll") for (int m = 0; m < 4; ++m) _Pragma("unroll") for (int k = 0; k < 2; ++k) dst[m][k] = *(const PG8_LAS bf16x8*)(lds + PG8_SA(b, h) + aoff + m * 2048 + k * 1024); } while (0)
; #define PG8_MMA(ai, bj, At, Bt) do { __builtin_amdgcn_s_setprio(1); _Pragma("unroll") for (int m = 0; m < 4; ++m) _Pragma("unroll") for (int n = 0; n < 2; ++n) _Pragma("unroll") for (int k = 0; k < 2; ++k) \
;         acc[ai][bj][m][n] = __builtin_amdgcn_mfma_f32_16x16x32_bf16(Bt[n][k], At[m][k], acc[ai][bj][m][n], 0, 0, 0); __builtin_amdgcn_s_setprio(0); } while (0)
; #define PG8_WAIT_V(n) asm volatile("s_waitcnt vmcnt(" #n ")" ::: "memory")
; #define PG8_WAIT_L(n) asm volatile("s_waitcnt lgkmcnt(" #n ")" ::: "memory")
; #define PG8_BAR __builtin_amdgcn_s_barrier()
; #define PG8_SCHED __builtin_amdgcn_sched_barrier(0)
; template <class Epi, class Sched, bool ALIGN_EPI = false, bool SP2 = false, bool AGM = false  >
; __device__ __forceinline__ void gemm_phase(PG8_LAS unsigned char* lds, const Gemm g, const Sched& S, const Epi& E) {
;     ...
;             PG8_WAIT_V(8); PG8_WAIT_L(0); PG8_BAR; PG8_MMA(0, 0, At, B0); PG8_MMA(0, 1, At, B1); PG8_BAR; PG8_SCHED;
;             PG8_LDA(At, 0, 1); PG8_STAGE(PG8_SB(0, 0), b2, voffB); PG8_STAGE(PG8_SB(0, 1), b2 + hstep, voffB); PG8_STAGE(PG8_SA(0, 0), a2, voffA);
;             PG8_WAIT_V(8); PG8_WAIT_L(0); PG8_BAR; PG8_MMA(1, 0, At, B0); PG8_MMA(1, 1, At, B1); PG8_BAR; PG8_SCHED;
	s_setprio 1
	s_waitcnt lgkmcnt(0)
	v_mfma_f32_16x16x32_bf16 v[126:129], v[148:151], v[192:195], v[126:129]
	v_mfma_f32_16x16x32_bf16 v[122:125], v[168:171], v[192:195], v[122:125]
	v_mfma_f32_16x16x32_bf16 v[110:113], v[148:151], v[200:203], v[110:113]
	v_mfma_f32_16x16x32_bf16 v[106:109], v[168:171], v[200:203], v[106:109]
	v_mfma_f32_16x16x32_bf16 v[94:97], v[148:151], v[208:211], v[94:97]
	v_mfma_f32_16x16x32_bf16 v[90:93], v[168:171], v[208:211], v[90:93]
	v_mfma_f32_16x16x32_bf16 v[78:81], v[148:151], v[216:219], v[78:81]
	v_mfma_f32_16x16x32_bf16 v[74:77], v[168:171], v[216:219], v[74:77]
	v_mfma_f32_16x16x32_bf16 v[126:129], v[164:167], v[196:199], v[126:129]
	v_mfma_f32_16x16x32_bf16 v[122:125], v[172:175], v[196:199], v[122:125]
	v_mfma_f32_16x16x32_bf16 v[110:113], v[164:167], v[204:207], v[110:113]
	v_mfma_f32_16x16x32_bf16 v[106:109], v[172:175], v[204:207], v[106:109]
	v_mfma_f32_16x16x32_bf16 v[94:97], v[164:167], v[212:215], v[94:97]
	v_mfma_f32_16x16x32_bf16 v[90:93], v[172:175], v[212:215], v[90:93]
	v_mfma_f32_16x16x32_bf16 v[78:81], v[164:167], v[220:223], v[78:81]
	v_mfma_f32_16x16x32_bf16 v[74:77], v[172:175], v[220:223], v[74:77]
	s_setprio 0
	s_setprio 1
	v_mfma_f32_16x16x32_bf16 v[118:121], v[176:179], v[192:195], v[118:121]
	v_mfma_f32_16x16x32_bf16 v[114:117], v[184:187], v[192:195], v[114:117]
	v_mfma_f32_16x16x32_bf16 v[102:105], v[176:179], v[200:203], v[102:105]
	v_mfma_f32_16x16x32_bf16 v[98:101], v[184:187], v[200:203], v[98:101]
	v_mfma_f32_16x16x32_bf16 v[86:89], v[176:179], v[208:211], v[86:89]
	v_mfma_f32_16x16x32_bf16 v[82:85], v[184:187], v[208:211], v[82:85]
	v_mfma_f32_16x16x32_bf16 v[70:73], v[176:179], v[216:219], v[70:73]
	v_mfma_f32_16x16x32_bf16 v[66:69], v[184:187], v[216:219], v[66:69]
	v_mfma_f32_16x16x32_bf16 v[118:121], v[180:183], v[196:199], v[118:121]
	v_mfma_f32_16x16x32_bf16 v[114:117], v[188:191], v[196:199], v[114:117]
	v_mfma_f32_16x16x32_bf16 v[102:105], v[180:183], v[204:207], v[102:105]
	v_mfma_f32_16x16x32_bf16 v[98:101], v[188:191], v[204:207], v[98:101]
	v_mfma_f32_16x16x32_bf16 v[86:89], v[180:183], v[212:215], v[86:89]
	v_mfma_f32_16x16x32_bf16 v[82:85], v[188:191], v[212:215], v[82:85]
	v_mfma_f32_16x16x32_bf16 v[70:73], v[180:183], v[220:223], v[70:73]
	v_mfma_f32_16x16x32_bf16 v[66:69], v[188:191], v[220:223], v[66:69]
	s_setprio 0
	s_barrier
	s_add_i32 s69, s53, s3
	v_lshl_add_u64 v[224:225], s[30:31], 0, v[134:135]
	s_mov_b32 m0, s69
	ds_read_b128 v[192:195], v158 offset:16384
	ds_read_b128 v[196:199], v158 offset:17408
	ds_read_b128 v[200:203], v158 offset:18432
	ds_read_b128 v[204:207], v158 offset:19456
	ds_read_b128 v[208:211], v158 offset:20480
	ds_read_b128 v[212:215], v158 offset:21504
	ds_read_b128 v[216:219], v158 offset:22528
	ds_read_b128 v[220:223], v158 offset:23552
	global_load_lds_dwordx4 v[224:225], off
	s_add_i32 m0, s69, 0x2000
	s_add_u32 s70, s30, 0x40000
	v_lshl_add_u64 v[226:227], s[30:31], 0, v[130:131]
	s_addc_u32 s71, s31, 0
	s_add_i32 s69, s54, s3
	global_load_lds_dwordx4 v[226:227], off
	v_lshl_add_u64 v[228:229], s[70:71], 0, v[134:135]
	s_mov_b32 m0, s69
	v_lshl_add_u64 v[230:231], s[34:35], 0, v[132:133]
	global_load_lds_dwordx4 v[228:229], off
	v_lshl_add_u64 v[228:229], s[70:71], 0, v[130:131]
	s_add_i32 m0, s69, 0x2000
	s_nop 0
	global_load_lds_dwordx4 v[228:229], off
	s_waitcnt vmcnt(6)
	s_waitcnt lgkmcnt(0)
	s_barrier
	s_setprio 1
	s_waitcnt lgkmcnt(0)
	v_mfma_f32_16x16x32_bf16 v[62:65], v[148:151], v[192:195], v[62:65]
	v_mfma_f32_16x16x32_bf16 v[58:61], v[168:171], v[192:195], v[58:61]
	v_mfma_f32_16x16x32_bf16 v[46:49], v[148:151], v[200:203], v[46:49]
	v_mfma_f32_16x16x32_bf16 v[42:45], v[168:171], v[200:203], v[42:45]
	v_mfma_f32_16x16x32_bf16 v[30:33], v[148:151], v[208:211], v[30:33]
	v_mfma_f32_16x16x32_bf16 v[26:29], v[168:171], v[208:211], v[26:29]
	v_mfma_f32_16x16x32_bf16 v[14:17], v[148:151], v[216:219], v[14:17]
	v_mfma_f32_16x16x32_bf16 v[10:13], v[168:171], v[216:219], v[10:13]
	v_mfma_f32_16x16x32_bf16 v[62:65], v[164:167], v[196:199], v[62:65]
	v_mfma_f32_16x16x32_bf16 v[58:61], v[172:175], v[196:199], v[58:61]
	v_lshl_add_u64 v[228:229], s[34:35], 0, v[136:137]
	s_mov_b32 m0, s37
	s_nop 0
	global_load_lds_dwordx4 v[228:229], off
	v_mfma_f32_16x16x32_bf16 v[46:49], v[164:167], v[204:207], v[46:49]
	v_mfma_f32_16x16x32_bf16 v[42:45], v[172:175], v[204:207], v[42:45]
	v_mfma_f32_16x16x32_bf16 v[30:33], v[164:167], v[212:215], v[30:33]
	v_mfma_f32_16x16x32_bf16 v[26:29], v[172:175], v[212:215], v[26:29]
	v_mfma_f32_16x16x32_bf16 v[14:17], v[164:167], v[220:223], v[14:17]
	v_mfma_f32_16x16x32_bf16 v[10:13], v[172:175], v[220:223], v[10:13]
	s_setprio 0
	s_setprio 1
	v_mfma_f32_16x16x32_bf16 v[54:57], v[176:179], v[192:195], v[54:57]
	v_mfma_f32_16x16x32_bf16 v[50:53], v[184:187], v[192:195], v[50:53]
	v_mfma_f32_16x16x32_bf16 v[38:41], v[176:179], v[200:203], v[38:41]
	v_mfma_f32_16x16x32_bf16 v[34:37], v[184:187], v[200:203], v[34:37]
	v_mfma_f32_16x16x32_bf16 v[22:25], v[176:179], v[208:211], v[22:25]
	v_mfma_f32_16x16x32_bf16 v[18:21], v[184:187], v[208:211], v[18:21]
	v_mfma_f32_16x16x32_bf16 v[6:9], v[176:179], v[216:219], v[6:9]
	v_mfma_f32_16x16x32_bf16 v[2:5], v[184:187], v[216:219], v[2:5]
	v_mfma_f32_16x16x32_bf16 v[54:57], v[180:183], v[196:199], v[54:57]
	v_mfma_f32_16x16x32_bf16 v[50:53], v[188:191], v[196:199], v[50:53]
	s_mov_b32 m0, s38
	s_nop 0
	global_load_lds_dwordx4 v[230:231], off
	v_mfma_f32_16x16x32_bf16 v[38:41], v[180:183], v[204:207], v[38:41]
	v_mfma_f32_16x16x32_bf16 v[34:37], v[188:191], v[204:207], v[34:37]
	v_mfma_f32_16x16x32_bf16 v[22:25], v[180:183], v[212:215], v[22:25]
	v_mfma_f32_16x16x32_bf16 v[18:21], v[188:191], v[212:215], v[18:21]
	v_mfma_f32_16x16x32_bf16 v[6:9], v[180:183], v[220:223], v[6:9]
	v_mfma_f32_16x16x32_bf16 v[2:5], v[188:191], v[220:223], v[2:5]
	s_setprio 0
	s_barrier
; #define PG8_STAGE(bufoff, gbase, voff) do { _Pragma("unroll") for (int _i = 0; _i < 2; ++_i) \
;         __builtin_amdgcn_global_load_lds((const unsigned*)((const char*)(gbase) + (voff)[_i]), (PG8_LAS unsigned*)(lds + (bufoff) + ldsw + _i * 8192), 16, 0, 0); } while (0)
; #define PG8_LDA(dst, b, h) do { _Pragma("unroll") for (int m = 0; m < 4; ++m) _Pragma("unroll") for (int k = 0; k < 2; ++k) dst[m][k] = *(const PG8_LAS bf16x8*)(lds + PG8_SA(b, h) + aoff + m * 2048 + k * 1024); } while (0)
; #define PG8_LDB(dst, b, h) do { _Pragma("unroll") for (int n = 0; n < 2; ++n) _Pragma("unroll") for (int k = 0; k < 2; ++k) dst[n][k] = *(const PG8_LAS bf16x8*)(lds + PG8_SB(b, h) + boff + n * 2048 + k * 1024); } while (0)
; #define PG8_MMA(ai, bj, At, Bt) do { __builtin_amdgcn_s_setprio(1); _Pragma("unroll") for (int m = 0; m < 4; ++m) _Pragma("unroll") for (int n = 0; n < 2; ++n) _Pragma("unroll") for (int k = 0; k < 2; ++k) \
;         acc[ai][bj][m][n] = __builtin_amdgcn_mfma_f32_16x16x32_bf16(Bt[n][k], At[m][k], acc[ai][bj][m][n], 0, 0, 0); __builtin_amdgcn_s_setprio(0); } while (0)
; #define PG8_WAIT_V(n) asm volatile("s_waitcnt vmcnt(" #n ")" ::: "memory")
; #define PG8_WAIT_L(n) asm volatile("s_waitcnt lgkmcnt(" #n ")" ::: "memory")
; #define PG8_BAR __builtin_amdgcn_s_barrier()
; #define PG8_SCHED __builtin_amdgcn_sched_barrier(0)
; template <class Epi, class Sched, bool ALIGN_EPI = false, bool SP2 = false, bool AGM = false  >
; __device__ __forceinline__ void gemm_phase(PG8_LAS unsigned char* lds, const Gemm g, const Sched& S, const Epi& E) {
;     ...
;             PG8_LDB(B0, 1, 0); PG8_LDB(B1, 1, 1); PG8_SCHED; PG8_LDA(At, 1, 0); PG8_STAGE(PG8_SA(0, 1), a2 + hstepA, voffA);
;             PG8_WAIT_V(8); PG8_WAIT_L(0); PG8_BAR; PG8_MMA(0, 0, At, B0); PG8_MMA(0, 1, At, B1); PG8_BAR; PG8_SCHED;
	s_add_i32 s69, 0, 0x18000
	s_add_i32 s70, 0, 0x1c000
	v_add_u32_e32 v172, s69, v155
	v_add_u32_e32 v188, s70, v155
	ds_read_b128 v[148:151], v172
	ds_read_b128 v[164:167], v172 offset:1024
	ds_read_b128 v[168:171], v172 offset:2048
	ds_read_b128 v[172:175], v172 offset:3072
	ds_read_b128 v[176:179], v188
	ds_read_b128 v[180:183], v188 offset:1024
	ds_read_b128 v[184:187], v188 offset:2048
	ds_read_b128 v[188:191], v188 offset:3072
	s_add_u32 s34, s34, 0x40000
	s_addc_u32 s35, s35, 0
	s_mov_b32 m0, s39
	v_lshl_add_u64 v[232:233], s[34:35], 0, v[136:137]
	ds_read_b128 v[192:195], v158 offset:32768
	ds_read_b128 v[196:199], v158 offset:33792
	ds_read_b128 v[200:203], v158 offset:34816
	ds_read_b128 v[204:207], v158 offset:35840
	ds_read_b128 v[208:211], v158 offset:36864
	ds_read_b128 v[212:215], v158 offset:37888
	ds_read_b128 v[216:219], v158 offset:38912
	ds_read_b128 v[220:223], v158 offset:39936
	global_load_lds_dwordx4 v[232:233], off
	v_lshl_add_u64 v[232:233], s[34:35], 0, v[132:133]
	s_mov_b32 m0, s40
	s_nop 0
	global_load_lds_dwordx4 v[232:233], off
	s_waitcnt vmcnt(8)
	s_waitcnt lgkmcnt(0)
	s_barrier
	s_setprio 1
	s_waitcnt lgkmcnt(0)
	v_mfma_f32_16x16x32_bf16 v[126:129], v[148:151], v[192:195], v[126:129]
	v_mfma_f32_16x16x32_bf16 v[122:125], v[168:171], v[192:195], v[122:125]
	v_mfma_f32_16x16x32_bf16 v[110:113], v[148:151], v[200:203], v[110:113]
	v_mfma_f32_16x16x32_bf16 v[106:109], v[168:171], v[200:203], v[106:109]
	v_mfma_f32_16x16x32_bf16 v[94:97], v[148:151], v[208:211], v[94:97]
	v_mfma_f32_16x16x32_bf16 v[90:93], v[168:171], v[208:211], v[90:93]
	v_mfma_f32_16x16x32_bf16 v[78:81], v[148:151], v[216:219], v[78:81]
	v_mfma_f32_16x16x32_bf16 v[74:77], v[168:171], v[216:219], v[74:77]
	v_mfma_f32_16x16x32_bf16 v[126:129], v[164:167], v[196:199], v[126:129]
	v_mfma_f32_16x16x32_bf16 v[122:125], v[172:175], v[196:199], v[122:125]
	v_mfma_f32_16x16x32_bf16 v[110:113], v[164:167], v[204:207], v[110:113]
	v_mfma_f32_16x16x32_bf16 v[106:109], v[172:175], v[204:207], v[106:109]
	v_mfma_f32_16x16x32_bf16 v[94:97], v[164:167], v[212:215], v[94:97]
	v_mfma_f32_16x16x32_bf16 v[90:93], v[172:175], v[212:215], v[90:93]
	v_mfma_f32_16x16x32_bf16 v[78:81], v[164:167], v[220:223], v[78:81]
	v_mfma_f32_16x16x32_bf16 v[74:77], v[172:175], v[220:223], v[74:77]
	s_setprio 0
	s_setprio 1
	v_mfma_f32_16x16x32_bf16 v[118:121], v[176:179], v[192:195], v[118:121]
	v_mfma_f32_16x16x32_bf16 v[114:117], v[184:187], v[192:195], v[114:117]
	v_mfma_f32_16x16x32_bf16 v[102:105], v[176:179], v[200:203], v[102:105]
	v_mfma_f32_16x16x32_bf16 v[98:101], v[184:187], v[200:203], v[98:101]
	v_mfma_f32_16x16x32_bf16 v[86:89], v[176:179], v[208:211], v[86:89]
	v_mfma_f32_16x16x32_bf16 v[82:85], v[184:187], v[208:211], v[82:85]
	v_mfma_f32_16x16x32_bf16 v[70:73], v[176:179], v[216:219], v[70:73]
	v_mfma_f32_16x16x32_bf16 v[66:69], v[184:187], v[216:219], v[66:69]
	v_mfma_f32_16x16x32_bf16 v[118:121], v[180:183], v[196:199], v[118:121]
	v_mfma_f32_16x16x32_bf16 v[114:117], v[188:191], v[196:199], v[114:117]
	v_mfma_f32_16x16x32_bf16 v[102:105], v[180:183], v[204:207], v[102:105]
	v_mfma_f32_16x16x32_bf16 v[98:101], v[188:191], v[204:207], v[98:101]
	v_mfma_f32_16x16x32_bf16 v[86:89], v[180:183], v[212:215], v[86:89]
	v_mfma_f32_16x16x32_bf16 v[82:85], v[188:191], v[212:215], v[82:85]
	v_mfma_f32_16x16x32_bf16 v[70:73], v[180:183], v[220:223], v[70:73]
	v_mfma_f32_16x16x32_bf16 v[66:69], v[188:191], v[220:223], v[66:69]
	s_setprio 0
	s_barrier
; #define PG8_STAGE(bufoff, gbase, voff) do { _Pragma("unroll") for (int _i = 0; _i < 2; ++_i) \
;         __builtin_amdgcn_global_load_lds((const unsigned*)((const char*)(gbase) + (voff)[_i]), (PG8_LAS unsigned*)(lds + (bufoff) + ldsw + _i * 8192), 16, 0, 0); } while (0)
; #define PG8_LDA(dst, b, h) do { _Pragma("unroll") for (int m = 0; m < 4; ++m) _Pragma("unroll") for (int k = 0; k < 2; ++k) dst[m][k] = *(const PG8_LAS bf16x8*)(lds + PG8_SA(b, h) + aoff + m * 2048 + k * 1024); } while (0)
; #define PG8_MMA(ai, bj, At, Bt) do { __builtin_amdgcn_s_setprio(1); _Pragma("unroll") for (int m = 0; m < 4; ++m) _Pragma("unroll") for (int n = 0; n < 2; ++n) _Pragma("unroll") for (int k = 0; k < 2; ++k) \
;         acc[ai][bj][m][n] = __builtin_amdgcn_mfma_f32_16x16x32_bf16(Bt[n][k], At[m][k], acc[ai][bj][m][n], 0, 0, 0); __builtin_amdgcn_s_setprio(0); } while (0)
; #define PG8_WAIT_V(n) asm volatile("s_waitcnt vmcnt(" #n ")" ::: "memory")
; #define PG8_WAIT_L(n) asm volatile("s_waitcnt lgkmcnt(" #n ")" ::: "memory")
; #define PG8_BAR __builtin_amdgcn_s_barrier()
; #define PG8_SCHED __builtin_amdgcn_sched_barrier(0)
; template <class Epi, class Sched, bool ALIGN_EPI = false, bool SP2 = false, bool AGM = false  >
; __device__ __forceinline__ void gemm_phase(PG8_LAS unsigned char* lds, const Gemm g, const Sched& S, const Epi& E) {
;     ...
;             PG8_LDA(At, 1, 1); PG8_STAGE(PG8_SB(1, 0), b3, voffB); PG8_STAGE(PG8_SB(1, 1), b3 + hstep, voffB); PG8_STAGE(PG8_SA(1, 0), a3, voffA);
;             PG8_WAIT_V(8); PG8_WAIT_L(0); PG8_BAR; PG8_MMA(1, 0, At, B0); PG8_MMA(1, 1, At, B1); PG8_BAR; PG8_SCHED;
	s_add_i32 s34, s69, s3
	v_lshl_add_u64 v[224:225], v[224:225], 0, s[16:17]
	s_mov_b32 m0, s34
	ds_read_b128 v[192:195], v158 offset:49152
	ds_read_b128 v[196:199], v158 offset:50176
	ds_read_b128 v[200:203], v158 offset:51200
	ds_read_b128 v[204:207], v158 offset:52224
	ds_read_b128 v[208:211], v158 offset:53248
	ds_read_b128 v[212:215], v158 offset:54272
	ds_read_b128 v[216:219], v158 offset:55296
	ds_read_b128 v[220:223], v158 offset:56320
	global_load_lds_dwordx4 v[224:225], off
	s_add_i32 m0, s34, 0x2000
	s_add_u32 s30, s30, 0x40080
	v_lshl_add_u64 v[224:225], v[226:227], 0, s[16:17]
	s_addc_u32 s31, s31, 0
	s_add_i32 s34, s70, s3
	global_load_lds_dwordx4 v[224:225], off
	v_lshl_add_u64 v[224:225], s[30:31], 0, v[134:135]
	s_mov_b32 m0, s34
	s_nop 0
	global_load_lds_dwordx4 v[224:225], off
	v_lshl_add_u64 v[224:225], s[30:31], 0, v[130:131]
	s_add_i32 m0, s34, 0x2000
	s_nop 0
	global_load_lds_dwordx4 v[224:225], off
	s_waitcnt vmcnt(6)
	s_waitcnt lgkmcnt(0)
	s_barrier
	s_setprio 1
	s_waitcnt lgkmcnt(0)
	v_mfma_f32_16x16x32_bf16 v[62:65], v[148:151], v[192:195], v[62:65]
	v_mfma_f32_16x16x32_bf16 v[58:61], v[168:171], v[192:195], v[58:61]
	v_mfma_f32_16x16x32_bf16 v[46:49], v[148:151], v[200:203], v[46:49]
	v_mfma_f32_16x16x32_bf16 v[42:45], v[168:171], v[200:203], v[42:45]
	v_mfma_f32_16x16x32_bf16 v[30:33], v[148:151], v[208:211], v[30:33]
	v_mfma_f32_16x16x32_bf16 v[26:29], v[168:171], v[208:211], v[26:29]
	v_mfma_f32_16x16x32_bf16 v[14:17], v[148:151], v[216:219], v[14:17]
	v_mfma_f32_16x16x32_bf16 v[10:13], v[168:171], v[216:219], v[10:13]
	v_mfma_f32_16x16x32_bf16 v[62:65], v[164:167], v[196:199], v[62:65]
	v_mfma_f32_16x16x32_bf16 v[58:61], v[172:175], v[196:199], v[58:61]
	v_lshl_add_u64 v[224:225], v[228:229], 0, s[16:17]
	s_mov_b32 m0, s43
	s_nop 0
	global_load_lds_dwordx4 v[224:225], off
	v_mfma_f32_16x16x32_bf16 v[46:49], v[164:167], v[204:207], v[46:49]
	v_mfma_f32_16x16x32_bf16 v[42:45], v[172:175], v[204:207], v[42:45]
	v_mfma_f32_16x16x32_bf16 v[30:33], v[164:167], v[212:215], v[30:33]
	v_mfma_f32_16x16x32_bf16 v[26:29], v[172:175], v[212:215], v[26:29]
	v_mfma_f32_16x16x32_bf16 v[14:17], v[164:167], v[220:223], v[14:17]
	v_mfma_f32_16x16x32_bf16 v[10:13], v[172:175], v[220:223], v[10:13]
	s_setprio 0
	s_setprio 1
	v_mfma_f32_16x16x32_bf16 v[54:57], v[176:179], v[192:195], v[54:57]
	v_mfma_f32_16x16x32_bf16 v[50:53], v[184:187], v[192:195], v[50:53]
	v_mfma_f32_16x16x32_bf16 v[38:41], v[176:179], v[200:203], v[38:41]
	v_mfma_f32_16x16x32_bf16 v[34:37], v[184:187], v[200:203], v[34:37]
	v_mfma_f32_16x16x32_bf16 v[22:25], v[176:179], v[208:211], v[22:25]
	v_mfma_f32_16x16x32_bf16 v[18:21], v[184:187], v[208:211], v[18:21]
	v_mfma_f32_16x16x32_bf16 v[6:9], v[176:179], v[216:219], v[6:9]
	v_mfma_f32_16x16x32_bf16 v[2:5], v[184:187], v[216:219], v[2:5]
	v_mfma_f32_16x16x32_bf16 v[54:57], v[180:183], v[196:199], v[54:57]
	v_mfma_f32_16x16x32_bf16 v[50:53], v[188:191], v[196:199], v[50:53]
	v_lshl_add_u64 v[224:225], v[230:231], 0, s[16:17]
	s_mov_b32 m0, s44
	s_nop 0
	global_load_lds_dwordx4 v[224:225], off
	v_mfma_f32_16x16x32_bf16 v[38:41], v[180:183], v[204:207], v[38:41]
	v_mfma_f32_16x16x32_bf16 v[34:37], v[188:191], v[204:207], v[34:37]
	v_mfma_f32_16x16x32_bf16 v[22:25], v[180:183], v[212:215], v[22:25]
	v_mfma_f32_16x16x32_bf16 v[18:21], v[188:191], v[212:215], v[18:21]
	v_mfma_f32_16x16x32_bf16 v[6:9], v[180:183], v[220:223], v[6:9]
	v_mfma_f32_16x16x32_bf16 v[2:5], v[188:191], v[220:223], v[2:5]
	s_setprio 0
	s_barrier
	s_add_i32 s68, s68, 2
	s_add_u32 s28, s28, 0x100
	s_addc_u32 s29, s29, 0
	s_add_u32 s66, s66, 0x100
	s_addc_u32 s67, s67, 0
	s_cmp_gt_u32 s68, 13
	s_cbranch_scc0 .LBB0_877

; #define PG8_STAGE(bufoff, gbase, voff) do { _Pragma("unroll") for (int _i = 0; _i < 2; ++_i) \
;         __builtin_amdgcn_global_load_lds((const unsigned*)((const char*)(gbase) + (voff)[_i]), (PG8_LAS unsigned*)(lds + (bufoff) + ldsw + _i * 8192), 16, 0, 0); } while (0)
; #define PG8_LDA(dst, b, h) do { _Pragma("unroll") for (int m = 0; m < 4; ++m) _Pragma("unroll") for (int k = 0; k < 2; ++k) dst[m][k] = *(const PG8_LAS bf16x8*)(lds + PG8_SA(b, h) + aoff + m * 2048 + k * 1024); } while (0)
; #define PG8_LDB(dst, b, h) do { _Pragma("unroll") for (int n = 0; n < 2; ++n) _Pragma("unroll") for (int k = 0; k < 2; ++k) dst[n][k] = *(const PG8_LAS bf16x8*)(lds + PG8_SB(b, h) + boff + n * 2048 + k * 1024); } while (0)
; #define PG8_MMA(ai, bj, At, Bt) do { __builtin_amdgcn_s_setprio(1); _Pragma("unroll") for (int m = 0; m < 4; ++m) _Pragma("unroll") for (int n = 0; n < 2; ++n) _Pragma("unroll") for (int k = 0; k < 2; ++k) \
;         acc[ai][bj][m][n] = __builtin_amdgcn_mfma_f32_16x16x32_bf16(Bt[n][k], At[m][k], acc[ai][bj][m][n], 0, 0, 0); __builtin_amdgcn_s_setprio(0); } while (0)
; #define PG8_WAIT_V(n) asm volatile("s_waitcnt vmcnt(" #n ")" ::: "memory")
; #define PG8_WAIT_L(n) asm volatile("s_waitcnt lgkmcnt(" #n ")" ::: "memory")
; template <class Epi, class Sched, bool ALIGN_EPI = false, bool SP2 = false, bool AGM = false  >
; __device__ __forceinline__ void gemm_phase(PG8_LAS unsigned char* lds, const Gemm g, const Sched& S, const Epi& E) {
;     ...
;             const bool last = (t == nt - 2);
;             const char* a1 = cA + (size_t)(t + 1) * kstepA;
;             const char* a2 = last ? nA : cA + (size_t)(t + 2) * kstepA; const char* b2 = last ? nB : cB + (size_t)(t + 2) * kstep;
;             const char* a3 = a2 + kstepA; const char* b3 = b2 + kstep;
;             if (last && has_next) S.a_ready(nxt);
;             if constexpr (SP2) {
;             PG8_LDB(B0, 0, 0); PG8_LDB(B1, 0, 1); PG8_SCHED; PG8_LDA(At, 0, 0); PG8_STAGE(PG8_SA(1, 1), a1 + hstepA, voffA);
;             PG8_WAIT_V(8); PG8_WAIT_L(0); PG8_BAR; PG8_MMA(0, 0, At, B0); PG8_MMA(0, 1, At, B1); PG8_BAR; PG8_SCHED;
;             PG8_LDA(At, 0, 1); PG8_STAGE(PG8_SB(0, 0), b2, voffB); PG8_STAGE(PG8_SB(0, 1), b2 + hstep, voffB); PG8_STAGE(PG8_SA(0, 0), a2, voffA);
;             PG8_WAIT_V(8); PG8_WAIT_L(0); PG8_BAR; PG8_MMA(1, 0, At, B0); PG8_MMA(1, 1, At, B1); PG8_BAR; PG8_SCHED;
.LBB0_1068:
	ds_read_b128 v[150:153], v167
	ds_read_b128 v[156:159], v167 offset:1024
	ds_read_b128 v[160:163], v167 offset:2048
	ds_read_b128 v[176:179], v167 offset:3072
	ds_read_b128 v[180:183], v168
	ds_read_b128 v[184:187], v168 offset:1024
	ds_read_b128 v[188:191], v168 offset:2048
	ds_read_b128 v[192:195], v168 offset:3072
	s_add_u32 s34, s30, 0xfff50080
	s_addc_u32 s35, s31, -1
	s_cmp_eq_u32 s65, 40
	s_cselect_b32 s37, s13, s35
	s_cselect_b32 s36, s12, s34
	s_cselect_b32 s35, s29, s33
	s_cselect_b32 s34, s28, s5
	v_lshl_add_u64 v[164:165], s[30:31], 0, v[142:143]
	s_add_i32 m0, s39, 0xc000
	ds_read_b128 v[196:199], v169
	ds_read_b128 v[200:203], v169 offset:1024
	ds_read_b128 v[204:207], v169 offset:2048
	ds_read_b128 v[208:211], v169 offset:3072
	ds_read_b128 v[212:215], v169 offset:4096
	ds_read_b128 v[216:219], v169 offset:5120
	ds_read_b128 v[220:223], v169 offset:6144
	ds_read_b128 v[224:227], v169 offset:7168
	global_load_lds_dwordx4 v[164:165], off
	v_lshl_add_u64 v[164:165], s[30:31], 0, v[144:145]
	s_add_i32 m0, s39, 0xe000
	s_nop 0
	global_load_lds_dwordx4 v[164:165], off
	s_waitcnt vmcnt(8)
	s_waitcnt lgkmcnt(0)
	s_barrier
	s_setprio 1
	s_waitcnt lgkmcnt(0)
	v_mfma_f32_16x16x32_bf16 v[126:129], v[150:153], v[196:199], v[126:129]
	v_mfma_f32_16x16x32_bf16 v[122:125], v[160:163], v[196:199], v[122:125]
	v_mfma_f32_16x16x32_bf16 v[110:113], v[150:153], v[204:207], v[110:113]
	v_mfma_f32_16x16x32_bf16 v[106:109], v[160:163], v[204:207], v[106:109]
	v_mfma_f32_16x16x32_bf16 v[94:97], v[150:153], v[212:215], v[94:97]
	v_mfma_f32_16x16x32_bf16 v[90:93], v[160:163], v[212:215], v[90:93]
	v_mfma_f32_16x16x32_bf16 v[78:81], v[150:153], v[220:223], v[78:81]
	v_mfma_f32_16x16x32_bf16 v[74:77], v[160:163], v[220:223], v[74:77]
	v_mfma_f32_16x16x32_bf16 v[126:129], v[156:159], v[200:203], v[126:129]
	v_mfma_f32_16x16x32_bf16 v[122:125], v[176:179], v[200:203], v[122:125]
	v_mfma_f32_16x16x32_bf16 v[110:113], v[156:159], v[208:211], v[110:113]
	v_mfma_f32_16x16x32_bf16 v[106:109], v[176:179], v[208:211], v[106:109]
	v_mfma_f32_16x16x32_bf16 v[94:97], v[156:159], v[216:219], v[94:97]
	v_mfma_f32_16x16x32_bf16 v[90:93], v[176:179], v[216:219], v[90:93]
	v_mfma_f32_16x16x32_bf16 v[78:81], v[156:159], v[224:227], v[78:81]
	v_mfma_f32_16x16x32_bf16 v[74:77], v[176:179], v[224:227], v[74:77]
	s_setprio 0
	s_setprio 1
	v_mfma_f32_16x16x32_bf16 v[118:121], v[180:183], v[196:199], v[118:121]
	v_mfma_f32_16x16x32_bf16 v[114:117], v[188:191], v[196:199], v[114:117]
	v_mfma_f32_16x16x32_bf16 v[102:105], v[180:183], v[204:207], v[102:105]
	v_mfma_f32_16x16x32_bf16 v[98:101], v[188:191], v[204:207], v[98:101]
	v_mfma_f32_16x16x32_bf16 v[86:89], v[180:183], v[212:215], v[86:89]
	v_mfma_f32_16x16x32_bf16 v[82:85], v[188:191], v[212:215], v[82:85]
	v_mfma_f32_16x16x32_bf16 v[70:73], v[180:183], v[220:223], v[70:73]
	v_mfma_f32_16x16x32_bf16 v[66:69], v[188:191], v[220:223], v[66:69]
	v_mfma_f32_16x16x32_bf16 v[118:121], v[184:187], v[200:203], v[118:121]
	v_mfma_f32_16x16x32_bf16 v[114:117], v[192:195], v[200:203], v[114:117]
	v_mfma_f32_16x16x32_bf16 v[102:105], v[184:187], v[208:211], v[102:105]
	v_mfma_f32_16x16x32_bf16 v[98:101], v[192:195], v[208:211], v[98:101]
	v_mfma_f32_16x16x32_bf16 v[86:89], v[184:187], v[216:219], v[86:89]
	v_mfma_f32_16x16x32_bf16 v[82:85], v[192:195], v[216:219], v[82:85]
	v_mfma_f32_16x16x32_bf16 v[70:73], v[184:187], v[224:227], v[70:73]
	v_mfma_f32_16x16x32_bf16 v[66:69], v[192:195], v[224:227], v[66:69]
	s_setprio 0
	s_barrier
	s_add_i32 s66, s60, s38
	v_lshl_add_u64 v[164:165], s[34:35], 0, v[132:133]
	s_mov_b32 m0, s66
	ds_read_b128 v[196:199], v169 offset:16384
	ds_read_b128 v[200:203], v169 offset:17408
	ds_read_b128 v[204:207], v169 offset:18432
	ds_read_b128 v[208:211], v169 offset:19456
	ds_read_b128 v[212:215], v169 offset:20480
	ds_read_b128 v[216:219], v169 offset:21504
	ds_read_b128 v[220:223], v169 offset:22528
	ds_read_b128 v[224:227], v169 offset:23552
	global_load_lds_dwordx4 v[164:165], off
	s_add_i32 m0, s66, 0x2000
	s_add_u32 s66, s34, 0xb0000
	v_lshl_add_u64 v[228:229], s[34:35], 0, v[136:137]
	s_addc_u32 s67, s35, 0
	s_add_i32 s68, s61, s38
	global_load_lds_dwordx4 v[228:229], off
	v_lshl_add_u64 v[230:231], s[66:67], 0, v[132:133]
	s_mov_b32 m0, s68
	v_lshl_add_u64 v[232:233], s[36:37], 0, v[134:135]
	global_load_lds_dwordx4 v[230:231], off
	v_lshl_add_u64 v[230:231], s[66:67], 0, v[136:137]
	s_add_i32 m0, s68, 0x2000
	s_nop 0
	global_load_lds_dwordx4 v[230:231], off
	s_waitcnt vmcnt(6)
	s_waitcnt lgkmcnt(0)
	s_barrier
; #define PG8_STAGE(bufoff, gbase, voff) do { _Pragma("unroll") for (int _i = 0; _i < 2; ++_i) \
;         __builtin_amdgcn_global_load_lds((const unsigned*)((const char*)(gbase) + (voff)[_i]), (PG8_LAS unsigned*)(lds + (bufoff) + ldsw + _i * 8192), 16, 0, 0); } while (0)
; #define PG8_LDA(dst, b, h) do { _Pragma("unroll") for (int m = 0; m < 4; ++m) _Pragma("unroll") for (int k = 0; k < 2; ++k) dst[m][k] = *(const PG8_LAS bf16x8*)(lds + PG8_SA(b, h) + aoff + m * 2048 + k * 1024); } while (0)
; #define PG8_LDB(dst, b, h) do { _Pragma("unroll") for (int n = 0; n < 2; ++n) _Pragma("unroll") for (int k = 0; k < 2; ++k) dst[n][k] = *(const PG8_LAS bf16x8*)(lds + PG8_SB(b, h) + boff + n * 2048 + k * 1024); } while (0)
; #define PG8_MMA(ai, bj, At, Bt) do { __builtin_amdgcn_s_setprio(1); _Pragma("unroll") for (int m = 0; m < 4; ++m) _Pragma("unroll") for (int n = 0; n < 2; ++n) _Pragma("unroll") for (int k = 0; k < 2; ++k) \
;         acc[ai][bj][m][n] = __builtin_amdgcn_mfma_f32_16x16x32_bf16(Bt[n][k], At[m][k], acc[ai][bj][m][n], 0, 0, 0); __builtin_amdgcn_s_setprio(0); } while (0)
; #define PG8_WAIT_V(n) asm volatile("s_waitcnt vmcnt(" #n ")" ::: "memory")
; #define PG8_WAIT_L(n) asm volatile("s_waitcnt lgkmcnt(" #n ")" ::: "memory")
; #define PG8_BAR __builtin_amdgcn_s_barrier()
; #define PG8_SCHED __builtin_amdgcn_sched_barrier(0)
; template <class Epi, class Sched, bool ALIGN_EPI = false, bool SP2 = false, bool AGM = false  >
; __device__ __forceinline__ void gemm_phase(PG8_LAS unsigned char* lds, const Gemm g, const Sched& S, const Epi& E) {
;     ...
;             PG8_LDA(At, 0, 1); PG8_STAGE(PG8_SB(0, 0), b2, voffB); PG8_STAGE(PG8_SB(0, 1), b2 + hstep, voffB); PG8_STAGE(PG8_SA(0, 0), a2, voffA);
;             PG8_WAIT_V(8); PG8_WAIT_L(0); PG8_BAR; PG8_MMA(1, 0, At, B0); PG8_MMA(1, 1, At, B1); PG8_BAR; PG8_SCHED;
;             PG8_LDB(B0, 1, 0); PG8_LDB(B1, 1, 1); PG8_SCHED; PG8_LDA(At, 1, 0); PG8_STAGE(PG8_SA(0, 1), a2 + hstepA, voffA);
;             PG8_WAIT_V(8); PG8_WAIT_L(0); PG8_BAR; PG8_MMA(0, 0, At, B0); PG8_MMA(0, 1, At, B1); PG8_BAR; PG8_SCHED;
	s_setprio 1
	s_waitcnt lgkmcnt(0)
	v_mfma_f32_16x16x32_bf16 v[62:65], v[150:153], v[196:199], v[62:65]
	v_mfma_f32_16x16x32_bf16 v[58:61], v[160:163], v[196:199], v[58:61]
	v_mfma_f32_16x16x32_bf16 v[46:49], v[150:153], v[204:207], v[46:49]
	v_mfma_f32_16x16x32_bf16 v[42:45], v[160:163], v[204:207], v[42:45]
	v_mfma_f32_16x16x32_bf16 v[30:33], v[150:153], v[212:215], v[30:33]
	v_mfma_f32_16x16x32_bf16 v[26:29], v[160:163], v[212:215], v[26:29]
	v_mfma_f32_16x16x32_bf16 v[14:17], v[150:153], v[220:223], v[14:17]
	v_mfma_f32_16x16x32_bf16 v[10:13], v[160:163], v[220:223], v[10:13]
	v_mfma_f32_16x16x32_bf16 v[62:65], v[156:159], v[200:203], v[62:65]
	v_mfma_f32_16x16x32_bf16 v[58:61], v[176:179], v[200:203], v[58:61]
	v_lshl_add_u64 v[230:231], s[36:37], 0, v[130:131]
	s_mov_b32 m0, s39
	s_nop 0
	global_load_lds_dwordx4 v[230:231], off
	v_mfma_f32_16x16x32_bf16 v[46:49], v[156:159], v[208:211], v[46:49]
	v_mfma_f32_16x16x32_bf16 v[42:45], v[176:179], v[208:211], v[42:45]
	v_mfma_f32_16x16x32_bf16 v[30:33], v[156:159], v[216:219], v[30:33]
	v_mfma_f32_16x16x32_bf16 v[26:29], v[176:179], v[216:219], v[26:29]
	v_mfma_f32_16x16x32_bf16 v[14:17], v[156:159], v[224:227], v[14:17]
	v_mfma_f32_16x16x32_bf16 v[10:13], v[176:179], v[224:227], v[10:13]
	s_setprio 0
	s_setprio 1
	v_mfma_f32_16x16x32_bf16 v[54:57], v[180:183], v[196:199], v[54:57]
	v_mfma_f32_16x16x32_bf16 v[50:53], v[188:191], v[196:199], v[50:53]
	v_mfma_f32_16x16x32_bf16 v[38:41], v[180:183], v[204:207], v[38:41]
	v_mfma_f32_16x16x32_bf16 v[34:37], v[188:191], v[204:207], v[34:37]
	v_mfma_f32_16x16x32_bf16 v[22:25], v[180:183], v[212:215], v[22:25]
	v_mfma_f32_16x16x32_bf16 v[18:21], v[188:191], v[212:215], v[18:21]
	v_mfma_f32_16x16x32_bf16 v[6:9], v[180:183], v[220:223], v[6:9]
	v_mfma_f32_16x16x32_bf16 v[2:5], v[188:191], v[220:223], v[2:5]
	v_mfma_f32_16x16x32_bf16 v[54:57], v[184:187], v[200:203], v[54:57]
	v_mfma_f32_16x16x32_bf16 v[50:53], v[192:195], v[200:203], v[50:53]
	s_mov_b32 m0, s40
	s_nop 0
	global_load_lds_dwordx4 v[232:233], off
	v_mfma_f32_16x16x32_bf16 v[38:41], v[184:187], v[208:211], v[38:41]
	v_mfma_f32_16x16x32_bf16 v[34:37], v[192:195], v[208:211], v[34:37]
	v_mfma_f32_16x16x32_bf16 v[22:25], v[184:187], v[216:219], v[22:25]
	v_mfma_f32_16x16x32_bf16 v[18:21], v[192:195], v[216:219], v[18:21]
	v_mfma_f32_16x16x32_bf16 v[6:9], v[184:187], v[224:227], v[6:9]
	v_mfma_f32_16x16x32_bf16 v[2:5], v[192:195], v[224:227], v[2:5]
	s_setprio 0
	s_barrier
	s_add_i32 s66, 0, 0x18000
	s_add_i32 s67, 0, 0x1c000
	v_add_u32_e32 v176, s66, v1
	v_add_u32_e32 v192, s67, v1
	ds_read_b128 v[150:153], v176
	ds_read_b128 v[156:159], v176 offset:1024
	ds_read_b128 v[160:163], v176 offset:2048
	ds_read_b128 v[176:179], v176 offset:3072
	ds_read_b128 v[180:183], v192
	ds_read_b128 v[184:187], v192 offset:1024
	ds_read_b128 v[188:191], v192 offset:2048
	ds_read_b128 v[192:195], v192 offset:3072
	s_add_u32 s36, s36, 0xb0000
	s_addc_u32 s37, s37, 0
	s_mov_b32 m0, s41
	v_lshl_add_u64 v[234:235], s[36:37], 0, v[130:131]
	ds_read_b128 v[196:199], v169 offset:32768
	ds_read_b128 v[200:203], v169 offset:33792
	ds_read_b128 v[204:207], v169 offset:34816
	ds_read_b128 v[208:211], v169 offset:35840
	ds_read_b128 v[212:215], v169 offset:36864
	ds_read_b128 v[216:219], v169 offset:37888
	ds_read_b128 v[220:223], v169 offset:38912
	ds_read_b128 v[224:227], v169 offset:39936
	global_load_lds_dwordx4 v[234:235], off
	v_lshl_add_u64 v[234:235], s[36:37], 0, v[134:135]
	s_mov_b32 m0, s42
	s_nop 0
	global_load_lds_dwordx4 v[234:235], off
	s_waitcnt vmcnt(8)
	s_waitcnt lgkmcnt(0)
	s_barrier
	s_setprio 1
	s_waitcnt lgkmcnt(0)
	v_mfma_f32_16x16x32_bf16 v[126:129], v[150:153], v[196:199], v[126:129]
	v_mfma_f32_16x16x32_bf16 v[122:125], v[160:163], v[196:199], v[122:125]
	v_mfma_f32_16x16x32_bf16 v[110:113], v[150:153], v[204:207], v[110:113]
	v_mfma_f32_16x16x32_bf16 v[106:109], v[160:163], v[204:207], v[106:109]
	v_mfma_f32_16x16x32_bf16 v[94:97], v[150:153], v[212:215], v[94:97]
	v_mfma_f32_16x16x32_bf16 v[90:93], v[160:163], v[212:215], v[90:93]
	v_mfma_f32_16x16x32_bf16 v[78:81], v[150:153], v[220:223], v[78:81]
	v_mfma_f32_16x16x32_bf16 v[74:77], v[160:163], v[220:223], v[74:77]
	v_mfma_f32_16x16x32_bf16 v[126:129], v[156:159], v[200:203], v[126:129]
	v_mfma_f32_16x16x32_bf16 v[122:125], v[176:179], v[200:203], v[122:125]
	v_mfma_f32_16x16x32_bf16 v[110:113], v[156:159], v[208:211], v[110:113]
	v_mfma_f32_16x16x32_bf16 v[106:109], v[176:179], v[208:211], v[106:109]
	v_mfma_f32_16x16x32_bf16 v[94:97], v[156:159], v[216:219], v[94:97]
	v_mfma_f32_16x16x32_bf16 v[90:93], v[176:179], v[216:219], v[90:93]
	v_mfma_f32_16x16x32_bf16 v[78:81], v[156:159], v[224:227], v[78:81]
	v_mfma_f32_16x16x32_bf16 v[74:77], v[176:179], v[224:227], v[74:77]
	s_setprio 0
	s_setprio 1
	v_mfma_f32_16x16x32_bf16 v[118:121], v[180:183], v[196:199], v[118:121]
	v_mfma_f32_16x16x32_bf16 v[114:117], v[188:191], v[196:199], v[114:117]
	v_mfma_f32_16x16x32_bf16 v[102:105], v[180:183], v[204:207], v[102:105]
	v_mfma_f32_16x16x32_bf16 v[98:101], v[188:191], v[204:207], v[98:101]
	v_mfma_f32_16x16x32_bf16 v[86:89], v[180:183], v[212:215], v[86:89]
	v_mfma_f32_16x16x32_bf16 v[82:85], v[188:191], v[212:215], v[82:85]
	v_mfma_f32_16x16x32_bf16 v[70:73], v[180:183], v[220:223], v[70:73]
	v_mfma_f32_16x16x32_bf16 v[66:69], v[188:191], v[220:223], v[66:69]
	v_mfma_f32_16x16x32_bf16 v[118:121], v[184:187], v[200:203], v[118:121]
	v_mfma_f32_16x16x32_bf16 v[114:117], v[192:195], v[200:203], v[114:117]
	v_mfma_f32_16x16x32_bf16 v[102:105], v[184:187], v[208:211], v[102:105]
	v_mfma_f32_16x16x32_bf16 v[98:101], v[192:195], v[208:211], v[98:101]
	v_mfma_f32_16x16x32_bf16 v[86:89], v[184:187], v[216:219], v[86:89]
	v_mfma_f32_16x16x32_bf16 v[82:85], v[192:195], v[216:219], v[82:85]
	v_mfma_f32_16x16x32_bf16 v[70:73], v[184:187], v[224:227], v[70:73]
	v_mfma_f32_16x16x32_bf16 v[66:69], v[192:195], v[224:227], v[66:69]
	s_setprio 0
	s_barrier
; #define PG8_STAGE(bufoff, gbase, voff) do { _Pragma("unroll") for (int _i = 0; _i < 2; ++_i) \
;         __builtin_amdgcn_global_load_lds((const unsigned*)((const char*)(gbase) + (voff)[_i]), (PG8_LAS unsigned*)(lds + (bufoff) + ldsw + _i * 8192), 16, 0, 0); } while (0)
; #define PG8_LDA(dst, b, h) do { _Pragma("unroll") for (int m = 0; m < 4; ++m) _Pragma("unroll") for (int k = 0; k < 2; ++k) dst[m][k] = *(const PG8_LAS bf16x8*)(lds + PG8_SA(b, h) + aoff + m * 2048 + k * 1024); } while (0)
; #define PG8_MMA(ai, bj, At, Bt) do { __builtin_amdgcn_s_setprio(1); _Pragma("unroll") for (int m = 0; m < 4; ++m) _Pragma("unroll") for (int n = 0; n < 2; ++n) _Pragma("unroll") for (int k = 0; k < 2; ++k) \
;         acc[ai][bj][m][n] = __builtin_amdgcn_mfma_f32_16x16x32_bf16(Bt[n][k], At[m][k], acc[ai][bj][m][n], 0, 0, 0); __builtin_amdgcn_s_setprio(0); } while (0)
; #define PG8_WAIT_V(n) asm volatile("s_waitcnt vmcnt(" #n ")" ::: "memory")
; #define PG8_WAIT_L(n) asm volatile("s_waitcnt lgkmcnt(" #n ")" ::: "memory")
; #define PG8_BAR __builtin_amdgcn_s_barrier()
; #define PG8_SCHED __builtin_amdgcn_sched_barrier(0)
; template <class Epi, class Sched, bool ALIGN_EPI = false, bool SP2 = false, bool AGM = false  >
; __device__ __forceinline__ void gemm_phase(PG8_LAS unsigned char* lds, const Gemm g, const Sched& S, const Epi& E) {
;     ...
;             PG8_LDA(At, 1, 1); PG8_STAGE(PG8_SB(1, 0), b3, voffB); PG8_STAGE(PG8_SB(1, 1), b3 + hstep, voffB); PG8_STAGE(PG8_SA(1, 0), a3, voffA);
;             PG8_WAIT_V(8); PG8_WAIT_L(0); PG8_BAR; PG8_MMA(1, 0, At, B0); PG8_MMA(1, 1, At, B1); PG8_BAR; PG8_SCHED;
	s_add_i32 s36, s66, s38
	v_lshl_add_u64 v[164:165], v[164:165], 0, s[24:25]
	s_mov_b32 m0, s36
	ds_read_b128 v[196:199], v169 offset:49152
	ds_read_b128 v[200:203], v169 offset:50176
	ds_read_b128 v[204:207], v169 offset:51200
	ds_read_b128 v[208:211], v169 offset:52224
	ds_read_b128 v[212:215], v169 offset:53248
	ds_read_b128 v[216:219], v169 offset:54272
	ds_read_b128 v[220:223], v169 offset:55296
	ds_read_b128 v[224:227], v169 offset:56320
	global_load_lds_dwordx4 v[164:165], off
	s_add_i32 m0, s36, 0x2000
	s_add_u32 s34, s34, 0xb0080
	v_lshl_add_u64 v[164:165], v[228:229], 0, s[24:25]
	s_addc_u32 s35, s35, 0
	s_add_i32 s36, s67, s38
	global_load_lds_dwordx4 v[164:165], off
	v_lshl_add_u64 v[164:165], s[34:35], 0, v[132:133]
	s_mov_b32 m0, s36
	s_nop 0
	global_load_lds_dwordx4 v[164:165], off
	v_lshl_add_u64 v[164:165], s[34:35], 0, v[136:137]
	s_add_i32 m0, s36, 0x2000
	s_nop 0
	global_load_lds_dwordx4 v[164:165], off
	s_waitcnt vmcnt(6)
	s_waitcnt lgkmcnt(0)
	s_barrier
	s_setprio 1
	s_waitcnt lgkmcnt(0)
	v_mfma_f32_16x16x32_bf16 v[62:65], v[150:153], v[196:199], v[62:65]
	v_mfma_f32_16x16x32_bf16 v[58:61], v[160:163], v[196:199], v[58:61]
	v_mfma_f32_16x16x32_bf16 v[46:49], v[150:153], v[204:207], v[46:49]
	v_mfma_f32_16x16x32_bf16 v[42:45], v[160:163], v[204:207], v[42:45]
	v_mfma_f32_16x16x32_bf16 v[30:33], v[150:153], v[212:215], v[30:33]
	v_mfma_f32_16x16x32_bf16 v[26:29], v[160:163], v[212:215], v[26:29]
	v_mfma_f32_16x16x32_bf16 v[14:17], v[150:153], v[220:223], v[14:17]
	v_mfma_f32_16x16x32_bf16 v[10:13], v[160:163], v[220:223], v[10:13]
	v_mfma_f32_16x16x32_bf16 v[62:65], v[156:159], v[200:203], v[62:65]
	v_mfma_f32_16x16x32_bf16 v[58:61], v[176:179], v[200:203], v[58:61]
	v_lshl_add_u64 v[164:165], v[230:231], 0, s[24:25]
	s_mov_b32 m0, s55
	s_nop 0
	global_load_lds_dwordx4 v[164:165], off
	v_mfma_f32_16x16x32_bf16 v[46:49], v[156:159], v[208:211], v[46:49]
	v_mfma_f32_16x16x32_bf16 v[42:45], v[176:179], v[208:211], v[42:45]
	v_mfma_f32_16x16x32_bf16 v[30:33], v[156:159], v[216:219], v[30:33]
	v_mfma_f32_16x16x32_bf16 v[26:29], v[176:179], v[216:219], v[26:29]
	v_mfma_f32_16x16x32_bf16 v[14:17], v[156:159], v[224:227], v[14:17]
	v_mfma_f32_16x16x32_bf16 v[10:13], v[176:179], v[224:227], v[10:13]
	s_setprio 0
	s_setprio 1
	v_mfma_f32_16x16x32_bf16 v[54:57], v[180:183], v[196:199], v[54:57]
	v_mfma_f32_16x16x32_bf16 v[50:53], v[188:191], v[196:199], v[50:53]
	v_mfma_f32_16x16x32_bf16 v[38:41], v[180:183], v[204:207], v[38:41]
	v_mfma_f32_16x16x32_bf16 v[34:37], v[188:191], v[204:207], v[34:37]
	v_mfma_f32_16x16x32_bf16 v[22:25], v[180:183], v[212:215], v[22:25]
	v_mfma_f32_16x16x32_bf16 v[18:21], v[188:191], v[212:215], v[18:21]
	v_mfma_f32_16x16x32_bf16 v[6:9], v[180:183], v[220:223], v[6:9]
	v_mfma_f32_16x16x32_bf16 v[2:5], v[188:191], v[220:223], v[2:5]
	v_mfma_f32_16x16x32_bf16 v[54:57], v[184:187], v[200:203], v[54:57]
	v_mfma_f32_16x16x32_bf16 v[50:53], v[192:195], v[200:203], v[50:53]
	v_lshl_add_u64 v[164:165], v[232:233], 0, s[24:25]
	s_mov_b32 m0, s58
	s_nop 0
	global_load_lds_dwordx4 v[164:165], off
	v_mfma_f32_16x16x32_bf16 v[38:41], v[184:187], v[208:211], v[38:41]
	v_mfma_f32_16x16x32_bf16 v[34:37], v[192:195], v[208:211], v[34:37]
	v_mfma_f32_16x16x32_bf16 v[22:25], v[184:187], v[216:219], v[22:25]
	v_mfma_f32_16x16x32_bf16 v[18:21], v[192:195], v[216:219], v[18:21]
	v_mfma_f32_16x16x32_bf16 v[6:9], v[184:187], v[224:227], v[6:9]
	v_mfma_f32_16x16x32_bf16 v[2:5], v[192:195], v[224:227], v[2:5]
	s_setprio 0
	s_barrier
	s_add_i32 s65, s65, 2
	s_add_u32 s30, s30, 0x100
	s_addc_u32 s31, s31, 0
	s_add_u32 s5, s5, 0x100
	s_addc_u32 s33, s33, 0
	s_cmp_gt_u32 s65, 41
	s_cbranch_scc0 .LBB0_1068
	s_and_b64 vcc, exec, s[26:27]
	s_cbranch_vccz .LBB0_1071
	s_barrier
